# v29 plus MFMA order in every k-outer 16-block changed to accumulator-chained (k0 then k1 of the same accumulator adjacent, SrcC forwarded); same accumulation order, bit-identical
# speedup vs baseline: 1.0050x; 1.0050x over previous
; #define PG8_STAGE(bufoff, gbase, voff) do { _Pragma("unroll") for (int _i = 0; _i < 2; ++_i) \
;         __builtin_amdgcn_global_load_lds((const unsigned*)((const char*)(gbase) + (voff)[_i]), (PG8_LAS unsigned*)(lds + (bufoff) + ldsw + _i * 8192), 16, 0, 0); } while (0)
; #define PG8_LDA(dst, b, h) do { _Pragma("unroll") for (int m = 0; m < 4; ++m) _Pragma("unroll") for (int k = 0; k < 2; ++k) dst[m][k] = *(const PG8_LAS bf16x8*)(lds + PG8_SA(b, h) + aoff + m * 2048 + k * 1024); } while (0)
; #define PG8_LDB(dst, b, h) do { _Pragma("unroll") for (int n = 0; n < 2; ++n) _Pragma("unroll") for (int k = 0; k < 2; ++k) dst[n][k] = *(const PG8_LAS bf16x8*)(lds + PG8_SB(b, h) + boff + n * 2048 + k * 1024); } while (0)
; #define PG8_MMA(ai, bj, At, Bt) do { __builtin_amdgcn_s_setprio(1); _Pragma("unroll") for (int m = 0; m < 4; ++m) _Pragma("unroll") for (int n = 0; n < 2; ++n) _Pragma("unroll") for (int k = 0; k < 2; ++k) \
;         acc[ai][bj][m][n] = __builtin_amdgcn_mfma_f32_16x16x32_bf16(Bt[n][k], At[m][k], acc[ai][bj][m][n], 0, 0, 0); __builtin_amdgcn_s_setprio(0); } while (0)
; #define PG8_WAIT_V(n) asm volatile("s_waitcnt vmcnt(" #n ")" ::: "memory")
; #define PG8_WAIT_L(n) asm volatile("s_waitcnt lgkmcnt(" #n ")" ::: "memory")
; template <class Epi, class Sched, bool ALIGN_EPI = false, bool SP2 = false>
; __device__ __forceinline__ void gemm_phase(PG8_LAS unsigned char* lds, const Gemm g, const Sched& S, const Epi& E) {
;     ...
;             const bool last = (t == nt - 2);
;             const char* a1 = cA + (size_t)(t + 1) * kstep;
;             const char* a2 = last ? nA : cA + (size_t)(t + 2) * kstep; const char* b2 = last ? nB : cB + (size_t)(t + 2) * kstep;
;             const char* a3 = a2 + kstep; const char* b3 = b2 + kstep;
;             if (last && has_next) S.a_ready(nxt);
;             if constexpr (SP2) {
;             PG8_LDB(B0, 0, 0); PG8_LDB(B1, 0, 1); PG8_SCHED; PG8_LDA(At, 0, 0); PG8_STAGE(PG8_SA(1, 1), a1 + hstep, voffA);
;             PG8_WAIT_V(8); PG8_WAIT_L(0); PG8_BAR; PG8_MMA(0, 0, At, B0); PG8_MMA(0, 1, At, B1); PG8_BAR; PG8_SCHED;
;             PG8_LDA(At, 0, 1); PG8_STAGE(PG8_SB(0, 0), b2, voffB); PG8_STAGE(PG8_SB(0, 1), b2 + hstep, voffB); PG8_STAGE(PG8_SA(0, 0), a2, voffA);
;             PG8_WAIT_V(8); PG8_WAIT_L(0); PG8_BAR; PG8_MMA(1, 0, At, B0); PG8_MMA(1, 1, At, B1); PG8_BAR; PG8_SCHED;
.LBB0_139:
	ds_read_b128 v[2:5], v187
	ds_read_b128 v[6:9], v187 offset:1024
	ds_read_b128 v[138:141], v187 offset:2048
	ds_read_b128 v[142:145], v187 offset:3072
	ds_read_b128 v[146:149], v197
	ds_read_b128 v[150:153], v197 offset:1024
	ds_read_b128 v[154:157], v197 offset:2048
	ds_read_b128 v[158:161], v197 offset:3072
	s_add_u32 s14, s12, 0xfff00080
	s_addc_u32 s15, s13, -1
	s_cmp_eq_u32 s33, 60
	s_cselect_b32 s17, s2, s15
	s_cselect_b32 s16, s11, s14
	s_cselect_b32 s15, s26, s30
	s_cselect_b32 s14, s28, s29
	v_lshl_add_u64 v[162:163], s[12:13], 0, v[188:189]
	s_add_i32 m0, s27, 0xc000
	ds_read_b128 v[202:205], v199
	ds_read_b128 v[206:209], v199 offset:1024
	ds_read_b128 v[214:217], v199 offset:2048
	ds_read_b128 v[218:221], v199 offset:3072
	ds_read_b128 v[222:225], v199 offset:4096
	ds_read_b128 v[226:229], v199 offset:5120
	ds_read_b128 v[230:233], v199 offset:6144
	ds_read_b128 v[234:237], v199 offset:7168
	global_load_lds_dwordx4 v[162:163], off
	v_lshl_add_u64 v[162:163], s[12:13], 0, v[190:191]
	s_add_i32 m0, s27, 0xe000
	s_nop 0
	global_load_lds_dwordx4 v[162:163], off
	s_waitcnt vmcnt(8)
	s_waitcnt lgkmcnt(0)
	s_setprio 1
	s_barrier
	v_mfma_f32_16x16x32_bf16 v[134:137], v[2:5], v[202:205], v[134:137]
	v_mfma_f32_16x16x32_bf16 v[134:137], v[6:9], v[206:209], v[134:137]
	v_mfma_f32_16x16x32_bf16 v[130:133], v[138:141], v[202:205], v[130:133]
	v_mfma_f32_16x16x32_bf16 v[130:133], v[142:145], v[206:209], v[130:133]
	v_mfma_f32_16x16x32_bf16 v[118:121], v[2:5], v[214:217], v[118:121]
	v_mfma_f32_16x16x32_bf16 v[118:121], v[6:9], v[218:221], v[118:121]
	v_mfma_f32_16x16x32_bf16 v[114:117], v[138:141], v[214:217], v[114:117]
	v_mfma_f32_16x16x32_bf16 v[114:117], v[142:145], v[218:221], v[114:117]
	v_mfma_f32_16x16x32_bf16 v[102:105], v[2:5], v[222:225], v[102:105]
	v_mfma_f32_16x16x32_bf16 v[102:105], v[6:9], v[226:229], v[102:105]
	v_mfma_f32_16x16x32_bf16 v[98:101], v[138:141], v[222:225], v[98:101]
	v_mfma_f32_16x16x32_bf16 v[98:101], v[142:145], v[226:229], v[98:101]
	v_mfma_f32_16x16x32_bf16 v[86:89], v[2:5], v[230:233], v[86:89]
	v_mfma_f32_16x16x32_bf16 v[86:89], v[6:9], v[234:237], v[86:89]
	v_mfma_f32_16x16x32_bf16 v[82:85], v[138:141], v[230:233], v[82:85]
	v_mfma_f32_16x16x32_bf16 v[82:85], v[142:145], v[234:237], v[82:85]
	s_setprio 0
	s_setprio 1
	v_mfma_f32_16x16x32_bf16 v[126:129], v[146:149], v[202:205], v[126:129]
	v_mfma_f32_16x16x32_bf16 v[126:129], v[150:153], v[206:209], v[126:129]
	v_mfma_f32_16x16x32_bf16 v[122:125], v[154:157], v[202:205], v[122:125]
	v_mfma_f32_16x16x32_bf16 v[122:125], v[158:161], v[206:209], v[122:125]
	v_mfma_f32_16x16x32_bf16 v[110:113], v[146:149], v[214:217], v[110:113]
	v_mfma_f32_16x16x32_bf16 v[110:113], v[150:153], v[218:221], v[110:113]
	v_mfma_f32_16x16x32_bf16 v[106:109], v[154:157], v[214:217], v[106:109]
	v_mfma_f32_16x16x32_bf16 v[106:109], v[158:161], v[218:221], v[106:109]
	v_mfma_f32_16x16x32_bf16 v[94:97], v[146:149], v[222:225], v[94:97]
	v_mfma_f32_16x16x32_bf16 v[94:97], v[150:153], v[226:229], v[94:97]
	v_mfma_f32_16x16x32_bf16 v[90:93], v[154:157], v[222:225], v[90:93]
	v_mfma_f32_16x16x32_bf16 v[90:93], v[158:161], v[226:229], v[90:93]
	v_mfma_f32_16x16x32_bf16 v[78:81], v[146:149], v[230:233], v[78:81]
	v_mfma_f32_16x16x32_bf16 v[78:81], v[150:153], v[234:237], v[78:81]
	v_mfma_f32_16x16x32_bf16 v[74:77], v[154:157], v[230:233], v[74:77]
	v_mfma_f32_16x16x32_bf16 v[74:77], v[158:161], v[234:237], v[74:77]
	s_barrier
	s_setprio 0
	s_add_i32 s34, s41, s25
	v_lshl_add_u64 v[162:163], s[14:15], 0, v[168:169]
	s_mov_b32 m0, s34
	ds_read_b128 v[202:205], v199 offset:16384
	ds_read_b128 v[206:209], v199 offset:17408
	ds_read_b128 v[214:217], v199 offset:18432
	ds_read_b128 v[218:221], v199 offset:19456
	ds_read_b128 v[222:225], v199 offset:20480
	ds_read_b128 v[226:229], v199 offset:21504
	ds_read_b128 v[230:233], v199 offset:22528
	ds_read_b128 v[234:237], v199 offset:23552
	global_load_lds_dwordx4 v[162:163], off
	s_add_i32 m0, s34, 0x2000
	s_add_u32 s34, s14, 0x100000
	v_lshl_add_u64 v[210:211], s[14:15], 0, v[172:173]
	s_addc_u32 s35, s15, 0
	s_add_i32 s79, s92, s25
	global_load_lds_dwordx4 v[210:211], off
	v_lshl_add_u64 v[238:239], s[34:35], 0, v[168:169]
	s_mov_b32 m0, s79
	v_lshl_add_u64 v[240:241], s[16:17], 0, v[170:171]
	global_load_lds_dwordx4 v[238:239], off
	v_lshl_add_u64 v[238:239], s[34:35], 0, v[172:173]
	s_add_i32 m0, s79, 0x2000
	s_nop 0
	global_load_lds_dwordx4 v[238:239], off
	v_lshl_add_u64 v[238:239], s[16:17], 0, v[164:165]
	s_mov_b32 m0, s27
	s_nop 0
	global_load_lds_dwordx4 v[238:239], off
	s_mov_b32 m0, s39
	s_nop 0
	global_load_lds_dwordx4 v[240:241], off
	s_waitcnt vmcnt(8)
	s_waitcnt lgkmcnt(0)
	s_setprio 1
	s_barrier
; #define PG8_STAGE(bufoff, gbase, voff) do { _Pragma("unroll") for (int _i = 0; _i < 2; ++_i) \
;         __builtin_amdgcn_global_load_lds((const unsigned*)((const char*)(gbase) + (voff)[_i]), (PG8_LAS unsigned*)(lds + (bufoff) + ldsw + _i * 8192), 16, 0, 0); } while (0)
; #define PG8_LDA(dst, b, h) do { _Pragma("unroll") for (int m = 0; m < 4; ++m) _Pragma("unroll") for (int k = 0; k < 2; ++k) dst[m][k] = *(const PG8_LAS bf16x8*)(lds + PG8_SA(b, h) + aoff + m * 2048 + k * 1024); } while (0)
; #define PG8_LDB(dst, b, h) do { _Pragma("unroll") for (int n = 0; n < 2; ++n) _Pragma("unroll") for (int k = 0; k < 2; ++k) dst[n][k] = *(const PG8_LAS bf16x8*)(lds + PG8_SB(b, h) + boff + n * 2048 + k * 1024); } while (0)
; #define PG8_MMA(ai, bj, At, Bt) do { __builtin_amdgcn_s_setprio(1); _Pragma("unroll") for (int m = 0; m < 4; ++m) _Pragma("unroll") for (int n = 0; n < 2; ++n) _Pragma("unroll") for (int k = 0; k < 2; ++k) \
;         acc[ai][bj][m][n] = __builtin_amdgcn_mfma_f32_16x16x32_bf16(Bt[n][k], At[m][k], acc[ai][bj][m][n], 0, 0, 0); __builtin_amdgcn_s_setprio(0); } while (0)
; #define PG8_WAIT_V(n) asm volatile("s_waitcnt vmcnt(" #n ")" ::: "memory")
; #define PG8_WAIT_L(n) asm volatile("s_waitcnt lgkmcnt(" #n ")" ::: "memory")
; #define PG8_BAR __builtin_amdgcn_s_barrier()
; #define PG8_SCHED __builtin_amdgcn_sched_barrier(0)
; template <class Epi, class Sched, bool ALIGN_EPI = false, bool SP2 = false>
; __device__ __forceinline__ void gemm_phase(PG8_LAS unsigned char* lds, const Gemm g, const Sched& S, const Epi& E) {
;     ...
;             PG8_WAIT_V(8); PG8_WAIT_L(0); PG8_BAR; PG8_MMA(1, 0, At, B0); PG8_MMA(1, 1, At, B1); PG8_BAR; PG8_SCHED;
;             PG8_LDB(B0, 1, 0); PG8_LDB(B1, 1, 1); PG8_SCHED; PG8_LDA(At, 1, 0); PG8_STAGE(PG8_SA(0, 1), a2 + hstep, voffA);
;             PG8_WAIT_V(8); PG8_WAIT_L(0); PG8_BAR; PG8_MMA(0, 0, At, B0); PG8_MMA(0, 1, At, B1); PG8_BAR; PG8_SCHED;
	v_mfma_f32_16x16x32_bf16 v[70:73], v[2:5], v[202:205], v[70:73]
	v_mfma_f32_16x16x32_bf16 v[66:69], v[138:141], v[202:205], v[66:69]
	v_mfma_f32_16x16x32_bf16 v[54:57], v[2:5], v[214:217], v[54:57]
	v_mfma_f32_16x16x32_bf16 v[50:53], v[138:141], v[214:217], v[50:53]
	v_mfma_f32_16x16x32_bf16 v[38:41], v[2:5], v[222:225], v[38:41]
	v_mfma_f32_16x16x32_bf16 v[34:37], v[138:141], v[222:225], v[34:37]
	v_mfma_f32_16x16x32_bf16 v[2:5], v[2:5], v[230:233], v[22:25]
	v_mfma_f32_16x16x32_bf16 v[70:73], v[6:9], v[206:209], v[70:73]
	v_mfma_f32_16x16x32_bf16 v[66:69], v[142:145], v[206:209], v[66:69]
	v_mfma_f32_16x16x32_bf16 v[54:57], v[6:9], v[218:221], v[54:57]
	v_mfma_f32_16x16x32_bf16 v[50:53], v[142:145], v[218:221], v[50:53]
	v_mfma_f32_16x16x32_bf16 v[38:41], v[6:9], v[226:229], v[38:41]
	v_mfma_f32_16x16x32_bf16 v[34:37], v[142:145], v[226:229], v[34:37]
	v_mfma_f32_16x16x32_bf16 v[2:5], v[6:9], v[234:237], v[2:5]
	v_mfma_f32_16x16x32_bf16 v[6:9], v[138:141], v[230:233], v[18:21]
	v_mfma_f32_16x16x32_bf16 v[6:9], v[142:145], v[234:237], v[6:9]
	s_setprio 0
	s_setprio 1
	v_mfma_f32_16x16x32_bf16 v[18:21], v[146:149], v[202:205], v[62:65]
	v_mfma_f32_16x16x32_bf16 v[62:65], v[150:153], v[206:209], v[18:21]
	v_mfma_f32_16x16x32_bf16 v[18:21], v[154:157], v[202:205], v[58:61]
	v_mfma_f32_16x16x32_bf16 v[58:61], v[158:161], v[206:209], v[18:21]
	v_mfma_f32_16x16x32_bf16 v[18:21], v[146:149], v[214:217], v[46:49]
	v_mfma_f32_16x16x32_bf16 v[46:49], v[150:153], v[218:221], v[18:21]
	v_mfma_f32_16x16x32_bf16 v[18:21], v[154:157], v[214:217], v[42:45]
	v_mfma_f32_16x16x32_bf16 v[42:45], v[158:161], v[218:221], v[18:21]
	v_mfma_f32_16x16x32_bf16 v[18:21], v[146:149], v[222:225], v[30:33]
	v_mfma_f32_16x16x32_bf16 v[30:33], v[150:153], v[226:229], v[18:21]
	v_mfma_f32_16x16x32_bf16 v[18:21], v[154:157], v[222:225], v[26:29]
	v_mfma_f32_16x16x32_bf16 v[14:17], v[146:149], v[230:233], v[14:17]
	v_mfma_f32_16x16x32_bf16 v[10:13], v[154:157], v[230:233], v[10:13]
	v_mfma_f32_16x16x32_bf16 v[26:29], v[158:161], v[226:229], v[18:21]
	v_mfma_f32_16x16x32_bf16 v[14:17], v[150:153], v[234:237], v[14:17]
	v_mfma_f32_16x16x32_bf16 v[10:13], v[158:161], v[234:237], v[10:13]
	s_barrier
	s_setprio 0
	s_add_i32 s34, 0, 0x18000
	s_add_i32 s35, 0, 0x1c000
	v_add_u32_e32 v142, s34, v179
	v_add_u32_e32 v158, s35, v179
	ds_read_b128 v[18:21], v142
	ds_read_b128 v[22:25], v142 offset:1024
	ds_read_b128 v[138:141], v142 offset:2048
	ds_read_b128 v[142:145], v142 offset:3072
	ds_read_b128 v[146:149], v158
	ds_read_b128 v[150:153], v158 offset:1024
	ds_read_b128 v[154:157], v158 offset:2048
	ds_read_b128 v[158:161], v158 offset:3072
	s_add_u32 s16, s16, 0x100000
	s_addc_u32 s17, s17, 0
	s_mov_b32 m0, s71
	v_lshl_add_u64 v[242:243], s[16:17], 0, v[164:165]
	ds_read_b128 v[202:205], v199 offset:32768
	ds_read_b128 v[206:209], v199 offset:33792
	ds_read_b128 v[214:217], v199 offset:34816
	ds_read_b128 v[218:221], v199 offset:35840
	ds_read_b128 v[222:225], v199 offset:36864
	ds_read_b128 v[226:229], v199 offset:37888
	ds_read_b128 v[230:233], v199 offset:38912
	ds_read_b128 v[234:237], v199 offset:39936
	global_load_lds_dwordx4 v[242:243], off
	v_lshl_add_u64 v[242:243], s[16:17], 0, v[170:171]
	s_mov_b32 m0, s87
	s_nop 0
	global_load_lds_dwordx4 v[242:243], off
	s_waitcnt vmcnt(8)
	s_waitcnt lgkmcnt(0)
	s_setprio 1
	s_barrier
	v_mfma_f32_16x16x32_bf16 v[134:137], v[18:21], v[202:205], v[134:137]
	v_mfma_f32_16x16x32_bf16 v[134:137], v[22:25], v[206:209], v[134:137]
	v_mfma_f32_16x16x32_bf16 v[130:133], v[138:141], v[202:205], v[130:133]
	v_mfma_f32_16x16x32_bf16 v[130:133], v[142:145], v[206:209], v[130:133]
	v_mfma_f32_16x16x32_bf16 v[118:121], v[18:21], v[214:217], v[118:121]
	v_mfma_f32_16x16x32_bf16 v[118:121], v[22:25], v[218:221], v[118:121]
	v_mfma_f32_16x16x32_bf16 v[114:117], v[138:141], v[214:217], v[114:117]
	v_mfma_f32_16x16x32_bf16 v[114:117], v[142:145], v[218:221], v[114:117]
	v_mfma_f32_16x16x32_bf16 v[102:105], v[18:21], v[222:225], v[102:105]
	v_mfma_f32_16x16x32_bf16 v[102:105], v[22:25], v[226:229], v[102:105]
	v_mfma_f32_16x16x32_bf16 v[98:101], v[138:141], v[222:225], v[98:101]
	v_mfma_f32_16x16x32_bf16 v[98:101], v[142:145], v[226:229], v[98:101]
	v_mfma_f32_16x16x32_bf16 v[86:89], v[18:21], v[230:233], v[86:89]
	v_mfma_f32_16x16x32_bf16 v[86:89], v[22:25], v[234:237], v[86:89]
	v_mfma_f32_16x16x32_bf16 v[82:85], v[138:141], v[230:233], v[82:85]
	v_mfma_f32_16x16x32_bf16 v[82:85], v[142:145], v[234:237], v[82:85]
	s_setprio 0
	s_setprio 1
	v_mfma_f32_16x16x32_bf16 v[126:129], v[146:149], v[202:205], v[126:129]
	v_mfma_f32_16x16x32_bf16 v[126:129], v[150:153], v[206:209], v[126:129]
	v_mfma_f32_16x16x32_bf16 v[122:125], v[154:157], v[202:205], v[122:125]
	v_mfma_f32_16x16x32_bf16 v[122:125], v[158:161], v[206:209], v[122:125]
	v_mfma_f32_16x16x32_bf16 v[110:113], v[146:149], v[214:217], v[110:113]
	v_mfma_f32_16x16x32_bf16 v[110:113], v[150:153], v[218:221], v[110:113]
	v_mfma_f32_16x16x32_bf16 v[106:109], v[154:157], v[214:217], v[106:109]
	v_mfma_f32_16x16x32_bf16 v[106:109], v[158:161], v[218:221], v[106:109]
	v_mfma_f32_16x16x32_bf16 v[94:97], v[146:149], v[222:225], v[94:97]
	v_mfma_f32_16x16x32_bf16 v[94:97], v[150:153], v[226:229], v[94:97]
	v_mfma_f32_16x16x32_bf16 v[90:93], v[154:157], v[222:225], v[90:93]
	v_mfma_f32_16x16x32_bf16 v[90:93], v[158:161], v[226:229], v[90:93]
	v_mfma_f32_16x16x32_bf16 v[78:81], v[146:149], v[230:233], v[78:81]
	v_mfma_f32_16x16x32_bf16 v[78:81], v[150:153], v[234:237], v[78:81]
	v_mfma_f32_16x16x32_bf16 v[74:77], v[154:157], v[230:233], v[74:77]
	v_mfma_f32_16x16x32_bf16 v[74:77], v[158:161], v[234:237], v[74:77]
	s_barrier
; #define PG8_STAGE(bufoff, gbase, voff) do { _Pragma("unroll") for (int _i = 0; _i < 2; ++_i) \
;         __builtin_amdgcn_global_load_lds((const unsigned*)((const char*)(gbase) + (voff)[_i]), (PG8_LAS unsigned*)(lds + (bufoff) + ldsw + _i * 8192), 16, 0, 0); } while (0)
; #define PG8_LDA(dst, b, h) do { _Pragma("unroll") for (int m = 0; m < 4; ++m) _Pragma("unroll") for (int k = 0; k < 2; ++k) dst[m][k] = *(const PG8_LAS bf16x8*)(lds + PG8_SA(b, h) + aoff + m * 2048 + k * 1024); } while (0)
; #define PG8_MMA(ai, bj, At, Bt) do { __builtin_amdgcn_s_setprio(1); _Pragma("unroll") for (int m = 0; m < 4; ++m) _Pragma("unroll") for (int n = 0; n < 2; ++n) _Pragma("unroll") for (int k = 0; k < 2; ++k) \
;         acc[ai][bj][m][n] = __builtin_amdgcn_mfma_f32_16x16x32_bf16(Bt[n][k], At[m][k], acc[ai][bj][m][n], 0, 0, 0); __builtin_amdgcn_s_setprio(0); } while (0)
; #define PG8_WAIT_V(n) asm volatile("s_waitcnt vmcnt(" #n ")" ::: "memory")
; #define PG8_WAIT_L(n) asm volatile("s_waitcnt lgkmcnt(" #n ")" ::: "memory")
; #define PG8_BAR __builtin_amdgcn_s_barrier()
; #define PG8_SCHED __builtin_amdgcn_sched_barrier(0)
; template <class Epi, class Sched, bool ALIGN_EPI = false, bool SP2 = false>
; __device__ __forceinline__ void gemm_phase(PG8_LAS unsigned char* lds, const Gemm g, const Sched& S, const Epi& E) {
;     ...
;         for (int t = 0; t < nt; t += 2) {
;             const bool last = (t == nt - 2);
;             const char* a1 = cA + (size_t)(t + 1) * kstep;
;             const char* a2 = last ? nA : cA + (size_t)(t + 2) * kstep; const char* b2 = last ? nB : cB + (size_t)(t + 2) * kstep;
;     ...
;             PG8_LDA(At, 1, 1); PG8_STAGE(PG8_SB(1, 0), b3, voffB); PG8_STAGE(PG8_SB(1, 1), b3 + hstep, voffB); PG8_STAGE(PG8_SA(1, 0), a3, voffA);
;             PG8_WAIT_V(8); PG8_WAIT_L(0); PG8_BAR; PG8_MMA(1, 0, At, B0); PG8_MMA(1, 1, At, B1); PG8_BAR; PG8_SCHED;
	s_setprio 0
	s_add_i32 s16, s34, s25
	v_lshl_add_u64 v[162:163], v[162:163], 0, s[46:47]
	s_mov_b32 m0, s16
	ds_read_b128 v[202:205], v199 offset:49152
	ds_read_b128 v[206:209], v199 offset:50176
	ds_read_b128 v[214:217], v199 offset:51200
	ds_read_b128 v[218:221], v199 offset:52224
	ds_read_b128 v[222:225], v199 offset:53248
	ds_read_b128 v[226:229], v199 offset:54272
	ds_read_b128 v[230:233], v199 offset:55296
	ds_read_b128 v[234:237], v199 offset:56320
	global_load_lds_dwordx4 v[162:163], off
	s_add_i32 m0, s16, 0x2000
	s_add_u32 s14, s14, 0x100080
	v_lshl_add_u64 v[162:163], v[210:211], 0, s[46:47]
	s_addc_u32 s15, s15, 0
	s_add_i32 s16, s35, s25
	global_load_lds_dwordx4 v[162:163], off
	v_lshl_add_u64 v[162:163], s[14:15], 0, v[168:169]
	s_mov_b32 m0, s16
	s_nop 0
	global_load_lds_dwordx4 v[162:163], off
	v_lshl_add_u64 v[162:163], s[14:15], 0, v[172:173]
	s_add_i32 m0, s16, 0x2000
	s_nop 0
	global_load_lds_dwordx4 v[162:163], off
	v_lshl_add_u64 v[162:163], v[238:239], 0, s[46:47]
	s_mov_b32 m0, s95
	s_nop 0
	global_load_lds_dwordx4 v[162:163], off
	v_lshl_add_u64 v[162:163], v[240:241], 0, s[46:47]
	s_mov_b32 m0, s96
	s_nop 0
	global_load_lds_dwordx4 v[162:163], off
	s_waitcnt vmcnt(8)
	s_waitcnt lgkmcnt(0)
	s_setprio 1
	s_barrier
	v_mfma_f32_16x16x32_bf16 v[70:73], v[18:21], v[202:205], v[70:73]
	v_mfma_f32_16x16x32_bf16 v[54:57], v[18:21], v[214:217], v[54:57]
	v_mfma_f32_16x16x32_bf16 v[38:41], v[18:21], v[222:225], v[38:41]
	v_mfma_f32_16x16x32_bf16 v[2:5], v[18:21], v[230:233], v[2:5]
	v_mfma_f32_16x16x32_bf16 v[70:73], v[22:25], v[206:209], v[70:73]
	v_mfma_f32_16x16x32_bf16 v[66:69], v[138:141], v[202:205], v[66:69]
	v_mfma_f32_16x16x32_bf16 v[54:57], v[22:25], v[218:221], v[54:57]
	v_mfma_f32_16x16x32_bf16 v[50:53], v[138:141], v[214:217], v[50:53]
	v_mfma_f32_16x16x32_bf16 v[38:41], v[22:25], v[226:229], v[38:41]
	v_mfma_f32_16x16x32_bf16 v[34:37], v[138:141], v[222:225], v[34:37]
	v_mfma_f32_16x16x32_bf16 v[22:25], v[22:25], v[234:237], v[2:5]
	v_mfma_f32_16x16x32_bf16 v[2:5], v[138:141], v[230:233], v[6:9]
	v_mfma_f32_16x16x32_bf16 v[66:69], v[142:145], v[206:209], v[66:69]
	v_mfma_f32_16x16x32_bf16 v[50:53], v[142:145], v[218:221], v[50:53]
	v_mfma_f32_16x16x32_bf16 v[34:37], v[142:145], v[226:229], v[34:37]
	v_mfma_f32_16x16x32_bf16 v[18:21], v[142:145], v[234:237], v[2:5]
	s_setprio 0
	s_setprio 1
	v_mfma_f32_16x16x32_bf16 v[2:5], v[146:149], v[202:205], v[62:65]
	v_mfma_f32_16x16x32_bf16 v[62:65], v[150:153], v[206:209], v[2:5]
	v_mfma_f32_16x16x32_bf16 v[2:5], v[154:157], v[202:205], v[58:61]
	v_mfma_f32_16x16x32_bf16 v[58:61], v[158:161], v[206:209], v[2:5]
	v_mfma_f32_16x16x32_bf16 v[2:5], v[146:149], v[214:217], v[46:49]
	v_mfma_f32_16x16x32_bf16 v[46:49], v[150:153], v[218:221], v[2:5]
	v_mfma_f32_16x16x32_bf16 v[2:5], v[154:157], v[214:217], v[42:45]
	v_mfma_f32_16x16x32_bf16 v[42:45], v[158:161], v[218:221], v[2:5]
	v_mfma_f32_16x16x32_bf16 v[2:5], v[146:149], v[222:225], v[30:33]
	v_mfma_f32_16x16x32_bf16 v[30:33], v[150:153], v[226:229], v[2:5]
	v_mfma_f32_16x16x32_bf16 v[2:5], v[154:157], v[222:225], v[26:29]
	v_mfma_f32_16x16x32_bf16 v[26:29], v[158:161], v[226:229], v[2:5]
	v_mfma_f32_16x16x32_bf16 v[2:5], v[146:149], v[230:233], v[14:17]
	v_mfma_f32_16x16x32_bf16 v[14:17], v[150:153], v[234:237], v[2:5]
	v_mfma_f32_16x16x32_bf16 v[2:5], v[154:157], v[230:233], v[10:13]
	v_mfma_f32_16x16x32_bf16 v[10:13], v[158:161], v[234:237], v[2:5]
	s_barrier
	s_setprio 0
	s_add_i32 s33, s33, 2
	s_add_u32 s12, s12, 0x100
	s_addc_u32 s13, s13, 0
	s_add_u32 s29, s29, 0x100
	s_addc_u32 s30, s30, 0
	s_cmp_gt_u32 s33, 61
	s_cbranch_scc0 .LBB0_139
	s_and_b64 vcc, exec, s[48:49]
	s_cbranch_vccz .LBB0_142
	s_barrier

; #define PG8_STAGE(bufoff, gbase, voff) do { _Pragma("unroll") for (int _i = 0; _i < 2; ++_i) \
;         __builtin_amdgcn_global_load_lds((const unsigned*)((const char*)(gbase) + (voff)[_i]), (PG8_LAS unsigned*)(lds + (bufoff) + ldsw + _i * 8192), 16, 0, 0); } while (0)
; #define PG8_LDA(dst, b, h) do { _Pragma("unroll") for (int m = 0; m < 4; ++m) _Pragma("unroll") for (int k = 0; k < 2; ++k) dst[m][k] = *(const PG8_LAS bf16x8*)(lds + PG8_SA(b, h) + aoff + m * 2048 + k * 1024); } while (0)
; #define PG8_LDB(dst, b, h) do { _Pragma("unroll") for (int n = 0; n < 2; ++n) _Pragma("unroll") for (int k = 0; k < 2; ++k) dst[n][k] = *(const PG8_LAS bf16x8*)(lds + PG8_SB(b, h) + boff + n * 2048 + k * 1024); } while (0)
; #define PG8_MMA(ai, bj, At, Bt) do { __builtin_amdgcn_s_setprio(1); _Pragma("unroll") for (int m = 0; m < 4; ++m) _Pragma("unroll") for (int n = 0; n < 2; ++n) _Pragma("unroll") for (int k = 0; k < 2; ++k) \
;         acc[ai][bj][m][n] = __builtin_amdgcn_mfma_f32_16x16x32_bf16(Bt[n][k], At[m][k], acc[ai][bj][m][n], 0, 0, 0); __builtin_amdgcn_s_setprio(0); } while (0)
; #define PG8_WAIT_V(n) asm volatile("s_waitcnt vmcnt(" #n ")" ::: "memory")
; #define PG8_WAIT_L(n) asm volatile("s_waitcnt lgkmcnt(" #n ")" ::: "memory")
; template <class Epi, class Sched, bool ALIGN_EPI = false, bool SP2 = false>
; __device__ __forceinline__ void gemm_phase(PG8_LAS unsigned char* lds, const Gemm g, const Sched& S, const Epi& E) {
;     ...
;             const bool last = (t == nt - 2);
;             const char* a1 = cA + (size_t)(t + 1) * kstep;
;             const char* a2 = last ? nA : cA + (size_t)(t + 2) * kstep; const char* b2 = last ? nB : cB + (size_t)(t + 2) * kstep;
;             const char* a3 = a2 + kstep; const char* b3 = b2 + kstep;
;             if (last && has_next) S.a_ready(nxt);
;             if constexpr (SP2) {
;             PG8_LDB(B0, 0, 0); PG8_LDB(B1, 0, 1); PG8_SCHED; PG8_LDA(At, 0, 0); PG8_STAGE(PG8_SA(1, 1), a1 + hstep, voffA);
;             PG8_WAIT_V(8); PG8_WAIT_L(0); PG8_BAR; PG8_MMA(0, 0, At, B0); PG8_MMA(0, 1, At, B1); PG8_BAR; PG8_SCHED;
;             PG8_LDA(At, 0, 1); PG8_STAGE(PG8_SB(0, 0), b2, voffB); PG8_STAGE(PG8_SB(0, 1), b2 + hstep, voffB); PG8_STAGE(PG8_SA(0, 0), a2, voffA);
;             PG8_WAIT_V(8); PG8_WAIT_L(0); PG8_BAR; PG8_MMA(1, 0, At, B0); PG8_MMA(1, 1, At, B1); PG8_BAR; PG8_SCHED;
.LBB0_592:
	s_or_b32 s10, s52, 1
	s_lshl_b64 s[96:97], s[10:11], 7
	s_add_i32 s10, s52, 2
	s_lshl_b64 s[54:55], s[10:11], 7
	s_cmp_lg_u32 s52, s94
	s_cselect_b32 s52, s54, 0
	s_cselect_b32 s53, s55, 0
	s_add_u32 s54, s50, s52
	s_addc_u32 s55, s51, s53
	s_add_i32 s95, 0, 0x10000
	v_add_u32_e32 v87, s95, v85
	ds_read_b128 v[88:91], v87
	ds_read_b128 v[92:95], v87 offset:1024
	ds_read_b128 v[100:103], v87 offset:2048
	ds_read_b128 v[104:107], v87 offset:3072
	s_add_u32 s52, s48, s52
	s_addc_u32 s53, s49, s53
	s_add_u32 s96, s50, s96
	s_addc_u32 s97, s51, s97
	s_add_u32 s96, s96, 0x100000
	s_addc_u32 s97, s97, 0
	v_lshl_add_u64 v[96:97], s[96:97], 0, v[66:67]
	s_add_i32 m0, s17, 0xc000
	ds_read_b128 v[108:111], v86
	ds_read_b128 v[112:115], v86 offset:1024
	ds_read_b128 v[116:119], v86 offset:2048
	ds_read_b128 v[120:123], v86 offset:3072
	ds_read_b128 v[124:127], v86 offset:4096
	ds_read_b128 v[128:131], v86 offset:5120
	ds_read_b128 v[132:135], v86 offset:6144
	ds_read_b128 v[136:139], v86 offset:7168
	global_load_lds_dwordx4 v[96:97], off
	v_lshl_add_u64 v[96:97], s[96:97], 0, v[76:77]
	s_add_i32 m0, s17, 0xe000
	s_nop 0
	global_load_lds_dwordx4 v[96:97], off
	s_waitcnt vmcnt(8)
	s_waitcnt lgkmcnt(0)
	s_setprio 1
	s_barrier
	v_mfma_f32_16x16x32_bf16 v[62:65], v[88:91], v[108:111], v[62:65]
	v_mfma_f32_16x16x32_bf16 v[62:65], v[92:95], v[112:115], v[62:65]
	v_mfma_f32_16x16x32_bf16 v[58:61], v[100:103], v[108:111], v[58:61]
	v_mfma_f32_16x16x32_bf16 v[58:61], v[104:107], v[112:115], v[58:61]
	v_mfma_f32_16x16x32_bf16 v[54:57], v[88:91], v[116:119], v[54:57]
	v_mfma_f32_16x16x32_bf16 v[54:57], v[92:95], v[120:123], v[54:57]
	v_mfma_f32_16x16x32_bf16 v[50:53], v[100:103], v[116:119], v[50:53]
	v_mfma_f32_16x16x32_bf16 v[50:53], v[104:107], v[120:123], v[50:53]
	v_mfma_f32_16x16x32_bf16 v[46:49], v[88:91], v[124:127], v[46:49]
	v_mfma_f32_16x16x32_bf16 v[46:49], v[92:95], v[128:131], v[46:49]
	v_mfma_f32_16x16x32_bf16 v[42:45], v[100:103], v[124:127], v[42:45]
	v_mfma_f32_16x16x32_bf16 v[42:45], v[104:107], v[128:131], v[42:45]
	v_mfma_f32_16x16x32_bf16 v[38:41], v[88:91], v[132:135], v[38:41]
	v_mfma_f32_16x16x32_bf16 v[38:41], v[92:95], v[136:139], v[38:41]
	v_mfma_f32_16x16x32_bf16 v[34:37], v[100:103], v[132:135], v[34:37]
	v_mfma_f32_16x16x32_bf16 v[34:37], v[104:107], v[136:139], v[34:37]
	s_setprio 0
	s_setprio 1
	s_setprio 0
	s_barrier
	s_add_i32 s95, s95, s29
	v_lshl_add_u64 v[96:97], s[52:53], 0, v[78:79]
	s_mov_b32 m0, s95
	ds_read_b128 v[108:111], v86 offset:16384
	ds_read_b128 v[112:115], v86 offset:17408
	ds_read_b128 v[116:119], v86 offset:18432
	ds_read_b128 v[120:123], v86 offset:19456
	ds_read_b128 v[124:127], v86 offset:20480
	ds_read_b128 v[128:131], v86 offset:21504
	ds_read_b128 v[132:135], v86 offset:22528
	ds_read_b128 v[136:139], v86 offset:23552
	global_load_lds_dwordx4 v[96:97], off
	s_add_i32 m0, s95, 0x2000
	s_add_u32 s96, s52, 0x100000
	v_lshl_add_u64 v[140:141], s[52:53], 0, v[74:75]
	s_addc_u32 s97, s53, 0
	global_load_lds_dwordx4 v[140:141], off
	v_lshl_add_u64 v[142:143], s[96:97], 0, v[78:79]
	s_mov_b32 m0, s30
	v_lshl_add_u64 v[144:145], s[54:55], 0, v[76:77]
	global_load_lds_dwordx4 v[142:143], off
	v_lshl_add_u64 v[142:143], s[96:97], 0, v[74:75]
	s_mov_b32 m0, s33
	s_nop 0
	global_load_lds_dwordx4 v[142:143], off
	v_lshl_add_u64 v[142:143], s[54:55], 0, v[66:67]
	s_mov_b32 m0, s17
	s_nop 0
	global_load_lds_dwordx4 v[142:143], off
	s_mov_b32 m0, s34
	s_nop 0
	global_load_lds_dwordx4 v[144:145], off
	s_waitcnt vmcnt(8)
	s_waitcnt lgkmcnt(0)
	s_setprio 1
	s_barrier
	v_mfma_f32_16x16x32_bf16 v[30:33], v[88:91], v[108:111], v[30:33]
	v_mfma_f32_16x16x32_bf16 v[30:33], v[92:95], v[112:115], v[30:33]
	v_mfma_f32_16x16x32_bf16 v[26:29], v[100:103], v[108:111], v[26:29]
	v_mfma_f32_16x16x32_bf16 v[26:29], v[104:107], v[112:115], v[26:29]
	v_mfma_f32_16x16x32_bf16 v[22:25], v[88:91], v[116:119], v[22:25]
	v_mfma_f32_16x16x32_bf16 v[22:25], v[92:95], v[120:123], v[22:25]
	v_mfma_f32_16x16x32_bf16 v[18:21], v[100:103], v[116:119], v[18:21]
	v_mfma_f32_16x16x32_bf16 v[18:21], v[104:107], v[120:123], v[18:21]
	v_mfma_f32_16x16x32_bf16 v[14:17], v[88:91], v[124:127], v[14:17]
	v_mfma_f32_16x16x32_bf16 v[14:17], v[92:95], v[128:131], v[14:17]
	v_mfma_f32_16x16x32_bf16 v[10:13], v[100:103], v[124:127], v[10:13]
	v_mfma_f32_16x16x32_bf16 v[10:13], v[104:107], v[128:131], v[10:13]
	v_mfma_f32_16x16x32_bf16 v[6:9], v[88:91], v[132:135], v[6:9]
	v_mfma_f32_16x16x32_bf16 v[6:9], v[92:95], v[136:139], v[6:9]
	v_mfma_f32_16x16x32_bf16 v[2:5], v[100:103], v[132:135], v[2:5]
	v_mfma_f32_16x16x32_bf16 v[2:5], v[104:107], v[136:139], v[2:5]
	s_setprio 0
	s_setprio 1
	s_setprio 0
	s_barrier
; #define PG8_STAGE(bufoff, gbase, voff) do { _Pragma("unroll") for (int _i = 0; _i < 2; ++_i) \
;         __builtin_amdgcn_global_load_lds((const unsigned*)((const char*)(gbase) + (voff)[_i]), (PG8_LAS unsigned*)(lds + (bufoff) + ldsw + _i * 8192), 16, 0, 0); } while (0)
; #define PG8_LDA(dst, b, h) do { _Pragma("unroll") for (int m = 0; m < 4; ++m) _Pragma("unroll") for (int k = 0; k < 2; ++k) dst[m][k] = *(const PG8_LAS bf16x8*)(lds + PG8_SA(b, h) + aoff + m * 2048 + k * 1024); } while (0)
; #define PG8_LDB(dst, b, h) do { _Pragma("unroll") for (int n = 0; n < 2; ++n) _Pragma("unroll") for (int k = 0; k < 2; ++k) dst[n][k] = *(const PG8_LAS bf16x8*)(lds + PG8_SB(b, h) + boff + n * 2048 + k * 1024); } while (0)
; #define PG8_MMA(ai, bj, At, Bt) do { __builtin_amdgcn_s_setprio(1); _Pragma("unroll") for (int m = 0; m < 4; ++m) _Pragma("unroll") for (int n = 0; n < 2; ++n) _Pragma("unroll") for (int k = 0; k < 2; ++k) \
;         acc[ai][bj][m][n] = __builtin_amdgcn_mfma_f32_16x16x32_bf16(Bt[n][k], At[m][k], acc[ai][bj][m][n], 0, 0, 0); __builtin_amdgcn_s_setprio(0); } while (0)
; #define PG8_WAIT_V(n) asm volatile("s_waitcnt vmcnt(" #n ")" ::: "memory")
; #define PG8_WAIT_L(n) asm volatile("s_waitcnt lgkmcnt(" #n ")" ::: "memory")
; #define PG8_BAR __builtin_amdgcn_s_barrier()
; #define PG8_SCHED __builtin_amdgcn_sched_barrier(0)
; template <class Epi, class Sched, bool ALIGN_EPI = false, bool SP2 = false>
; __device__ __forceinline__ void gemm_phase(PG8_LAS unsigned char* lds, const Gemm g, const Sched& S, const Epi& E) {
;     ...
;             PG8_LDB(B0, 1, 0); PG8_LDB(B1, 1, 1); PG8_SCHED; PG8_LDA(At, 1, 0); PG8_STAGE(PG8_SA(0, 1), a2 + hstep, voffA);
;             PG8_WAIT_V(8); PG8_WAIT_L(0); PG8_BAR; PG8_MMA(0, 0, At, B0); PG8_MMA(0, 1, At, B1); PG8_BAR; PG8_SCHED;
;             PG8_LDA(At, 1, 1); PG8_STAGE(PG8_SB(1, 0), b3, voffB); PG8_STAGE(PG8_SB(1, 1), b3 + hstep, voffB); PG8_STAGE(PG8_SA(1, 0), a3, voffA);
;             PG8_WAIT_V(8); PG8_WAIT_L(0); PG8_BAR; PG8_MMA(1, 0, At, B0); PG8_MMA(1, 1, At, B1); PG8_BAR; PG8_SCHED;
	s_add_i32 s95, 0, 0x18000
	v_add_u32_e32 v87, s95, v85
	ds_read_b128 v[88:91], v87
	ds_read_b128 v[92:95], v87 offset:1024
	ds_read_b128 v[100:103], v87 offset:2048
	ds_read_b128 v[104:107], v87 offset:3072
	s_add_u32 s54, s54, 0x100000
	s_addc_u32 s55, s55, 0
	s_mov_b32 m0, s35
	v_lshl_add_u64 v[146:147], s[54:55], 0, v[66:67]
	ds_read_b128 v[108:111], v86 offset:32768
	ds_read_b128 v[112:115], v86 offset:33792
	ds_read_b128 v[116:119], v86 offset:34816
	ds_read_b128 v[120:123], v86 offset:35840
	ds_read_b128 v[124:127], v86 offset:36864
	ds_read_b128 v[128:131], v86 offset:37888
	ds_read_b128 v[132:135], v86 offset:38912
	ds_read_b128 v[136:139], v86 offset:39936
	global_load_lds_dwordx4 v[146:147], off
	v_lshl_add_u64 v[146:147], s[54:55], 0, v[76:77]
	s_mov_b32 m0, s88
	s_nop 0
	global_load_lds_dwordx4 v[146:147], off
	s_waitcnt vmcnt(8)
	s_waitcnt lgkmcnt(0)
	s_setprio 1
	s_barrier
	v_mfma_f32_16x16x32_bf16 v[62:65], v[88:91], v[108:111], v[62:65]
	v_mfma_f32_16x16x32_bf16 v[62:65], v[92:95], v[112:115], v[62:65]
	v_mfma_f32_16x16x32_bf16 v[58:61], v[100:103], v[108:111], v[58:61]
	v_mfma_f32_16x16x32_bf16 v[58:61], v[104:107], v[112:115], v[58:61]
	v_mfma_f32_16x16x32_bf16 v[54:57], v[88:91], v[116:119], v[54:57]
	v_mfma_f32_16x16x32_bf16 v[54:57], v[92:95], v[120:123], v[54:57]
	v_mfma_f32_16x16x32_bf16 v[50:53], v[100:103], v[116:119], v[50:53]
	v_mfma_f32_16x16x32_bf16 v[50:53], v[104:107], v[120:123], v[50:53]
	v_mfma_f32_16x16x32_bf16 v[46:49], v[88:91], v[124:127], v[46:49]
	v_mfma_f32_16x16x32_bf16 v[46:49], v[92:95], v[128:131], v[46:49]
	v_mfma_f32_16x16x32_bf16 v[42:45], v[100:103], v[124:127], v[42:45]
	v_mfma_f32_16x16x32_bf16 v[42:45], v[104:107], v[128:131], v[42:45]
	v_mfma_f32_16x16x32_bf16 v[38:41], v[88:91], v[132:135], v[38:41]
	v_mfma_f32_16x16x32_bf16 v[38:41], v[92:95], v[136:139], v[38:41]
	v_mfma_f32_16x16x32_bf16 v[34:37], v[100:103], v[132:135], v[34:37]
	v_mfma_f32_16x16x32_bf16 v[34:37], v[104:107], v[136:139], v[34:37]
	s_setprio 0
	s_setprio 1
	s_setprio 0
	s_barrier
	s_add_i32 s54, s95, s29
	v_lshl_add_u64 v[96:97], v[96:97], 0, s[14:15]
	s_mov_b32 m0, s54
	ds_read_b128 v[108:111], v86 offset:49152
	ds_read_b128 v[112:115], v86 offset:50176
	ds_read_b128 v[116:119], v86 offset:51200
	ds_read_b128 v[120:123], v86 offset:52224
	ds_read_b128 v[124:127], v86 offset:53248
	ds_read_b128 v[128:131], v86 offset:54272
	ds_read_b128 v[132:135], v86 offset:55296
	ds_read_b128 v[136:139], v86 offset:56320
	global_load_lds_dwordx4 v[96:97], off
	s_add_i32 m0, s54, 0x2000
	s_add_u32 s52, s52, 0x100080
	v_lshl_add_u64 v[96:97], v[140:141], 0, s[14:15]
	s_addc_u32 s53, s53, 0
	global_load_lds_dwordx4 v[96:97], off
	v_lshl_add_u64 v[96:97], s[52:53], 0, v[78:79]
	s_mov_b32 m0, s92
	s_nop 0
	global_load_lds_dwordx4 v[96:97], off
	v_lshl_add_u64 v[96:97], s[52:53], 0, v[74:75]
	s_mov_b32 m0, s93
	s_nop 0
	global_load_lds_dwordx4 v[96:97], off
	v_lshl_add_u64 v[96:97], v[142:143], 0, s[14:15]
	s_mov_b32 m0, s90
	s_nop 0
	global_load_lds_dwordx4 v[96:97], off
	v_lshl_add_u64 v[96:97], v[144:145], 0, s[14:15]
	s_mov_b32 m0, s91
	s_nop 0
	global_load_lds_dwordx4 v[96:97], off
	s_waitcnt vmcnt(8)
	s_waitcnt lgkmcnt(0)
	s_setprio 1
	s_barrier
	v_mfma_f32_16x16x32_bf16 v[30:33], v[88:91], v[108:111], v[30:33]
	v_mfma_f32_16x16x32_bf16 v[30:33], v[92:95], v[112:115], v[30:33]
	v_mfma_f32_16x16x32_bf16 v[26:29], v[100:103], v[108:111], v[26:29]
	v_mfma_f32_16x16x32_bf16 v[26:29], v[104:107], v[112:115], v[26:29]
	v_mfma_f32_16x16x32_bf16 v[22:25], v[88:91], v[116:119], v[22:25]
	v_mfma_f32_16x16x32_bf16 v[22:25], v[92:95], v[120:123], v[22:25]
	v_mfma_f32_16x16x32_bf16 v[18:21], v[100:103], v[116:119], v[18:21]
	v_mfma_f32_16x16x32_bf16 v[18:21], v[104:107], v[120:123], v[18:21]
	v_mfma_f32_16x16x32_bf16 v[14:17], v[88:91], v[124:127], v[14:17]
	v_mfma_f32_16x16x32_bf16 v[14:17], v[92:95], v[128:131], v[14:17]
	v_mfma_f32_16x16x32_bf16 v[10:13], v[100:103], v[124:127], v[10:13]
	v_mfma_f32_16x16x32_bf16 v[10:13], v[104:107], v[128:131], v[10:13]
	v_mfma_f32_16x16x32_bf16 v[6:9], v[88:91], v[132:135], v[6:9]
	v_mfma_f32_16x16x32_bf16 v[6:9], v[92:95], v[136:139], v[6:9]
	v_mfma_f32_16x16x32_bf16 v[2:5], v[100:103], v[132:135], v[2:5]
	v_mfma_f32_16x16x32_bf16 v[2:5], v[104:107], v[136:139], v[2:5]
	s_setprio 0
	s_setprio 1
	s_setprio 0
	s_barrier
	s_cmp_ge_u32 s10, s28
	s_mov_b32 s52, s10
	s_cbranch_scc0 .LBB0_592
	s_cmpk_lt_u32 s26, 0x100
	s_cbranch_scc0 .LBB0_482
	s_barrier
	s_branch .LBB0_482

; #define PG8_STAGE(bufoff, gbase, voff) do { _Pragma("unroll") for (int _i = 0; _i < 2; ++_i) \
;         __builtin_amdgcn_global_load_lds((const unsigned*)((const char*)(gbase) + (voff)[_i]), (PG8_LAS unsigned*)(lds + (bufoff) + ldsw + _i * 8192), 16, 0, 0); } while (0)
; #define PG8_LDA(dst, b, h) do { _Pragma("unroll") for (int m = 0; m < 4; ++m) _Pragma("unroll") for (int k = 0; k < 2; ++k) dst[m][k] = *(const PG8_LAS bf16x8*)(lds + PG8_SA(b, h) + aoff + m * 2048 + k * 1024); } while (0)
; #define PG8_LDB(dst, b, h) do { _Pragma("unroll") for (int n = 0; n < 2; ++n) _Pragma("unroll") for (int k = 0; k < 2; ++k) dst[n][k] = *(const PG8_LAS bf16x8*)(lds + PG8_SB(b, h) + boff + n * 2048 + k * 1024); } while (0)
; #define PG8_MMA(ai, bj, At, Bt) do { __builtin_amdgcn_s_setprio(1); _Pragma("unroll") for (int m = 0; m < 4; ++m) _Pragma("unroll") for (int n = 0; n < 2; ++n) _Pragma("unroll") for (int k = 0; k < 2; ++k) \
;         acc[ai][bj][m][n] = __builtin_amdgcn_mfma_f32_16x16x32_bf16(Bt[n][k], At[m][k], acc[ai][bj][m][n], 0, 0, 0); __builtin_amdgcn_s_setprio(0); } while (0)
; #define PG8_WAIT_V(n) asm volatile("s_waitcnt vmcnt(" #n ")" ::: "memory")
; #define PG8_WAIT_L(n) asm volatile("s_waitcnt lgkmcnt(" #n ")" ::: "memory")
; template <class Epi, class Sched, bool ALIGN_EPI = false, bool SP2 = false>
; __device__ __forceinline__ void gemm_phase(PG8_LAS unsigned char* lds, const Gemm g, const Sched& S, const Epi& E) {
;     ...
;             const bool last = (t == nt - 2);
;             const char* a1 = cA + (size_t)(t + 1) * kstep;
;             const char* a2 = last ? nA : cA + (size_t)(t + 2) * kstep; const char* b2 = last ? nB : cB + (size_t)(t + 2) * kstep;
;             const char* a3 = a2 + kstep; const char* b3 = b2 + kstep;
;             if (last && has_next) S.a_ready(nxt);
;             if constexpr (SP2) {
;             PG8_LDB(B0, 0, 0); PG8_LDB(B1, 0, 1); PG8_SCHED; PG8_LDA(At, 0, 0); PG8_STAGE(PG8_SA(1, 1), a1 + hstep, voffA);
;             PG8_WAIT_V(8); PG8_WAIT_L(0); PG8_BAR; PG8_MMA(0, 0, At, B0); PG8_MMA(0, 1, At, B1); PG8_BAR; PG8_SCHED;
;             PG8_LDA(At, 0, 1); PG8_STAGE(PG8_SB(0, 0), b2, voffB); PG8_STAGE(PG8_SB(0, 1), b2 + hstep, voffB); PG8_STAGE(PG8_SA(0, 0), a2, voffA);
;             PG8_WAIT_V(8); PG8_WAIT_L(0); PG8_BAR; PG8_MMA(1, 0, At, B0); PG8_MMA(1, 1, At, B1); PG8_BAR; PG8_SCHED;
.LBB0_1062:
	ds_read_b128 v[146:149], v155
	ds_read_b128 v[158:161], v155 offset:1024
	ds_read_b128 v[168:171], v155 offset:2048
	ds_read_b128 v[172:175], v155 offset:3072
	ds_read_b128 v[176:179], v156
	ds_read_b128 v[180:183], v156 offset:1024
	ds_read_b128 v[184:187], v156 offset:2048
	ds_read_b128 v[188:191], v156 offset:3072
	s_add_u32 s72, s70, 0xfff80080
	s_addc_u32 s73, s71, -1
	s_cmp_eq_u32 s77, 28
	s_cselect_b32 s75, s34, s73
	s_cselect_b32 s74, s35, s72
	s_cselect_b32 s73, s61, s76
	s_cselect_b32 s72, s63, s69
	v_lshl_add_u64 v[150:151], s[70:71], 0, v[138:139]
	s_add_i32 m0, s25, 0xc000
	ds_read_b128 v[200:203], v157
	ds_read_b128 v[204:207], v157 offset:1024
	ds_read_b128 v[208:211], v157 offset:2048
	ds_read_b128 v[212:215], v157 offset:3072
	ds_read_b128 v[216:219], v157 offset:4096
	ds_read_b128 v[220:223], v157 offset:5120
	ds_read_b128 v[224:227], v157 offset:6144
	ds_read_b128 v[228:231], v157 offset:7168
	global_load_lds_dwordx4 v[150:151], off
	v_lshl_add_u64 v[150:151], s[70:71], 0, v[140:141]
	s_add_i32 m0, s25, 0xe000
	s_nop 0
	global_load_lds_dwordx4 v[150:151], off
	s_waitcnt vmcnt(8)
	s_waitcnt lgkmcnt(0)
	s_setprio 1
	s_barrier
	v_mfma_f32_16x16x32_bf16 v[126:129], v[146:149], v[200:203], v[126:129]
	v_mfma_f32_16x16x32_bf16 v[126:129], v[158:161], v[204:207], v[126:129]
	v_mfma_f32_16x16x32_bf16 v[122:125], v[168:171], v[200:203], v[122:125]
	v_mfma_f32_16x16x32_bf16 v[122:125], v[172:175], v[204:207], v[122:125]
	v_mfma_f32_16x16x32_bf16 v[110:113], v[146:149], v[208:211], v[110:113]
	v_mfma_f32_16x16x32_bf16 v[110:113], v[158:161], v[212:215], v[110:113]
	v_mfma_f32_16x16x32_bf16 v[106:109], v[168:171], v[208:211], v[106:109]
	v_mfma_f32_16x16x32_bf16 v[106:109], v[172:175], v[212:215], v[106:109]
	v_mfma_f32_16x16x32_bf16 v[94:97], v[146:149], v[216:219], v[94:97]
	v_mfma_f32_16x16x32_bf16 v[94:97], v[158:161], v[220:223], v[94:97]
	v_mfma_f32_16x16x32_bf16 v[90:93], v[168:171], v[216:219], v[90:93]
	v_mfma_f32_16x16x32_bf16 v[90:93], v[172:175], v[220:223], v[90:93]
	v_mfma_f32_16x16x32_bf16 v[78:81], v[146:149], v[224:227], v[78:81]
	v_mfma_f32_16x16x32_bf16 v[78:81], v[158:161], v[228:231], v[78:81]
	v_mfma_f32_16x16x32_bf16 v[74:77], v[168:171], v[224:227], v[74:77]
	v_mfma_f32_16x16x32_bf16 v[74:77], v[172:175], v[228:231], v[74:77]
	s_setprio 0
	s_setprio 1
	v_mfma_f32_16x16x32_bf16 v[118:121], v[176:179], v[200:203], v[118:121]
	v_mfma_f32_16x16x32_bf16 v[118:121], v[180:183], v[204:207], v[118:121]
	v_mfma_f32_16x16x32_bf16 v[114:117], v[184:187], v[200:203], v[114:117]
	v_mfma_f32_16x16x32_bf16 v[114:117], v[188:191], v[204:207], v[114:117]
	v_mfma_f32_16x16x32_bf16 v[102:105], v[176:179], v[208:211], v[102:105]
	v_mfma_f32_16x16x32_bf16 v[102:105], v[180:183], v[212:215], v[102:105]
	v_mfma_f32_16x16x32_bf16 v[98:101], v[184:187], v[208:211], v[98:101]
	v_mfma_f32_16x16x32_bf16 v[98:101], v[188:191], v[212:215], v[98:101]
	v_mfma_f32_16x16x32_bf16 v[86:89], v[176:179], v[216:219], v[86:89]
	v_mfma_f32_16x16x32_bf16 v[86:89], v[180:183], v[220:223], v[86:89]
	v_mfma_f32_16x16x32_bf16 v[82:85], v[184:187], v[216:219], v[82:85]
	v_mfma_f32_16x16x32_bf16 v[82:85], v[188:191], v[220:223], v[82:85]
	v_mfma_f32_16x16x32_bf16 v[70:73], v[176:179], v[224:227], v[70:73]
	v_mfma_f32_16x16x32_bf16 v[70:73], v[180:183], v[228:231], v[70:73]
	v_mfma_f32_16x16x32_bf16 v[66:69], v[184:187], v[224:227], v[66:69]
	v_mfma_f32_16x16x32_bf16 v[66:69], v[188:191], v[228:231], v[66:69]
	s_barrier
	s_setprio 0
	s_add_i32 s78, s31, s2
	v_lshl_add_u64 v[150:151], s[72:73], 0, v[134:135]
	s_mov_b32 m0, s78
	ds_read_b128 v[200:203], v157 offset:16384
	ds_read_b128 v[204:207], v157 offset:17408
	ds_read_b128 v[208:211], v157 offset:18432
	ds_read_b128 v[212:215], v157 offset:19456
	ds_read_b128 v[216:219], v157 offset:20480
	ds_read_b128 v[220:223], v157 offset:21504
	ds_read_b128 v[224:227], v157 offset:22528
	ds_read_b128 v[228:231], v157 offset:23552
	global_load_lds_dwordx4 v[150:151], off
	s_add_i32 m0, s78, 0x2000
	s_add_u32 s78, s72, 0x80000
	v_lshl_add_u64 v[162:163], s[72:73], 0, v[130:131]
	s_addc_u32 s79, s73, 0
	s_add_i32 s80, s40, s2
	global_load_lds_dwordx4 v[162:163], off
	v_lshl_add_u64 v[192:193], s[78:79], 0, v[134:135]
	s_mov_b32 m0, s80
	v_lshl_add_u64 v[232:233], s[74:75], 0, v[132:133]
	global_load_lds_dwordx4 v[192:193], off
	v_lshl_add_u64 v[192:193], s[78:79], 0, v[130:131]
	s_add_i32 m0, s80, 0x2000
	s_nop 0
	global_load_lds_dwordx4 v[192:193], off
	v_lshl_add_u64 v[192:193], s[74:75], 0, v[136:137]
	s_mov_b32 m0, s25
	s_nop 0
	global_load_lds_dwordx4 v[192:193], off
	s_mov_b32 m0, s26
	s_nop 0
	global_load_lds_dwordx4 v[232:233], off
	s_waitcnt vmcnt(8)
	s_waitcnt lgkmcnt(0)
	s_setprio 1
	s_barrier
; #define PG8_STAGE(bufoff, gbase, voff) do { _Pragma("unroll") for (int _i = 0; _i < 2; ++_i) \
;         __builtin_amdgcn_global_load_lds((const unsigned*)((const char*)(gbase) + (voff)[_i]), (PG8_LAS unsigned*)(lds + (bufoff) + ldsw + _i * 8192), 16, 0, 0); } while (0)
; #define PG8_LDA(dst, b, h) do { _Pragma("unroll") for (int m = 0; m < 4; ++m) _Pragma("unroll") for (int k = 0; k < 2; ++k) dst[m][k] = *(const PG8_LAS bf16x8*)(lds + PG8_SA(b, h) + aoff + m * 2048 + k * 1024); } while (0)
; #define PG8_LDB(dst, b, h) do { _Pragma("unroll") for (int n = 0; n < 2; ++n) _Pragma("unroll") for (int k = 0; k < 2; ++k) dst[n][k] = *(const PG8_LAS bf16x8*)(lds + PG8_SB(b, h) + boff + n * 2048 + k * 1024); } while (0)
; #define PG8_MMA(ai, bj, At, Bt) do { __builtin_amdgcn_s_setprio(1); _Pragma("unroll") for (int m = 0; m < 4; ++m) _Pragma("unroll") for (int n = 0; n < 2; ++n) _Pragma("unroll") for (int k = 0; k < 2; ++k) \
;         acc[ai][bj][m][n] = __builtin_amdgcn_mfma_f32_16x16x32_bf16(Bt[n][k], At[m][k], acc[ai][bj][m][n], 0, 0, 0); __builtin_amdgcn_s_setprio(0); } while (0)
; #define PG8_WAIT_V(n) asm volatile("s_waitcnt vmcnt(" #n ")" ::: "memory")
; #define PG8_WAIT_L(n) asm volatile("s_waitcnt lgkmcnt(" #n ")" ::: "memory")
; #define PG8_BAR __builtin_amdgcn_s_barrier()
; #define PG8_SCHED __builtin_amdgcn_sched_barrier(0)
; template <class Epi, class Sched, bool ALIGN_EPI = false, bool SP2 = false>
; __device__ __forceinline__ void gemm_phase(PG8_LAS unsigned char* lds, const Gemm g, const Sched& S, const Epi& E) {
;     ...
;             PG8_WAIT_V(8); PG8_WAIT_L(0); PG8_BAR; PG8_MMA(1, 0, At, B0); PG8_MMA(1, 1, At, B1); PG8_BAR; PG8_SCHED;
;             PG8_LDB(B0, 1, 0); PG8_LDB(B1, 1, 1); PG8_SCHED; PG8_LDA(At, 1, 0); PG8_STAGE(PG8_SA(0, 1), a2 + hstep, voffA);
;             PG8_WAIT_V(8); PG8_WAIT_L(0); PG8_BAR; PG8_MMA(0, 0, At, B0); PG8_MMA(0, 1, At, B1); PG8_BAR; PG8_SCHED;
	v_mfma_f32_16x16x32_bf16 v[62:65], v[146:149], v[200:203], v[62:65]
	v_mfma_f32_16x16x32_bf16 v[62:65], v[158:161], v[204:207], v[62:65]
	v_mfma_f32_16x16x32_bf16 v[58:61], v[168:171], v[200:203], v[58:61]
	v_mfma_f32_16x16x32_bf16 v[58:61], v[172:175], v[204:207], v[58:61]
	v_mfma_f32_16x16x32_bf16 v[46:49], v[146:149], v[208:211], v[46:49]
	v_mfma_f32_16x16x32_bf16 v[46:49], v[158:161], v[212:215], v[46:49]
	v_mfma_f32_16x16x32_bf16 v[42:45], v[168:171], v[208:211], v[42:45]
	v_mfma_f32_16x16x32_bf16 v[42:45], v[172:175], v[212:215], v[42:45]
	v_mfma_f32_16x16x32_bf16 v[30:33], v[146:149], v[216:219], v[30:33]
	v_mfma_f32_16x16x32_bf16 v[30:33], v[158:161], v[220:223], v[30:33]
	v_mfma_f32_16x16x32_bf16 v[26:29], v[168:171], v[216:219], v[26:29]
	v_mfma_f32_16x16x32_bf16 v[26:29], v[172:175], v[220:223], v[26:29]
	v_mfma_f32_16x16x32_bf16 v[14:17], v[146:149], v[224:227], v[14:17]
	v_mfma_f32_16x16x32_bf16 v[14:17], v[158:161], v[228:231], v[14:17]
	v_mfma_f32_16x16x32_bf16 v[10:13], v[168:171], v[224:227], v[10:13]
	v_mfma_f32_16x16x32_bf16 v[10:13], v[172:175], v[228:231], v[10:13]
	s_setprio 0
	s_setprio 1
	v_mfma_f32_16x16x32_bf16 v[54:57], v[176:179], v[200:203], v[54:57]
	v_mfma_f32_16x16x32_bf16 v[54:57], v[180:183], v[204:207], v[54:57]
	v_mfma_f32_16x16x32_bf16 v[50:53], v[184:187], v[200:203], v[50:53]
	v_mfma_f32_16x16x32_bf16 v[50:53], v[188:191], v[204:207], v[50:53]
	v_mfma_f32_16x16x32_bf16 v[38:41], v[176:179], v[208:211], v[38:41]
	v_mfma_f32_16x16x32_bf16 v[38:41], v[180:183], v[212:215], v[38:41]
	v_mfma_f32_16x16x32_bf16 v[34:37], v[184:187], v[208:211], v[34:37]
	v_mfma_f32_16x16x32_bf16 v[34:37], v[188:191], v[212:215], v[34:37]
	v_mfma_f32_16x16x32_bf16 v[22:25], v[176:179], v[216:219], v[22:25]
	v_mfma_f32_16x16x32_bf16 v[22:25], v[180:183], v[220:223], v[22:25]
	v_mfma_f32_16x16x32_bf16 v[18:21], v[184:187], v[216:219], v[18:21]
	v_mfma_f32_16x16x32_bf16 v[18:21], v[188:191], v[220:223], v[18:21]
	v_mfma_f32_16x16x32_bf16 v[6:9], v[176:179], v[224:227], v[6:9]
	v_mfma_f32_16x16x32_bf16 v[6:9], v[180:183], v[228:231], v[6:9]
	v_mfma_f32_16x16x32_bf16 v[2:5], v[184:187], v[224:227], v[2:5]
	v_mfma_f32_16x16x32_bf16 v[2:5], v[188:191], v[228:231], v[2:5]
	s_barrier
	s_setprio 0
	s_add_i32 s78, 0, 0x18000
	v_add_u32_e32 v166, s78, v153
	s_add_i32 s79, 0, 0x1c000
	ds_read_b128 v[146:149], v166
	ds_read_b128 v[158:161], v166 offset:1024
	ds_read_b128 v[168:171], v166 offset:2048
	ds_read_b128 v[172:175], v166 offset:3072
	v_add_u32_e32 v166, s79, v153
	ds_read_b128 v[176:179], v166
	ds_read_b128 v[180:183], v166 offset:1024
	ds_read_b128 v[184:187], v166 offset:2048
	ds_read_b128 v[188:191], v166 offset:3072
	s_add_u32 s74, s74, 0x80000
	s_addc_u32 s75, s75, 0
	s_mov_b32 m0, s27
	v_lshl_add_u64 v[240:241], s[74:75], 0, v[136:137]
	ds_read_b128 v[200:203], v157 offset:32768
	ds_read_b128 v[204:207], v157 offset:33792
	ds_read_b128 v[208:211], v157 offset:34816
	ds_read_b128 v[212:215], v157 offset:35840
	ds_read_b128 v[216:219], v157 offset:36864
	ds_read_b128 v[220:223], v157 offset:37888
	ds_read_b128 v[224:227], v157 offset:38912
	ds_read_b128 v[228:231], v157 offset:39936
	global_load_lds_dwordx4 v[240:241], off
	v_lshl_add_u64 v[240:241], s[74:75], 0, v[132:133]
	s_mov_b32 m0, s28
	s_nop 0
	global_load_lds_dwordx4 v[240:241], off
	s_waitcnt vmcnt(8)
	s_waitcnt lgkmcnt(0)
	s_setprio 1
	s_barrier
	v_mfma_f32_16x16x32_bf16 v[126:129], v[146:149], v[200:203], v[126:129]
	v_mfma_f32_16x16x32_bf16 v[126:129], v[158:161], v[204:207], v[126:129]
	v_mfma_f32_16x16x32_bf16 v[122:125], v[168:171], v[200:203], v[122:125]
	v_mfma_f32_16x16x32_bf16 v[122:125], v[172:175], v[204:207], v[122:125]
	v_mfma_f32_16x16x32_bf16 v[110:113], v[146:149], v[208:211], v[110:113]
	v_mfma_f32_16x16x32_bf16 v[110:113], v[158:161], v[212:215], v[110:113]
	v_mfma_f32_16x16x32_bf16 v[106:109], v[168:171], v[208:211], v[106:109]
	v_mfma_f32_16x16x32_bf16 v[106:109], v[172:175], v[212:215], v[106:109]
	v_mfma_f32_16x16x32_bf16 v[94:97], v[146:149], v[216:219], v[94:97]
	v_mfma_f32_16x16x32_bf16 v[94:97], v[158:161], v[220:223], v[94:97]
	v_mfma_f32_16x16x32_bf16 v[90:93], v[168:171], v[216:219], v[90:93]
	v_mfma_f32_16x16x32_bf16 v[90:93], v[172:175], v[220:223], v[90:93]
	v_mfma_f32_16x16x32_bf16 v[78:81], v[146:149], v[224:227], v[78:81]
	v_mfma_f32_16x16x32_bf16 v[78:81], v[158:161], v[228:231], v[78:81]
	v_mfma_f32_16x16x32_bf16 v[74:77], v[168:171], v[224:227], v[74:77]
	v_mfma_f32_16x16x32_bf16 v[74:77], v[172:175], v[228:231], v[74:77]
	s_setprio 0
	s_setprio 1
	v_mfma_f32_16x16x32_bf16 v[118:121], v[176:179], v[200:203], v[118:121]
	v_mfma_f32_16x16x32_bf16 v[118:121], v[180:183], v[204:207], v[118:121]
	v_mfma_f32_16x16x32_bf16 v[114:117], v[184:187], v[200:203], v[114:117]
	v_mfma_f32_16x16x32_bf16 v[114:117], v[188:191], v[204:207], v[114:117]
	v_mfma_f32_16x16x32_bf16 v[102:105], v[176:179], v[208:211], v[102:105]
	v_mfma_f32_16x16x32_bf16 v[102:105], v[180:183], v[212:215], v[102:105]
	v_mfma_f32_16x16x32_bf16 v[98:101], v[184:187], v[208:211], v[98:101]
	v_mfma_f32_16x16x32_bf16 v[98:101], v[188:191], v[212:215], v[98:101]
	v_mfma_f32_16x16x32_bf16 v[86:89], v[176:179], v[216:219], v[86:89]
	v_mfma_f32_16x16x32_bf16 v[86:89], v[180:183], v[220:223], v[86:89]
	v_mfma_f32_16x16x32_bf16 v[82:85], v[184:187], v[216:219], v[82:85]
	v_mfma_f32_16x16x32_bf16 v[82:85], v[188:191], v[220:223], v[82:85]
	v_mfma_f32_16x16x32_bf16 v[70:73], v[176:179], v[224:227], v[70:73]
	v_mfma_f32_16x16x32_bf16 v[70:73], v[180:183], v[228:231], v[70:73]
	v_mfma_f32_16x16x32_bf16 v[66:69], v[184:187], v[224:227], v[66:69]
	v_mfma_f32_16x16x32_bf16 v[66:69], v[188:191], v[228:231], v[66:69]
	s_barrier
; #define PG8_STAGE(bufoff, gbase, voff) do { _Pragma("unroll") for (int _i = 0; _i < 2; ++_i) \
;         __builtin_amdgcn_global_load_lds((const unsigned*)((const char*)(gbase) + (voff)[_i]), (PG8_LAS unsigned*)(lds + (bufoff) + ldsw + _i * 8192), 16, 0, 0); } while (0)
; #define PG8_LDA(dst, b, h) do { _Pragma("unroll") for (int m = 0; m < 4; ++m) _Pragma("unroll") for (int k = 0; k < 2; ++k) dst[m][k] = *(const PG8_LAS bf16x8*)(lds + PG8_SA(b, h) + aoff + m * 2048 + k * 1024); } while (0)
; #define PG8_MMA(ai, bj, At, Bt) do { __builtin_amdgcn_s_setprio(1); _Pragma("unroll") for (int m = 0; m < 4; ++m) _Pragma("unroll") for (int n = 0; n < 2; ++n) _Pragma("unroll") for (int k = 0; k < 2; ++k) \
;         acc[ai][bj][m][n] = __builtin_amdgcn_mfma_f32_16x16x32_bf16(Bt[n][k], At[m][k], acc[ai][bj][m][n], 0, 0, 0); __builtin_amdgcn_s_setprio(0); } while (0)
; #define PG8_WAIT_V(n) asm volatile("s_waitcnt vmcnt(" #n ")" ::: "memory")
; #define PG8_WAIT_L(n) asm volatile("s_waitcnt lgkmcnt(" #n ")" ::: "memory")
; #define PG8_BAR __builtin_amdgcn_s_barrier()
; #define PG8_SCHED __builtin_amdgcn_sched_barrier(0)
; template <class Epi, class Sched, bool ALIGN_EPI = false, bool SP2 = false>
; __device__ __forceinline__ void gemm_phase(PG8_LAS unsigned char* lds, const Gemm g, const Sched& S, const Epi& E) {
;     ...
;         for (int t = 0; t < nt; t += 2) {
;             const bool last = (t == nt - 2);
;             const char* a1 = cA + (size_t)(t + 1) * kstep;
;             const char* a2 = last ? nA : cA + (size_t)(t + 2) * kstep; const char* b2 = last ? nB : cB + (size_t)(t + 2) * kstep;
;     ...
;             PG8_LDA(At, 1, 1); PG8_STAGE(PG8_SB(1, 0), b3, voffB); PG8_STAGE(PG8_SB(1, 1), b3 + hstep, voffB); PG8_STAGE(PG8_SA(1, 0), a3, voffA);
;             PG8_WAIT_V(8); PG8_WAIT_L(0); PG8_BAR; PG8_MMA(1, 0, At, B0); PG8_MMA(1, 1, At, B1); PG8_BAR; PG8_SCHED;
	s_setprio 0
	s_add_i32 s74, s78, s2
	v_lshl_add_u64 v[150:151], v[150:151], 0, s[10:11]
	s_mov_b32 m0, s74
	ds_read_b128 v[200:203], v157 offset:49152
	ds_read_b128 v[204:207], v157 offset:50176
	ds_read_b128 v[208:211], v157 offset:51200
	ds_read_b128 v[212:215], v157 offset:52224
	ds_read_b128 v[216:219], v157 offset:53248
	ds_read_b128 v[220:223], v157 offset:54272
	ds_read_b128 v[224:227], v157 offset:55296
	ds_read_b128 v[228:231], v157 offset:56320
	global_load_lds_dwordx4 v[150:151], off
	s_add_i32 m0, s74, 0x2000
	s_add_u32 s72, s72, 0x80080
	v_lshl_add_u64 v[150:151], v[162:163], 0, s[10:11]
	s_addc_u32 s73, s73, 0
	s_add_i32 s74, s79, s2
	global_load_lds_dwordx4 v[150:151], off
	v_lshl_add_u64 v[150:151], s[72:73], 0, v[134:135]
	s_mov_b32 m0, s74
	s_nop 0
	global_load_lds_dwordx4 v[150:151], off
	v_lshl_add_u64 v[150:151], s[72:73], 0, v[130:131]
	s_add_i32 m0, s74, 0x2000
	s_nop 0
	global_load_lds_dwordx4 v[150:151], off
	v_lshl_add_u64 v[150:151], v[192:193], 0, s[10:11]
	s_mov_b32 m0, s30
	s_nop 0
	global_load_lds_dwordx4 v[150:151], off
	v_lshl_add_u64 v[150:151], v[232:233], 0, s[10:11]
	s_mov_b32 m0, s33
	s_nop 0
	global_load_lds_dwordx4 v[150:151], off
	s_waitcnt vmcnt(8)
	s_waitcnt lgkmcnt(0)
	s_setprio 1
	s_barrier
	v_mfma_f32_16x16x32_bf16 v[62:65], v[146:149], v[200:203], v[62:65]
	v_mfma_f32_16x16x32_bf16 v[62:65], v[158:161], v[204:207], v[62:65]
	v_mfma_f32_16x16x32_bf16 v[58:61], v[168:171], v[200:203], v[58:61]
	v_mfma_f32_16x16x32_bf16 v[58:61], v[172:175], v[204:207], v[58:61]
	v_mfma_f32_16x16x32_bf16 v[46:49], v[146:149], v[208:211], v[46:49]
	v_mfma_f32_16x16x32_bf16 v[46:49], v[158:161], v[212:215], v[46:49]
	v_mfma_f32_16x16x32_bf16 v[42:45], v[168:171], v[208:211], v[42:45]
	v_mfma_f32_16x16x32_bf16 v[42:45], v[172:175], v[212:215], v[42:45]
	v_mfma_f32_16x16x32_bf16 v[30:33], v[146:149], v[216:219], v[30:33]
	v_mfma_f32_16x16x32_bf16 v[30:33], v[158:161], v[220:223], v[30:33]
	v_mfma_f32_16x16x32_bf16 v[26:29], v[168:171], v[216:219], v[26:29]
	v_mfma_f32_16x16x32_bf16 v[26:29], v[172:175], v[220:223], v[26:29]
	v_mfma_f32_16x16x32_bf16 v[14:17], v[146:149], v[224:227], v[14:17]
	v_mfma_f32_16x16x32_bf16 v[14:17], v[158:161], v[228:231], v[14:17]
	v_mfma_f32_16x16x32_bf16 v[10:13], v[168:171], v[224:227], v[10:13]
	v_mfma_f32_16x16x32_bf16 v[10:13], v[172:175], v[228:231], v[10:13]
	s_setprio 0
	s_setprio 1
	v_mfma_f32_16x16x32_bf16 v[54:57], v[176:179], v[200:203], v[54:57]
	v_mfma_f32_16x16x32_bf16 v[54:57], v[180:183], v[204:207], v[54:57]
	v_mfma_f32_16x16x32_bf16 v[50:53], v[184:187], v[200:203], v[50:53]
	v_mfma_f32_16x16x32_bf16 v[50:53], v[188:191], v[204:207], v[50:53]
	v_mfma_f32_16x16x32_bf16 v[38:41], v[176:179], v[208:211], v[38:41]
	v_mfma_f32_16x16x32_bf16 v[38:41], v[180:183], v[212:215], v[38:41]
	v_mfma_f32_16x16x32_bf16 v[34:37], v[184:187], v[208:211], v[34:37]
	v_mfma_f32_16x16x32_bf16 v[34:37], v[188:191], v[212:215], v[34:37]
	v_mfma_f32_16x16x32_bf16 v[22:25], v[176:179], v[216:219], v[22:25]
	v_mfma_f32_16x16x32_bf16 v[22:25], v[180:183], v[220:223], v[22:25]
	v_mfma_f32_16x16x32_bf16 v[18:21], v[184:187], v[216:219], v[18:21]
	v_mfma_f32_16x16x32_bf16 v[18:21], v[188:191], v[220:223], v[18:21]
	v_mfma_f32_16x16x32_bf16 v[6:9], v[176:179], v[224:227], v[6:9]
	v_mfma_f32_16x16x32_bf16 v[6:9], v[180:183], v[228:231], v[6:9]
	v_mfma_f32_16x16x32_bf16 v[2:5], v[184:187], v[224:227], v[2:5]
	v_mfma_f32_16x16x32_bf16 v[2:5], v[188:191], v[228:231], v[2:5]
	s_barrier
	s_setprio 0
	s_add_i32 s77, s77, 2
	s_add_u32 s70, s70, 0x100
	s_addc_u32 s71, s71, 0
	s_add_u32 s69, s69, 0x100
	s_addc_u32 s76, s76, 0
	s_cmp_gt_u32 s77, 29
	s_cbranch_scc0 .LBB0_1062
	s_and_b64 vcc, exec, s[48:49]
	s_cbranch_vccz .LBB0_1065
	s_barrier

; #define PG8_STAGE(bufoff, gbase, voff) do { _Pragma("unroll") for (int _i = 0; _i < 2; ++_i) \
;         __builtin_amdgcn_global_load_lds((const unsigned*)((const char*)(gbase) + (voff)[_i]), (PG8_LAS unsigned*)(lds + (bufoff) + ldsw + _i * 8192), 16, 0, 0); } while (0)
; #define PG8_LDA(dst, b, h) do { _Pragma("unroll") for (int m = 0; m < 4; ++m) _Pragma("unroll") for (int k = 0; k < 2; ++k) dst[m][k] = *(const PG8_LAS bf16x8*)(lds + PG8_SA(b, h) + aoff + m * 2048 + k * 1024); } while (0)
; #define PG8_LDB(dst, b, h) do { _Pragma("unroll") for (int n = 0; n < 2; ++n) _Pragma("unroll") for (int k = 0; k < 2; ++k) dst[n][k] = *(const PG8_LAS bf16x8*)(lds + PG8_SB(b, h) + boff + n * 2048 + k * 1024); } while (0)
; #define PG8_MMA(ai, bj, At, Bt) do { __builtin_amdgcn_s_setprio(1); _Pragma("unroll") for (int m = 0; m < 4; ++m) _Pragma("unroll") for (int n = 0; n < 2; ++n) _Pragma("unroll") for (int k = 0; k < 2; ++k) \
;         acc[ai][bj][m][n] = __builtin_amdgcn_mfma_f32_16x16x32_bf16(Bt[n][k], At[m][k], acc[ai][bj][m][n], 0, 0, 0); __builtin_amdgcn_s_setprio(0); } while (0)
; #define PG8_WAIT_V(n) asm volatile("s_waitcnt vmcnt(" #n ")" ::: "memory")
; #define PG8_WAIT_L(n) asm volatile("s_waitcnt lgkmcnt(" #n ")" ::: "memory")
; template <class Epi, class Sched, bool ALIGN_EPI = false, bool SP2 = false>
; __device__ __forceinline__ void gemm_phase(PG8_LAS unsigned char* lds, const Gemm g, const Sched& S, const Epi& E) {
;     ...
;             const bool last = (t == nt - 2);
;             const char* a1 = cA + (size_t)(t + 1) * kstep;
;             const char* a2 = last ? nA : cA + (size_t)(t + 2) * kstep; const char* b2 = last ? nB : cB + (size_t)(t + 2) * kstep;
;             const char* a3 = a2 + kstep; const char* b3 = b2 + kstep;
;             if (last && has_next) S.a_ready(nxt);
;             if constexpr (SP2) {
;             PG8_LDB(B0, 0, 0); PG8_LDB(B1, 0, 1); PG8_SCHED; PG8_LDA(At, 0, 0); PG8_STAGE(PG8_SA(1, 1), a1 + hstep, voffA);
;             PG8_WAIT_V(8); PG8_WAIT_L(0); PG8_BAR; PG8_MMA(0, 0, At, B0); PG8_MMA(0, 1, At, B1); PG8_BAR; PG8_SCHED;
;             PG8_LDA(At, 0, 1); PG8_STAGE(PG8_SB(0, 0), b2, voffB); PG8_STAGE(PG8_SB(0, 1), b2 + hstep, voffB); PG8_STAGE(PG8_SA(0, 0), a2, voffA);
;             PG8_WAIT_V(8); PG8_WAIT_L(0); PG8_BAR; PG8_MMA(1, 0, At, B0); PG8_MMA(1, 1, At, B1); PG8_BAR; PG8_SCHED;
.LBB0_1078:
	ds_read_b128 v[146:149], v155
	ds_read_b128 v[158:161], v155 offset:1024
	ds_read_b128 v[168:171], v155 offset:2048
	ds_read_b128 v[172:175], v155 offset:3072
	ds_read_b128 v[176:179], v156
	ds_read_b128 v[180:183], v156 offset:1024
	ds_read_b128 v[184:187], v156 offset:2048
	ds_read_b128 v[188:191], v156 offset:3072
	s_add_u32 s68, s66, 0xfff80080
	s_addc_u32 s69, s67, -1
	s_cmp_eq_u32 s73, 28
	s_cselect_b32 s71, s34, s69
	s_cselect_b32 s70, s35, s68
	s_cselect_b32 s69, s57, s72
	s_cselect_b32 s68, s59, s65
	v_lshl_add_u64 v[150:151], s[66:67], 0, v[138:139]
	s_add_i32 m0, s25, 0xc000
	ds_read_b128 v[200:203], v157
	ds_read_b128 v[204:207], v157 offset:1024
	ds_read_b128 v[208:211], v157 offset:2048
	ds_read_b128 v[212:215], v157 offset:3072
	ds_read_b128 v[216:219], v157 offset:4096
	ds_read_b128 v[220:223], v157 offset:5120
	ds_read_b128 v[224:227], v157 offset:6144
	ds_read_b128 v[228:231], v157 offset:7168
	global_load_lds_dwordx4 v[150:151], off
	v_lshl_add_u64 v[150:151], s[66:67], 0, v[140:141]
	s_add_i32 m0, s25, 0xe000
	s_nop 0
	global_load_lds_dwordx4 v[150:151], off
	s_waitcnt vmcnt(8)
	s_waitcnt lgkmcnt(0)
	s_setprio 1
	s_barrier
	v_mfma_f32_16x16x32_bf16 v[126:129], v[146:149], v[200:203], v[126:129]
	v_mfma_f32_16x16x32_bf16 v[126:129], v[158:161], v[204:207], v[126:129]
	v_mfma_f32_16x16x32_bf16 v[122:125], v[168:171], v[200:203], v[122:125]
	v_mfma_f32_16x16x32_bf16 v[122:125], v[172:175], v[204:207], v[122:125]
	v_mfma_f32_16x16x32_bf16 v[110:113], v[146:149], v[208:211], v[110:113]
	v_mfma_f32_16x16x32_bf16 v[110:113], v[158:161], v[212:215], v[110:113]
	v_mfma_f32_16x16x32_bf16 v[106:109], v[168:171], v[208:211], v[106:109]
	v_mfma_f32_16x16x32_bf16 v[106:109], v[172:175], v[212:215], v[106:109]
	v_mfma_f32_16x16x32_bf16 v[94:97], v[146:149], v[216:219], v[94:97]
	v_mfma_f32_16x16x32_bf16 v[94:97], v[158:161], v[220:223], v[94:97]
	v_mfma_f32_16x16x32_bf16 v[90:93], v[168:171], v[216:219], v[90:93]
	v_mfma_f32_16x16x32_bf16 v[90:93], v[172:175], v[220:223], v[90:93]
	v_mfma_f32_16x16x32_bf16 v[78:81], v[146:149], v[224:227], v[78:81]
	v_mfma_f32_16x16x32_bf16 v[78:81], v[158:161], v[228:231], v[78:81]
	v_mfma_f32_16x16x32_bf16 v[74:77], v[168:171], v[224:227], v[74:77]
	v_mfma_f32_16x16x32_bf16 v[74:77], v[172:175], v[228:231], v[74:77]
	s_setprio 0
	s_setprio 1
	v_mfma_f32_16x16x32_bf16 v[118:121], v[176:179], v[200:203], v[118:121]
	v_mfma_f32_16x16x32_bf16 v[118:121], v[180:183], v[204:207], v[118:121]
	v_mfma_f32_16x16x32_bf16 v[114:117], v[184:187], v[200:203], v[114:117]
	v_mfma_f32_16x16x32_bf16 v[114:117], v[188:191], v[204:207], v[114:117]
	v_mfma_f32_16x16x32_bf16 v[102:105], v[176:179], v[208:211], v[102:105]
	v_mfma_f32_16x16x32_bf16 v[102:105], v[180:183], v[212:215], v[102:105]
	v_mfma_f32_16x16x32_bf16 v[98:101], v[184:187], v[208:211], v[98:101]
	v_mfma_f32_16x16x32_bf16 v[98:101], v[188:191], v[212:215], v[98:101]
	v_mfma_f32_16x16x32_bf16 v[86:89], v[176:179], v[216:219], v[86:89]
	v_mfma_f32_16x16x32_bf16 v[86:89], v[180:183], v[220:223], v[86:89]
	v_mfma_f32_16x16x32_bf16 v[82:85], v[184:187], v[216:219], v[82:85]
	v_mfma_f32_16x16x32_bf16 v[82:85], v[188:191], v[220:223], v[82:85]
	v_mfma_f32_16x16x32_bf16 v[70:73], v[176:179], v[224:227], v[70:73]
	v_mfma_f32_16x16x32_bf16 v[70:73], v[180:183], v[228:231], v[70:73]
	v_mfma_f32_16x16x32_bf16 v[66:69], v[184:187], v[224:227], v[66:69]
	v_mfma_f32_16x16x32_bf16 v[66:69], v[188:191], v[228:231], v[66:69]
	s_barrier
	s_setprio 0
	s_add_i32 s74, s31, s2
	v_lshl_add_u64 v[150:151], s[68:69], 0, v[134:135]
	s_mov_b32 m0, s74
	ds_read_b128 v[200:203], v157 offset:16384
	ds_read_b128 v[204:207], v157 offset:17408
	ds_read_b128 v[208:211], v157 offset:18432
	ds_read_b128 v[212:215], v157 offset:19456
	ds_read_b128 v[216:219], v157 offset:20480
	ds_read_b128 v[220:223], v157 offset:21504
	ds_read_b128 v[224:227], v157 offset:22528
	ds_read_b128 v[228:231], v157 offset:23552
	global_load_lds_dwordx4 v[150:151], off
	s_add_i32 m0, s74, 0x2000
	s_add_u32 s74, s68, 0x80000
	v_lshl_add_u64 v[162:163], s[68:69], 0, v[130:131]
	s_addc_u32 s75, s69, 0
	s_add_i32 s76, s40, s2
	global_load_lds_dwordx4 v[162:163], off
	v_lshl_add_u64 v[192:193], s[74:75], 0, v[134:135]
	s_mov_b32 m0, s76
	v_lshl_add_u64 v[232:233], s[70:71], 0, v[132:133]
	global_load_lds_dwordx4 v[192:193], off
	v_lshl_add_u64 v[192:193], s[74:75], 0, v[130:131]
	s_add_i32 m0, s76, 0x2000
	s_nop 0
	global_load_lds_dwordx4 v[192:193], off
	v_lshl_add_u64 v[192:193], s[70:71], 0, v[136:137]
	s_mov_b32 m0, s25
	s_nop 0
	global_load_lds_dwordx4 v[192:193], off
	s_mov_b32 m0, s26
	s_nop 0
	global_load_lds_dwordx4 v[232:233], off
	s_waitcnt vmcnt(8)
	s_waitcnt lgkmcnt(0)
	s_setprio 1
	s_barrier
; #define PG8_STAGE(bufoff, gbase, voff) do { _Pragma("unroll") for (int _i = 0; _i < 2; ++_i) \
;         __builtin_amdgcn_global_load_lds((const unsigned*)((const char*)(gbase) + (voff)[_i]), (PG8_LAS unsigned*)(lds + (bufoff) + ldsw + _i * 8192), 16, 0, 0); } while (0)
; #define PG8_LDA(dst, b, h) do { _Pragma("unroll") for (int m = 0; m < 4; ++m) _Pragma("unroll") for (int k = 0; k < 2; ++k) dst[m][k] = *(const PG8_LAS bf16x8*)(lds + PG8_SA(b, h) + aoff + m * 2048 + k * 1024); } while (0)
; #define PG8_LDB(dst, b, h) do { _Pragma("unroll") for (int n = 0; n < 2; ++n) _Pragma("unroll") for (int k = 0; k < 2; ++k) dst[n][k] = *(const PG8_LAS bf16x8*)(lds + PG8_SB(b, h) + boff + n * 2048 + k * 1024); } while (0)
; #define PG8_MMA(ai, bj, At, Bt) do { __builtin_amdgcn_s_setprio(1); _Pragma("unroll") for (int m = 0; m < 4; ++m) _Pragma("unroll") for (int n = 0; n < 2; ++n) _Pragma("unroll") for (int k = 0; k < 2; ++k) \
;         acc[ai][bj][m][n] = __builtin_amdgcn_mfma_f32_16x16x32_bf16(Bt[n][k], At[m][k], acc[ai][bj][m][n], 0, 0, 0); __builtin_amdgcn_s_setprio(0); } while (0)
; #define PG8_WAIT_V(n) asm volatile("s_waitcnt vmcnt(" #n ")" ::: "memory")
; #define PG8_WAIT_L(n) asm volatile("s_waitcnt lgkmcnt(" #n ")" ::: "memory")
; #define PG8_BAR __builtin_amdgcn_s_barrier()
; #define PG8_SCHED __builtin_amdgcn_sched_barrier(0)
; template <class Epi, class Sched, bool ALIGN_EPI = false, bool SP2 = false>
; __device__ __forceinline__ void gemm_phase(PG8_LAS unsigned char* lds, const Gemm g, const Sched& S, const Epi& E) {
;     ...
;             PG8_WAIT_V(8); PG8_WAIT_L(0); PG8_BAR; PG8_MMA(1, 0, At, B0); PG8_MMA(1, 1, At, B1); PG8_BAR; PG8_SCHED;
;             PG8_LDB(B0, 1, 0); PG8_LDB(B1, 1, 1); PG8_SCHED; PG8_LDA(At, 1, 0); PG8_STAGE(PG8_SA(0, 1), a2 + hstep, voffA);
;             PG8_WAIT_V(8); PG8_WAIT_L(0); PG8_BAR; PG8_MMA(0, 0, At, B0); PG8_MMA(0, 1, At, B1); PG8_BAR; PG8_SCHED;
	v_mfma_f32_16x16x32_bf16 v[62:65], v[146:149], v[200:203], v[62:65]
	v_mfma_f32_16x16x32_bf16 v[62:65], v[158:161], v[204:207], v[62:65]
	v_mfma_f32_16x16x32_bf16 v[58:61], v[168:171], v[200:203], v[58:61]
	v_mfma_f32_16x16x32_bf16 v[58:61], v[172:175], v[204:207], v[58:61]
	v_mfma_f32_16x16x32_bf16 v[46:49], v[146:149], v[208:211], v[46:49]
	v_mfma_f32_16x16x32_bf16 v[46:49], v[158:161], v[212:215], v[46:49]
	v_mfma_f32_16x16x32_bf16 v[42:45], v[168:171], v[208:211], v[42:45]
	v_mfma_f32_16x16x32_bf16 v[42:45], v[172:175], v[212:215], v[42:45]
	v_mfma_f32_16x16x32_bf16 v[30:33], v[146:149], v[216:219], v[30:33]
	v_mfma_f32_16x16x32_bf16 v[30:33], v[158:161], v[220:223], v[30:33]
	v_mfma_f32_16x16x32_bf16 v[26:29], v[168:171], v[216:219], v[26:29]
	v_mfma_f32_16x16x32_bf16 v[26:29], v[172:175], v[220:223], v[26:29]
	v_mfma_f32_16x16x32_bf16 v[14:17], v[146:149], v[224:227], v[14:17]
	v_mfma_f32_16x16x32_bf16 v[14:17], v[158:161], v[228:231], v[14:17]
	v_mfma_f32_16x16x32_bf16 v[10:13], v[168:171], v[224:227], v[10:13]
	v_mfma_f32_16x16x32_bf16 v[10:13], v[172:175], v[228:231], v[10:13]
	s_setprio 0
	s_setprio 1
	v_mfma_f32_16x16x32_bf16 v[54:57], v[176:179], v[200:203], v[54:57]
	v_mfma_f32_16x16x32_bf16 v[54:57], v[180:183], v[204:207], v[54:57]
	v_mfma_f32_16x16x32_bf16 v[50:53], v[184:187], v[200:203], v[50:53]
	v_mfma_f32_16x16x32_bf16 v[50:53], v[188:191], v[204:207], v[50:53]
	v_mfma_f32_16x16x32_bf16 v[38:41], v[176:179], v[208:211], v[38:41]
	v_mfma_f32_16x16x32_bf16 v[38:41], v[180:183], v[212:215], v[38:41]
	v_mfma_f32_16x16x32_bf16 v[34:37], v[184:187], v[208:211], v[34:37]
	v_mfma_f32_16x16x32_bf16 v[34:37], v[188:191], v[212:215], v[34:37]
	v_mfma_f32_16x16x32_bf16 v[22:25], v[176:179], v[216:219], v[22:25]
	v_mfma_f32_16x16x32_bf16 v[22:25], v[180:183], v[220:223], v[22:25]
	v_mfma_f32_16x16x32_bf16 v[18:21], v[184:187], v[216:219], v[18:21]
	v_mfma_f32_16x16x32_bf16 v[18:21], v[188:191], v[220:223], v[18:21]
	v_mfma_f32_16x16x32_bf16 v[6:9], v[176:179], v[224:227], v[6:9]
	v_mfma_f32_16x16x32_bf16 v[6:9], v[180:183], v[228:231], v[6:9]
	v_mfma_f32_16x16x32_bf16 v[2:5], v[184:187], v[224:227], v[2:5]
	v_mfma_f32_16x16x32_bf16 v[2:5], v[188:191], v[228:231], v[2:5]
	s_barrier
	s_setprio 0
	s_add_i32 s74, 0, 0x18000
	v_add_u32_e32 v166, s74, v153
	s_add_i32 s75, 0, 0x1c000
	ds_read_b128 v[146:149], v166
	ds_read_b128 v[158:161], v166 offset:1024
	ds_read_b128 v[168:171], v166 offset:2048
	ds_read_b128 v[172:175], v166 offset:3072
	v_add_u32_e32 v166, s75, v153
	ds_read_b128 v[176:179], v166
	ds_read_b128 v[180:183], v166 offset:1024
	ds_read_b128 v[184:187], v166 offset:2048
	ds_read_b128 v[188:191], v166 offset:3072
	s_add_u32 s70, s70, 0x80000
	s_addc_u32 s71, s71, 0
	s_mov_b32 m0, s27
	v_lshl_add_u64 v[240:241], s[70:71], 0, v[136:137]
	ds_read_b128 v[200:203], v157 offset:32768
	ds_read_b128 v[204:207], v157 offset:33792
	ds_read_b128 v[208:211], v157 offset:34816
	ds_read_b128 v[212:215], v157 offset:35840
	ds_read_b128 v[216:219], v157 offset:36864
	ds_read_b128 v[220:223], v157 offset:37888
	ds_read_b128 v[224:227], v157 offset:38912
	ds_read_b128 v[228:231], v157 offset:39936
	global_load_lds_dwordx4 v[240:241], off
	v_lshl_add_u64 v[240:241], s[70:71], 0, v[132:133]
	s_mov_b32 m0, s28
	s_nop 0
	global_load_lds_dwordx4 v[240:241], off
	s_waitcnt vmcnt(8)
	s_waitcnt lgkmcnt(0)
	s_setprio 1
	s_barrier
	v_mfma_f32_16x16x32_bf16 v[126:129], v[146:149], v[200:203], v[126:129]
	v_mfma_f32_16x16x32_bf16 v[126:129], v[158:161], v[204:207], v[126:129]
	v_mfma_f32_16x16x32_bf16 v[122:125], v[168:171], v[200:203], v[122:125]
	v_mfma_f32_16x16x32_bf16 v[122:125], v[172:175], v[204:207], v[122:125]
	v_mfma_f32_16x16x32_bf16 v[110:113], v[146:149], v[208:211], v[110:113]
	v_mfma_f32_16x16x32_bf16 v[110:113], v[158:161], v[212:215], v[110:113]
	v_mfma_f32_16x16x32_bf16 v[106:109], v[168:171], v[208:211], v[106:109]
	v_mfma_f32_16x16x32_bf16 v[106:109], v[172:175], v[212:215], v[106:109]
	v_mfma_f32_16x16x32_bf16 v[94:97], v[146:149], v[216:219], v[94:97]
	v_mfma_f32_16x16x32_bf16 v[94:97], v[158:161], v[220:223], v[94:97]
	v_mfma_f32_16x16x32_bf16 v[90:93], v[168:171], v[216:219], v[90:93]
	v_mfma_f32_16x16x32_bf16 v[90:93], v[172:175], v[220:223], v[90:93]
	v_mfma_f32_16x16x32_bf16 v[78:81], v[146:149], v[224:227], v[78:81]
	v_mfma_f32_16x16x32_bf16 v[78:81], v[158:161], v[228:231], v[78:81]
	v_mfma_f32_16x16x32_bf16 v[74:77], v[168:171], v[224:227], v[74:77]
	v_mfma_f32_16x16x32_bf16 v[74:77], v[172:175], v[228:231], v[74:77]
	s_setprio 0
	s_setprio 1
	v_mfma_f32_16x16x32_bf16 v[118:121], v[176:179], v[200:203], v[118:121]
	v_mfma_f32_16x16x32_bf16 v[118:121], v[180:183], v[204:207], v[118:121]
	v_mfma_f32_16x16x32_bf16 v[114:117], v[184:187], v[200:203], v[114:117]
	v_mfma_f32_16x16x32_bf16 v[114:117], v[188:191], v[204:207], v[114:117]
	v_mfma_f32_16x16x32_bf16 v[102:105], v[176:179], v[208:211], v[102:105]
	v_mfma_f32_16x16x32_bf16 v[102:105], v[180:183], v[212:215], v[102:105]
	v_mfma_f32_16x16x32_bf16 v[98:101], v[184:187], v[208:211], v[98:101]
	v_mfma_f32_16x16x32_bf16 v[98:101], v[188:191], v[212:215], v[98:101]
	v_mfma_f32_16x16x32_bf16 v[86:89], v[176:179], v[216:219], v[86:89]
	v_mfma_f32_16x16x32_bf16 v[86:89], v[180:183], v[220:223], v[86:89]
	v_mfma_f32_16x16x32_bf16 v[82:85], v[184:187], v[216:219], v[82:85]
	v_mfma_f32_16x16x32_bf16 v[82:85], v[188:191], v[220:223], v[82:85]
	v_mfma_f32_16x16x32_bf16 v[70:73], v[176:179], v[224:227], v[70:73]
	v_mfma_f32_16x16x32_bf16 v[70:73], v[180:183], v[228:231], v[70:73]
	v_mfma_f32_16x16x32_bf16 v[66:69], v[184:187], v[224:227], v[66:69]
	v_mfma_f32_16x16x32_bf16 v[66:69], v[188:191], v[228:231], v[66:69]
	s_barrier
; #define PG8_STAGE(bufoff, gbase, voff) do { _Pragma("unroll") for (int _i = 0; _i < 2; ++_i) \
;         __builtin_amdgcn_global_load_lds((const unsigned*)((const char*)(gbase) + (voff)[_i]), (PG8_LAS unsigned*)(lds + (bufoff) + ldsw + _i * 8192), 16, 0, 0); } while (0)
; #define PG8_LDA(dst, b, h) do { _Pragma("unroll") for (int m = 0; m < 4; ++m) _Pragma("unroll") for (int k = 0; k < 2; ++k) dst[m][k] = *(const PG8_LAS bf16x8*)(lds + PG8_SA(b, h) + aoff + m * 2048 + k * 1024); } while (0)
; #define PG8_MMA(ai, bj, At, Bt) do { __builtin_amdgcn_s_setprio(1); _Pragma("unroll") for (int m = 0; m < 4; ++m) _Pragma("unroll") for (int n = 0; n < 2; ++n) _Pragma("unroll") for (int k = 0; k < 2; ++k) \
;         acc[ai][bj][m][n] = __builtin_amdgcn_mfma_f32_16x16x32_bf16(Bt[n][k], At[m][k], acc[ai][bj][m][n], 0, 0, 0); __builtin_amdgcn_s_setprio(0); } while (0)
; #define PG8_WAIT_V(n) asm volatile("s_waitcnt vmcnt(" #n ")" ::: "memory")
; #define PG8_WAIT_L(n) asm volatile("s_waitcnt lgkmcnt(" #n ")" ::: "memory")
; #define PG8_BAR __builtin_amdgcn_s_barrier()
; #define PG8_SCHED __builtin_amdgcn_sched_barrier(0)
; template <class Epi, class Sched, bool ALIGN_EPI = false, bool SP2 = false>
; __device__ __forceinline__ void gemm_phase(PG8_LAS unsigned char* lds, const Gemm g, const Sched& S, const Epi& E) {
;     ...
;         for (int t = 0; t < nt; t += 2) {
;             const bool last = (t == nt - 2);
;             const char* a1 = cA + (size_t)(t + 1) * kstep;
;             const char* a2 = last ? nA : cA + (size_t)(t + 2) * kstep; const char* b2 = last ? nB : cB + (size_t)(t + 2) * kstep;
;             const char* a3 = a2 + kstep; const char* b3 = b2 + kstep;
;     ...
;             PG8_LDA(At, 1, 1); PG8_STAGE(PG8_SB(1, 0), b3, voffB); PG8_STAGE(PG8_SB(1, 1), b3 + hstep, voffB); PG8_STAGE(PG8_SA(1, 0), a3, voffA);
;             PG8_WAIT_V(8); PG8_WAIT_L(0); PG8_BAR; PG8_MMA(1, 0, At, B0); PG8_MMA(1, 1, At, B1); PG8_BAR; PG8_SCHED;
	s_setprio 0
	s_add_i32 s70, s74, s2
	v_lshl_add_u64 v[150:151], v[150:151], 0, s[8:9]
	s_mov_b32 m0, s70
	ds_read_b128 v[200:203], v157 offset:49152
	ds_read_b128 v[204:207], v157 offset:50176
	ds_read_b128 v[208:211], v157 offset:51200
	ds_read_b128 v[212:215], v157 offset:52224
	ds_read_b128 v[216:219], v157 offset:53248
	ds_read_b128 v[220:223], v157 offset:54272
	ds_read_b128 v[224:227], v157 offset:55296
	ds_read_b128 v[228:231], v157 offset:56320
	global_load_lds_dwordx4 v[150:151], off
	s_add_i32 m0, s70, 0x2000
	s_add_u32 s68, s68, 0x80080
	v_lshl_add_u64 v[150:151], v[162:163], 0, s[8:9]
	s_addc_u32 s69, s69, 0
	s_add_i32 s70, s75, s2
	global_load_lds_dwordx4 v[150:151], off
	v_lshl_add_u64 v[150:151], s[68:69], 0, v[134:135]
	s_mov_b32 m0, s70
	s_nop 0
	global_load_lds_dwordx4 v[150:151], off
	v_lshl_add_u64 v[150:151], s[68:69], 0, v[130:131]
	s_add_i32 m0, s70, 0x2000
	s_nop 0
	global_load_lds_dwordx4 v[150:151], off
	v_lshl_add_u64 v[150:151], v[192:193], 0, s[8:9]
	s_mov_b32 m0, s30
	s_nop 0
	global_load_lds_dwordx4 v[150:151], off
	v_lshl_add_u64 v[150:151], v[232:233], 0, s[8:9]
	s_mov_b32 m0, s33
	s_nop 0
	global_load_lds_dwordx4 v[150:151], off
	s_waitcnt vmcnt(8)
	s_waitcnt lgkmcnt(0)
	s_setprio 1
	s_barrier
	v_mfma_f32_16x16x32_bf16 v[62:65], v[146:149], v[200:203], v[62:65]
	v_mfma_f32_16x16x32_bf16 v[62:65], v[158:161], v[204:207], v[62:65]
	v_mfma_f32_16x16x32_bf16 v[58:61], v[168:171], v[200:203], v[58:61]
	v_mfma_f32_16x16x32_bf16 v[58:61], v[172:175], v[204:207], v[58:61]
	v_mfma_f32_16x16x32_bf16 v[46:49], v[146:149], v[208:211], v[46:49]
	v_mfma_f32_16x16x32_bf16 v[46:49], v[158:161], v[212:215], v[46:49]
	v_mfma_f32_16x16x32_bf16 v[42:45], v[168:171], v[208:211], v[42:45]
	v_mfma_f32_16x16x32_bf16 v[42:45], v[172:175], v[212:215], v[42:45]
	v_mfma_f32_16x16x32_bf16 v[30:33], v[146:149], v[216:219], v[30:33]
	v_mfma_f32_16x16x32_bf16 v[30:33], v[158:161], v[220:223], v[30:33]
	v_mfma_f32_16x16x32_bf16 v[26:29], v[168:171], v[216:219], v[26:29]
	v_mfma_f32_16x16x32_bf16 v[26:29], v[172:175], v[220:223], v[26:29]
	v_mfma_f32_16x16x32_bf16 v[14:17], v[146:149], v[224:227], v[14:17]
	v_mfma_f32_16x16x32_bf16 v[14:17], v[158:161], v[228:231], v[14:17]
	v_mfma_f32_16x16x32_bf16 v[10:13], v[168:171], v[224:227], v[10:13]
	v_mfma_f32_16x16x32_bf16 v[10:13], v[172:175], v[228:231], v[10:13]
	s_setprio 0
	s_setprio 1
	v_mfma_f32_16x16x32_bf16 v[54:57], v[176:179], v[200:203], v[54:57]
	v_mfma_f32_16x16x32_bf16 v[54:57], v[180:183], v[204:207], v[54:57]
	v_mfma_f32_16x16x32_bf16 v[50:53], v[184:187], v[200:203], v[50:53]
	v_mfma_f32_16x16x32_bf16 v[50:53], v[188:191], v[204:207], v[50:53]
	v_mfma_f32_16x16x32_bf16 v[38:41], v[176:179], v[208:211], v[38:41]
	v_mfma_f32_16x16x32_bf16 v[38:41], v[180:183], v[212:215], v[38:41]
	v_mfma_f32_16x16x32_bf16 v[34:37], v[184:187], v[208:211], v[34:37]
	v_mfma_f32_16x16x32_bf16 v[34:37], v[188:191], v[212:215], v[34:37]
	v_mfma_f32_16x16x32_bf16 v[22:25], v[176:179], v[216:219], v[22:25]
	v_mfma_f32_16x16x32_bf16 v[22:25], v[180:183], v[220:223], v[22:25]
	v_mfma_f32_16x16x32_bf16 v[18:21], v[184:187], v[216:219], v[18:21]
	v_mfma_f32_16x16x32_bf16 v[18:21], v[188:191], v[220:223], v[18:21]
	v_mfma_f32_16x16x32_bf16 v[6:9], v[176:179], v[224:227], v[6:9]
	v_mfma_f32_16x16x32_bf16 v[6:9], v[180:183], v[228:231], v[6:9]
	v_mfma_f32_16x16x32_bf16 v[2:5], v[184:187], v[224:227], v[2:5]
	v_mfma_f32_16x16x32_bf16 v[2:5], v[188:191], v[228:231], v[2:5]
	s_barrier
	s_setprio 0
	s_add_i32 s73, s73, 2
	s_add_u32 s66, s66, 0x100
	s_addc_u32 s67, s67, 0
	s_add_u32 s65, s65, 0x100
	s_addc_u32 s72, s72, 0
	s_cmp_gt_u32 s73, 29
	s_cbranch_scc0 .LBB0_1078
	s_and_b64 vcc, exec, s[10:11]
	s_cbranch_vccz .LBB0_1081
	s_barrier

; #define PG8_STAGE(bufoff, gbase, voff) do { _Pragma("unroll") for (int _i = 0; _i < 2; ++_i) \
;         __builtin_amdgcn_global_load_lds((const unsigned*)((const char*)(gbase) + (voff)[_i]), (PG8_LAS unsigned*)(lds + (bufoff) + ldsw + _i * 8192), 16, 0, 0); } while (0)
; #define PG8_LDA(dst, b, h) do { _Pragma("unroll") for (int m = 0; m < 4; ++m) _Pragma("unroll") for (int k = 0; k < 2; ++k) dst[m][k] = *(const PG8_LAS bf16x8*)(lds + PG8_SA(b, h) + aoff + m * 2048 + k * 1024); } while (0)
; #define PG8_LDB(dst, b, h) do { _Pragma("unroll") for (int n = 0; n < 2; ++n) _Pragma("unroll") for (int k = 0; k < 2; ++k) dst[n][k] = *(const PG8_LAS bf16x8*)(lds + PG8_SB(b, h) + boff + n * 2048 + k * 1024); } while (0)
; #define PG8_MMA(ai, bj, At, Bt) do { __builtin_amdgcn_s_setprio(1); _Pragma("unroll") for (int m = 0; m < 4; ++m) _Pragma("unroll") for (int n = 0; n < 2; ++n) _Pragma("unroll") for (int k = 0; k < 2; ++k) \
;         acc[ai][bj][m][n] = __builtin_amdgcn_mfma_f32_16x16x32_bf16(Bt[n][k], At[m][k], acc[ai][bj][m][n], 0, 0, 0); __builtin_amdgcn_s_setprio(0); } while (0)
; #define PG8_WAIT_V(n) asm volatile("s_waitcnt vmcnt(" #n ")" ::: "memory")
; #define PG8_WAIT_L(n) asm volatile("s_waitcnt lgkmcnt(" #n ")" ::: "memory")
; #define PG8_BAR __builtin_amdgcn_s_barrier()
; #define PG8_SCHED __builtin_amdgcn_sched_barrier(0)
; template <class Epi, class Sched, bool ALIGN_EPI = false, bool SP2 = false>
; __device__ __forceinline__ void gemm_phase(PG8_LAS unsigned char* lds, const Gemm g, const Sched& S, const Epi& E) {
;     ...
;             const bool last = (t == nt - 2);
;             const char* a1 = cA + (size_t)(t + 1) * kstep;
;             const char* a2 = last ? nA : cA + (size_t)(t + 2) * kstep; const char* b2 = last ? nB : cB + (size_t)(t + 2) * kstep;
;             const char* a3 = a2 + kstep; const char* b3 = b2 + kstep;
;             if (last && has_next) S.a_ready(nxt);
;             if constexpr (SP2) {
;             PG8_LDB(B0, 0, 0); PG8_LDB(B1, 0, 1); PG8_SCHED; PG8_LDA(At, 0, 0); PG8_STAGE(PG8_SA(1, 1), a1 + hstep, voffA);
;             PG8_WAIT_V(8); PG8_WAIT_L(0); PG8_BAR; PG8_MMA(0, 0, At, B0); PG8_MMA(0, 1, At, B1); PG8_BAR; PG8_SCHED;
;             PG8_LDA(At, 0, 1); PG8_STAGE(PG8_SB(0, 0), b2, voffB); PG8_STAGE(PG8_SB(0, 1), b2 + hstep, voffB); PG8_STAGE(PG8_SA(0, 0), a2, voffA);
.LBB0_1203:
	ds_read_b128 v[146:149], v171
	ds_read_b128 v[176:179], v171 offset:1024
	ds_read_b128 v[180:183], v171 offset:2048
	ds_read_b128 v[184:187], v171 offset:3072
	ds_read_b128 v[188:191], v172
	ds_read_b128 v[200:203], v172 offset:1024
	ds_read_b128 v[204:207], v172 offset:2048
	ds_read_b128 v[208:211], v172 offset:3072
	s_add_u32 s63, s64, 0xfff00080
	s_addc_u32 s66, s65, -1
	s_cmp_eq_u32 s61, 60
	s_cselect_b32 s69, s34, s66
	s_cselect_b32 s68, s35, s63
	s_cselect_b32 s67, s40, s55
	s_cselect_b32 s66, s41, s53
	v_lshl_add_u64 v[150:151], s[64:65], 0, v[138:139]
	s_add_i32 m0, s4, 0xc000
	ds_read_b128 v[212:215], v173
	ds_read_b128 v[216:219], v173 offset:1024
	ds_read_b128 v[220:223], v173 offset:2048
	ds_read_b128 v[224:227], v173 offset:3072
	ds_read_b128 v[228:231], v173 offset:4096
	ds_read_b128 v[240:243], v173 offset:5120
	ds_read_b128 v[244:247], v173 offset:6144
	ds_read_b128 v[248:251], v173 offset:7168
	global_load_lds_dwordx4 v[150:151], off
	v_lshl_add_u64 v[150:151], s[64:65], 0, v[140:141]
	s_add_i32 m0, s4, 0xe000
	s_nop 0
	global_load_lds_dwordx4 v[150:151], off
	s_waitcnt vmcnt(8)
	s_waitcnt lgkmcnt(0)
	s_setprio 1
	s_barrier
	v_mfma_f32_16x16x32_bf16 v[126:129], v[146:149], v[212:215], v[126:129]
	v_mfma_f32_16x16x32_bf16 v[126:129], v[176:179], v[216:219], v[126:129]
	v_mfma_f32_16x16x32_bf16 v[122:125], v[180:183], v[212:215], v[122:125]
	v_mfma_f32_16x16x32_bf16 v[122:125], v[184:187], v[216:219], v[122:125]
	v_mfma_f32_16x16x32_bf16 v[110:113], v[146:149], v[220:223], v[110:113]
	v_mfma_f32_16x16x32_bf16 v[110:113], v[176:179], v[224:227], v[110:113]
	v_mfma_f32_16x16x32_bf16 v[106:109], v[180:183], v[220:223], v[106:109]
	v_mfma_f32_16x16x32_bf16 v[106:109], v[184:187], v[224:227], v[106:109]
	v_mfma_f32_16x16x32_bf16 v[94:97], v[146:149], v[228:231], v[94:97]
	v_mfma_f32_16x16x32_bf16 v[94:97], v[176:179], v[240:243], v[94:97]
	v_mfma_f32_16x16x32_bf16 v[90:93], v[180:183], v[228:231], v[90:93]
	v_mfma_f32_16x16x32_bf16 v[90:93], v[184:187], v[240:243], v[90:93]
	v_mfma_f32_16x16x32_bf16 v[78:81], v[146:149], v[244:247], v[78:81]
	v_mfma_f32_16x16x32_bf16 v[78:81], v[176:179], v[248:251], v[78:81]
	v_mfma_f32_16x16x32_bf16 v[74:77], v[180:183], v[244:247], v[74:77]
	v_mfma_f32_16x16x32_bf16 v[74:77], v[184:187], v[248:251], v[74:77]
	s_setprio 0
	s_setprio 1
	v_mfma_f32_16x16x32_bf16 v[118:121], v[188:191], v[212:215], v[118:121]
	v_mfma_f32_16x16x32_bf16 v[118:121], v[200:203], v[216:219], v[118:121]
	v_mfma_f32_16x16x32_bf16 v[114:117], v[204:207], v[212:215], v[114:117]
	v_mfma_f32_16x16x32_bf16 v[114:117], v[208:211], v[216:219], v[114:117]
	v_mfma_f32_16x16x32_bf16 v[102:105], v[188:191], v[220:223], v[102:105]
	v_mfma_f32_16x16x32_bf16 v[102:105], v[200:203], v[224:227], v[102:105]
	v_mfma_f32_16x16x32_bf16 v[98:101], v[204:207], v[220:223], v[98:101]
	v_mfma_f32_16x16x32_bf16 v[98:101], v[208:211], v[224:227], v[98:101]
	v_mfma_f32_16x16x32_bf16 v[86:89], v[188:191], v[228:231], v[86:89]
	v_mfma_f32_16x16x32_bf16 v[86:89], v[200:203], v[240:243], v[86:89]
	v_mfma_f32_16x16x32_bf16 v[82:85], v[204:207], v[228:231], v[82:85]
	v_mfma_f32_16x16x32_bf16 v[82:85], v[208:211], v[240:243], v[82:85]
	v_mfma_f32_16x16x32_bf16 v[70:73], v[188:191], v[244:247], v[70:73]
	v_mfma_f32_16x16x32_bf16 v[70:73], v[200:203], v[248:251], v[70:73]
	v_mfma_f32_16x16x32_bf16 v[66:69], v[204:207], v[244:247], v[66:69]
	v_mfma_f32_16x16x32_bf16 v[66:69], v[208:211], v[248:251], v[66:69]
	s_barrier
	s_setprio 0
	s_add_i32 s63, s31, s2
	v_lshl_add_u64 v[150:151], s[66:67], 0, v[132:133]
	s_mov_b32 m0, s63
	ds_read_b128 v[212:215], v173 offset:16384
	ds_read_b128 v[216:219], v173 offset:17408
	ds_read_b128 v[220:223], v173 offset:18432
	ds_read_b128 v[224:227], v173 offset:19456
	ds_read_b128 v[228:231], v173 offset:20480
	ds_read_b128 v[240:243], v173 offset:21504
	ds_read_b128 v[244:247], v173 offset:22528
	ds_read_b128 v[248:251], v173 offset:23552
	global_load_lds_dwordx4 v[150:151], off
	s_add_i32 m0, s63, 0x2000
	s_add_u32 s70, s66, 0x100000
	v_lshl_add_u64 v[192:193], s[66:67], 0, v[136:137]
	s_addc_u32 s71, s67, 0
	s_add_i32 s63, s39, s2
	global_load_lds_dwordx4 v[192:193], off
	v_lshl_add_u64 v[232:233], s[70:71], 0, v[132:133]
	s_mov_b32 m0, s63
	v_lshl_add_u64 v[252:253], s[68:69], 0, v[134:135]
	global_load_lds_dwordx4 v[232:233], off
	v_lshl_add_u64 v[232:233], s[70:71], 0, v[136:137]
	s_add_i32 m0, s63, 0x2000
	s_nop 0
	global_load_lds_dwordx4 v[232:233], off
	v_lshl_add_u64 v[232:233], s[68:69], 0, v[130:131]
	s_mov_b32 m0, s4
	s_nop 0
	global_load_lds_dwordx4 v[232:233], off
	s_mov_b32 m0, s5
	s_nop 0
	global_load_lds_dwordx4 v[252:253], off
	s_waitcnt vmcnt(8)
	s_waitcnt lgkmcnt(0)
	s_setprio 1
	s_barrier
; #define PG8_STAGE(bufoff, gbase, voff) do { _Pragma("unroll") for (int _i = 0; _i < 2; ++_i) \
;         __builtin_amdgcn_global_load_lds((const unsigned*)((const char*)(gbase) + (voff)[_i]), (PG8_LAS unsigned*)(lds + (bufoff) + ldsw + _i * 8192), 16, 0, 0); } while (0)
; #define PG8_LDA(dst, b, h) do { _Pragma("unroll") for (int m = 0; m < 4; ++m) _Pragma("unroll") for (int k = 0; k < 2; ++k) dst[m][k] = *(const PG8_LAS bf16x8*)(lds + PG8_SA(b, h) + aoff + m * 2048 + k * 1024); } while (0)
; #define PG8_LDB(dst, b, h) do { _Pragma("unroll") for (int n = 0; n < 2; ++n) _Pragma("unroll") for (int k = 0; k < 2; ++k) dst[n][k] = *(const PG8_LAS bf16x8*)(lds + PG8_SB(b, h) + boff + n * 2048 + k * 1024); } while (0)
; #define PG8_MMA(ai, bj, At, Bt) do { __builtin_amdgcn_s_setprio(1); _Pragma("unroll") for (int m = 0; m < 4; ++m) _Pragma("unroll") for (int n = 0; n < 2; ++n) _Pragma("unroll") for (int k = 0; k < 2; ++k) \
;         acc[ai][bj][m][n] = __builtin_amdgcn_mfma_f32_16x16x32_bf16(Bt[n][k], At[m][k], acc[ai][bj][m][n], 0, 0, 0); __builtin_amdgcn_s_setprio(0); } while (0)
; #define PG8_WAIT_V(n) asm volatile("s_waitcnt vmcnt(" #n ")" ::: "memory")
; #define PG8_WAIT_L(n) asm volatile("s_waitcnt lgkmcnt(" #n ")" ::: "memory")
; #define PG8_BAR __builtin_amdgcn_s_barrier()
; #define PG8_SCHED __builtin_amdgcn_sched_barrier(0)
; template <class Epi, class Sched, bool ALIGN_EPI = false, bool SP2 = false>
; __device__ __forceinline__ void gemm_phase(PG8_LAS unsigned char* lds, const Gemm g, const Sched& S, const Epi& E) {
;     ...
;             PG8_WAIT_V(8); PG8_WAIT_L(0); PG8_BAR; PG8_MMA(1, 0, At, B0); PG8_MMA(1, 1, At, B1); PG8_BAR; PG8_SCHED;
;             PG8_LDB(B0, 1, 0); PG8_LDB(B1, 1, 1); PG8_SCHED; PG8_LDA(At, 1, 0); PG8_STAGE(PG8_SA(0, 1), a2 + hstep, voffA);
;             PG8_WAIT_V(8); PG8_WAIT_L(0); PG8_BAR; PG8_MMA(0, 0, At, B0); PG8_MMA(0, 1, At, B1); PG8_BAR; PG8_SCHED;
	v_mfma_f32_16x16x32_bf16 v[62:65], v[146:149], v[212:215], v[62:65]
	v_mfma_f32_16x16x32_bf16 v[62:65], v[176:179], v[216:219], v[62:65]
	v_mfma_f32_16x16x32_bf16 v[58:61], v[180:183], v[212:215], v[58:61]
	v_mfma_f32_16x16x32_bf16 v[58:61], v[184:187], v[216:219], v[58:61]
	v_mfma_f32_16x16x32_bf16 v[46:49], v[146:149], v[220:223], v[46:49]
	v_mfma_f32_16x16x32_bf16 v[46:49], v[176:179], v[224:227], v[46:49]
	v_mfma_f32_16x16x32_bf16 v[42:45], v[180:183], v[220:223], v[42:45]
	v_mfma_f32_16x16x32_bf16 v[42:45], v[184:187], v[224:227], v[42:45]
	v_mfma_f32_16x16x32_bf16 v[30:33], v[146:149], v[228:231], v[30:33]
	v_mfma_f32_16x16x32_bf16 v[30:33], v[176:179], v[240:243], v[30:33]
	v_mfma_f32_16x16x32_bf16 v[26:29], v[180:183], v[228:231], v[26:29]
	v_mfma_f32_16x16x32_bf16 v[26:29], v[184:187], v[240:243], v[26:29]
	v_mfma_f32_16x16x32_bf16 v[14:17], v[146:149], v[244:247], v[14:17]
	v_mfma_f32_16x16x32_bf16 v[14:17], v[176:179], v[248:251], v[14:17]
	v_mfma_f32_16x16x32_bf16 v[10:13], v[180:183], v[244:247], v[10:13]
	v_mfma_f32_16x16x32_bf16 v[10:13], v[184:187], v[248:251], v[10:13]
	s_setprio 0
	s_setprio 1
	v_mfma_f32_16x16x32_bf16 v[54:57], v[188:191], v[212:215], v[54:57]
	v_mfma_f32_16x16x32_bf16 v[54:57], v[200:203], v[216:219], v[54:57]
	v_mfma_f32_16x16x32_bf16 v[50:53], v[204:207], v[212:215], v[50:53]
	v_mfma_f32_16x16x32_bf16 v[50:53], v[208:211], v[216:219], v[50:53]
	v_mfma_f32_16x16x32_bf16 v[38:41], v[188:191], v[220:223], v[38:41]
	v_mfma_f32_16x16x32_bf16 v[38:41], v[200:203], v[224:227], v[38:41]
	v_mfma_f32_16x16x32_bf16 v[34:37], v[204:207], v[220:223], v[34:37]
	v_mfma_f32_16x16x32_bf16 v[34:37], v[208:211], v[224:227], v[34:37]
	v_mfma_f32_16x16x32_bf16 v[22:25], v[188:191], v[228:231], v[22:25]
	v_mfma_f32_16x16x32_bf16 v[22:25], v[200:203], v[240:243], v[22:25]
	v_mfma_f32_16x16x32_bf16 v[18:21], v[204:207], v[228:231], v[18:21]
	v_mfma_f32_16x16x32_bf16 v[18:21], v[208:211], v[240:243], v[18:21]
	v_mfma_f32_16x16x32_bf16 v[6:9], v[188:191], v[244:247], v[6:9]
	v_mfma_f32_16x16x32_bf16 v[6:9], v[200:203], v[248:251], v[6:9]
	v_mfma_f32_16x16x32_bf16 v[2:5], v[204:207], v[244:247], v[2:5]
	v_mfma_f32_16x16x32_bf16 v[2:5], v[208:211], v[248:251], v[2:5]
	s_barrier
	s_setprio 0
	s_add_i32 s63, 0, 0x18000
	v_add_u32_e32 v175, s63, v153
	s_add_i32 s70, 0, 0x1c000
	ds_read_b128 v[146:149], v175
	ds_read_b128 v[176:179], v175 offset:1024
	ds_read_b128 v[180:183], v175 offset:2048
	ds_read_b128 v[184:187], v175 offset:3072
	v_add_u32_e32 v175, s70, v153
	ds_read_b128 v[188:191], v175
	ds_read_b128 v[200:203], v175 offset:1024
	ds_read_b128 v[204:207], v175 offset:2048
	ds_read_b128 v[208:211], v175 offset:3072
	s_add_u32 s68, s68, 0x100000
	s_addc_u32 s69, s69, 0
	s_mov_b32 m0, s16
	v_lshl_add_u64 v[194:195], s[68:69], 0, v[130:131]
	ds_read_b128 v[212:215], v173 offset:32768
	ds_read_b128 v[216:219], v173 offset:33792
	ds_read_b128 v[220:223], v173 offset:34816
	ds_read_b128 v[224:227], v173 offset:35840
	ds_read_b128 v[228:231], v173 offset:36864
	ds_read_b128 v[240:243], v173 offset:37888
	ds_read_b128 v[244:247], v173 offset:38912
	ds_read_b128 v[248:251], v173 offset:39936
	global_load_lds_dwordx4 v[194:195], off
	v_lshl_add_u64 v[194:195], s[68:69], 0, v[134:135]
	s_mov_b32 m0, s17
	s_nop 0
	global_load_lds_dwordx4 v[194:195], off
	s_waitcnt vmcnt(8)
	s_waitcnt lgkmcnt(0)
	s_setprio 1
	s_barrier
	v_mfma_f32_16x16x32_bf16 v[126:129], v[146:149], v[212:215], v[126:129]
	v_mfma_f32_16x16x32_bf16 v[126:129], v[176:179], v[216:219], v[126:129]
	v_mfma_f32_16x16x32_bf16 v[122:125], v[180:183], v[212:215], v[122:125]
	v_mfma_f32_16x16x32_bf16 v[122:125], v[184:187], v[216:219], v[122:125]
	v_mfma_f32_16x16x32_bf16 v[110:113], v[146:149], v[220:223], v[110:113]
	v_mfma_f32_16x16x32_bf16 v[110:113], v[176:179], v[224:227], v[110:113]
	v_mfma_f32_16x16x32_bf16 v[106:109], v[180:183], v[220:223], v[106:109]
	v_mfma_f32_16x16x32_bf16 v[106:109], v[184:187], v[224:227], v[106:109]
	v_mfma_f32_16x16x32_bf16 v[94:97], v[146:149], v[228:231], v[94:97]
	v_mfma_f32_16x16x32_bf16 v[94:97], v[176:179], v[240:243], v[94:97]
	v_mfma_f32_16x16x32_bf16 v[90:93], v[180:183], v[228:231], v[90:93]
	v_mfma_f32_16x16x32_bf16 v[90:93], v[184:187], v[240:243], v[90:93]
	v_mfma_f32_16x16x32_bf16 v[78:81], v[146:149], v[244:247], v[78:81]
	v_mfma_f32_16x16x32_bf16 v[78:81], v[176:179], v[248:251], v[78:81]
	v_mfma_f32_16x16x32_bf16 v[74:77], v[180:183], v[244:247], v[74:77]
	v_mfma_f32_16x16x32_bf16 v[74:77], v[184:187], v[248:251], v[74:77]
	s_setprio 0
	s_setprio 1
	v_mfma_f32_16x16x32_bf16 v[118:121], v[188:191], v[212:215], v[118:121]
	v_mfma_f32_16x16x32_bf16 v[118:121], v[200:203], v[216:219], v[118:121]
	v_mfma_f32_16x16x32_bf16 v[114:117], v[204:207], v[212:215], v[114:117]
	v_mfma_f32_16x16x32_bf16 v[114:117], v[208:211], v[216:219], v[114:117]
	v_mfma_f32_16x16x32_bf16 v[102:105], v[188:191], v[220:223], v[102:105]
	v_mfma_f32_16x16x32_bf16 v[102:105], v[200:203], v[224:227], v[102:105]
	v_mfma_f32_16x16x32_bf16 v[98:101], v[204:207], v[220:223], v[98:101]
	v_mfma_f32_16x16x32_bf16 v[98:101], v[208:211], v[224:227], v[98:101]
	v_mfma_f32_16x16x32_bf16 v[86:89], v[188:191], v[228:231], v[86:89]
	v_mfma_f32_16x16x32_bf16 v[86:89], v[200:203], v[240:243], v[86:89]
	v_mfma_f32_16x16x32_bf16 v[82:85], v[204:207], v[228:231], v[82:85]
	v_mfma_f32_16x16x32_bf16 v[82:85], v[208:211], v[240:243], v[82:85]
	v_mfma_f32_16x16x32_bf16 v[70:73], v[188:191], v[244:247], v[70:73]
	v_mfma_f32_16x16x32_bf16 v[70:73], v[200:203], v[248:251], v[70:73]
	v_mfma_f32_16x16x32_bf16 v[66:69], v[204:207], v[244:247], v[66:69]
	v_mfma_f32_16x16x32_bf16 v[66:69], v[208:211], v[248:251], v[66:69]
	s_barrier
; #define PG8_STAGE(bufoff, gbase, voff) do { _Pragma("unroll") for (int _i = 0; _i < 2; ++_i) \
;         __builtin_amdgcn_global_load_lds((const unsigned*)((const char*)(gbase) + (voff)[_i]), (PG8_LAS unsigned*)(lds + (bufoff) + ldsw + _i * 8192), 16, 0, 0); } while (0)
; #define PG8_LDA(dst, b, h) do { _Pragma("unroll") for (int m = 0; m < 4; ++m) _Pragma("unroll") for (int k = 0; k < 2; ++k) dst[m][k] = *(const PG8_LAS bf16x8*)(lds + PG8_SA(b, h) + aoff + m * 2048 + k * 1024); } while (0)
; #define PG8_MMA(ai, bj, At, Bt) do { __builtin_amdgcn_s_setprio(1); _Pragma("unroll") for (int m = 0; m < 4; ++m) _Pragma("unroll") for (int n = 0; n < 2; ++n) _Pragma("unroll") for (int k = 0; k < 2; ++k) \
;         acc[ai][bj][m][n] = __builtin_amdgcn_mfma_f32_16x16x32_bf16(Bt[n][k], At[m][k], acc[ai][bj][m][n], 0, 0, 0); __builtin_amdgcn_s_setprio(0); } while (0)
; #define PG8_WAIT_V(n) asm volatile("s_waitcnt vmcnt(" #n ")" ::: "memory")
; #define PG8_WAIT_L(n) asm volatile("s_waitcnt lgkmcnt(" #n ")" ::: "memory")
; #define PG8_BAR __builtin_amdgcn_s_barrier()
; #define PG8_SCHED __builtin_amdgcn_sched_barrier(0)
; template <class Epi, class Sched, bool ALIGN_EPI = false, bool SP2 = false>
; __device__ __forceinline__ void gemm_phase(PG8_LAS unsigned char* lds, const Gemm g, const Sched& S, const Epi& E) {
;     ...
;         for (int t = 0; t < nt; t += 2) {
;             const bool last = (t == nt - 2);
;             const char* a1 = cA + (size_t)(t + 1) * kstep;
;             const char* a2 = last ? nA : cA + (size_t)(t + 2) * kstep; const char* b2 = last ? nB : cB + (size_t)(t + 2) * kstep;
;             const char* a3 = a2 + kstep; const char* b3 = b2 + kstep;
;     ...
;             PG8_LDA(At, 1, 1); PG8_STAGE(PG8_SB(1, 0), b3, voffB); PG8_STAGE(PG8_SB(1, 1), b3 + hstep, voffB); PG8_STAGE(PG8_SA(1, 0), a3, voffA);
;             PG8_WAIT_V(8); PG8_WAIT_L(0); PG8_BAR; PG8_MMA(1, 0, At, B0); PG8_MMA(1, 1, At, B1); PG8_BAR; PG8_SCHED;
	s_setprio 0
	s_add_i32 s63, s63, s2
	v_lshl_add_u64 v[150:151], v[150:151], 0, s[44:45]
	s_mov_b32 m0, s63
	ds_read_b128 v[212:215], v173 offset:49152
	ds_read_b128 v[216:219], v173 offset:50176
	ds_read_b128 v[220:223], v173 offset:51200
	ds_read_b128 v[224:227], v173 offset:52224
	ds_read_b128 v[228:231], v173 offset:53248
	ds_read_b128 v[240:243], v173 offset:54272
	ds_read_b128 v[244:247], v173 offset:55296
	ds_read_b128 v[248:251], v173 offset:56320
	global_load_lds_dwordx4 v[150:151], off
	s_add_i32 m0, s63, 0x2000
	s_add_u32 s66, s66, 0x100080
	v_lshl_add_u64 v[150:151], v[192:193], 0, s[44:45]
	s_addc_u32 s67, s67, 0
	s_add_i32 s63, s70, s2
	global_load_lds_dwordx4 v[150:151], off
	v_lshl_add_u64 v[150:151], s[66:67], 0, v[132:133]
	s_mov_b32 m0, s63
	s_nop 0
	global_load_lds_dwordx4 v[150:151], off
	v_lshl_add_u64 v[150:151], s[66:67], 0, v[136:137]
	s_add_i32 m0, s63, 0x2000
	s_nop 0
	global_load_lds_dwordx4 v[150:151], off
	v_lshl_add_u64 v[150:151], v[232:233], 0, s[44:45]
	s_mov_b32 m0, s26
	s_nop 0
	global_load_lds_dwordx4 v[150:151], off
	v_lshl_add_u64 v[150:151], v[252:253], 0, s[44:45]
	s_mov_b32 m0, s27
	s_nop 0
	global_load_lds_dwordx4 v[150:151], off
	s_waitcnt vmcnt(8)
	s_waitcnt lgkmcnt(0)
	s_setprio 1
	s_barrier
	v_mfma_f32_16x16x32_bf16 v[62:65], v[146:149], v[212:215], v[62:65]
	v_mfma_f32_16x16x32_bf16 v[62:65], v[176:179], v[216:219], v[62:65]
	v_mfma_f32_16x16x32_bf16 v[58:61], v[180:183], v[212:215], v[58:61]
	v_mfma_f32_16x16x32_bf16 v[58:61], v[184:187], v[216:219], v[58:61]
	v_mfma_f32_16x16x32_bf16 v[46:49], v[146:149], v[220:223], v[46:49]
	v_mfma_f32_16x16x32_bf16 v[46:49], v[176:179], v[224:227], v[46:49]
	v_mfma_f32_16x16x32_bf16 v[42:45], v[180:183], v[220:223], v[42:45]
	v_mfma_f32_16x16x32_bf16 v[42:45], v[184:187], v[224:227], v[42:45]
	v_mfma_f32_16x16x32_bf16 v[30:33], v[146:149], v[228:231], v[30:33]
	v_mfma_f32_16x16x32_bf16 v[30:33], v[176:179], v[240:243], v[30:33]
	v_mfma_f32_16x16x32_bf16 v[26:29], v[180:183], v[228:231], v[26:29]
	v_mfma_f32_16x16x32_bf16 v[26:29], v[184:187], v[240:243], v[26:29]
	v_mfma_f32_16x16x32_bf16 v[14:17], v[146:149], v[244:247], v[14:17]
	v_mfma_f32_16x16x32_bf16 v[14:17], v[176:179], v[248:251], v[14:17]
	v_mfma_f32_16x16x32_bf16 v[10:13], v[180:183], v[244:247], v[10:13]
	v_mfma_f32_16x16x32_bf16 v[10:13], v[184:187], v[248:251], v[10:13]
	s_setprio 0
	s_setprio 1
	v_mfma_f32_16x16x32_bf16 v[54:57], v[188:191], v[212:215], v[54:57]
	v_mfma_f32_16x16x32_bf16 v[54:57], v[200:203], v[216:219], v[54:57]
	v_mfma_f32_16x16x32_bf16 v[50:53], v[204:207], v[212:215], v[50:53]
	v_mfma_f32_16x16x32_bf16 v[50:53], v[208:211], v[216:219], v[50:53]
	v_mfma_f32_16x16x32_bf16 v[38:41], v[188:191], v[220:223], v[38:41]
	v_mfma_f32_16x16x32_bf16 v[38:41], v[200:203], v[224:227], v[38:41]
	v_mfma_f32_16x16x32_bf16 v[34:37], v[204:207], v[220:223], v[34:37]
	v_mfma_f32_16x16x32_bf16 v[34:37], v[208:211], v[224:227], v[34:37]
	v_mfma_f32_16x16x32_bf16 v[22:25], v[188:191], v[228:231], v[22:25]
	v_mfma_f32_16x16x32_bf16 v[22:25], v[200:203], v[240:243], v[22:25]
	v_mfma_f32_16x16x32_bf16 v[18:21], v[204:207], v[228:231], v[18:21]
	v_mfma_f32_16x16x32_bf16 v[18:21], v[208:211], v[240:243], v[18:21]
	v_mfma_f32_16x16x32_bf16 v[6:9], v[188:191], v[244:247], v[6:9]
	v_mfma_f32_16x16x32_bf16 v[6:9], v[200:203], v[248:251], v[6:9]
	v_mfma_f32_16x16x32_bf16 v[2:5], v[204:207], v[244:247], v[2:5]
	v_mfma_f32_16x16x32_bf16 v[2:5], v[208:211], v[248:251], v[2:5]
	s_barrier
	s_setprio 0
	s_add_i32 s61, s61, 2
	s_add_u32 s64, s64, 0x100
	s_addc_u32 s65, s65, 0
	s_add_u32 s53, s53, 0x100
	s_addc_u32 s55, s55, 0
	s_cmp_gt_u32 s61, 61
	s_cbranch_scc0 .LBB0_1203
	s_and_b64 vcc, exec, s[46:47]
	s_cbranch_vccz .LBB0_1206
	s_barrier

; #define PG8_STAGE(bufoff, gbase, voff) do { _Pragma("unroll") for (int _i = 0; _i < 2; ++_i) \
;         __builtin_amdgcn_global_load_lds((const unsigned*)((const char*)(gbase) + (voff)[_i]), (PG8_LAS unsigned*)(lds + (bufoff) + ldsw + _i * 8192), 16, 0, 0); } while (0)
; #define PG8_LDA(dst, b, h) do { _Pragma("unroll") for (int m = 0; m < 4; ++m) _Pragma("unroll") for (int k = 0; k < 2; ++k) dst[m][k] = *(const PG8_LAS bf16x8*)(lds + PG8_SA(b, h) + aoff + m * 2048 + k * 1024); } while (0)
; #define PG8_LDB(dst, b, h) do { _Pragma("unroll") for (int n = 0; n < 2; ++n) _Pragma("unroll") for (int k = 0; k < 2; ++k) dst[n][k] = *(const PG8_LAS bf16x8*)(lds + PG8_SB(b, h) + boff + n * 2048 + k * 1024); } while (0)
; #define PG8_MMA(ai, bj, At, Bt) do { __builtin_amdgcn_s_setprio(1); _Pragma("unroll") for (int m = 0; m < 4; ++m) _Pragma("unroll") for (int n = 0; n < 2; ++n) _Pragma("unroll") for (int k = 0; k < 2; ++k) \
;         acc[ai][bj][m][n] = __builtin_amdgcn_mfma_f32_16x16x32_bf16(Bt[n][k], At[m][k], acc[ai][bj][m][n], 0, 0, 0); __builtin_amdgcn_s_setprio(0); } while (0)
; #define PG8_WAIT_V(n) asm volatile("s_waitcnt vmcnt(" #n ")" ::: "memory")
; #define PG8_WAIT_L(n) asm volatile("s_waitcnt lgkmcnt(" #n ")" ::: "memory")
; #define PG8_BAR __builtin_amdgcn_s_barrier()
; #define PG8_SCHED __builtin_amdgcn_sched_barrier(0)
; template <class Epi, class Sched, bool ALIGN_EPI = false, bool SP2 = false>
; __device__ __forceinline__ void gemm_phase(PG8_LAS unsigned char* lds, const Gemm g, const Sched& S, const Epi& E) {
;     ...
;             const bool last = (t == nt - 2);
;             const char* a1 = cA + (size_t)(t + 1) * kstep;
;             const char* a2 = last ? nA : cA + (size_t)(t + 2) * kstep; const char* b2 = last ? nB : cB + (size_t)(t + 2) * kstep;
;             const char* a3 = a2 + kstep; const char* b3 = b2 + kstep;
;             if (last && has_next) S.a_ready(nxt);
;             if constexpr (SP2) {
;             PG8_LDB(B0, 0, 0); PG8_LDB(B1, 0, 1); PG8_SCHED; PG8_LDA(At, 0, 0); PG8_STAGE(PG8_SA(1, 1), a1 + hstep, voffA);
;             PG8_WAIT_V(8); PG8_WAIT_L(0); PG8_BAR; PG8_MMA(0, 0, At, B0); PG8_MMA(0, 1, At, B1); PG8_BAR; PG8_SCHED;
;             PG8_LDA(At, 0, 1); PG8_STAGE(PG8_SB(0, 0), b2, voffB); PG8_STAGE(PG8_SB(0, 1), b2 + hstep, voffB); PG8_STAGE(PG8_SA(0, 0), a2, voffA);
.LBB0_1230:
	ds_read_b128 v[146:149], v140
	ds_read_b128 v[150:153], v140 offset:1024
	ds_read_b128 v[154:157], v140 offset:2048
	ds_read_b128 v[158:161], v140 offset:3072
	ds_read_b128 v[168:171], v141
	ds_read_b128 v[172:175], v141 offset:1024
	ds_read_b128 v[176:179], v141 offset:2048
	ds_read_b128 v[180:183], v141 offset:3072
	s_add_u32 s50, s46, 0x100
	s_addc_u32 s51, s47, 0
	s_cmp_lg_u32 s30, 12
	s_cselect_b32 s52, s50, 0
	s_cselect_b32 s53, s51, 0
	s_add_u32 s54, s10, s52
	s_addc_u32 s55, s11, s53
	s_add_u32 s52, s8, s52
	s_addc_u32 s53, s9, s53
	s_mov_b32 m0, s33
	v_lshl_add_u64 v[162:163], v[134:135], 0, s[46:47]
	ds_read_b128 v[184:187], v142
	ds_read_b128 v[188:191], v142 offset:1024
	ds_read_b128 v[200:203], v142 offset:2048
	ds_read_b128 v[204:207], v142 offset:3072
	ds_read_b128 v[208:211], v142 offset:4096
	ds_read_b128 v[212:215], v142 offset:5120
	ds_read_b128 v[216:219], v142 offset:6144
	ds_read_b128 v[220:223], v142 offset:7168
	global_load_lds_dwordx4 v[162:163], off
	v_lshl_add_u64 v[162:163], v[136:137], 0, s[46:47]
	s_mov_b32 m0, s34
	s_nop 0
	global_load_lds_dwordx4 v[162:163], off
	s_waitcnt vmcnt(8)
	s_waitcnt lgkmcnt(0)
	s_setprio 1
	s_barrier
	v_mfma_f32_16x16x32_bf16 v[126:129], v[146:149], v[184:187], v[126:129]
	v_mfma_f32_16x16x32_bf16 v[126:129], v[150:153], v[188:191], v[126:129]
	v_mfma_f32_16x16x32_bf16 v[122:125], v[154:157], v[184:187], v[122:125]
	v_mfma_f32_16x16x32_bf16 v[122:125], v[158:161], v[188:191], v[122:125]
	v_mfma_f32_16x16x32_bf16 v[118:121], v[146:149], v[200:203], v[118:121]
	v_mfma_f32_16x16x32_bf16 v[118:121], v[150:153], v[204:207], v[118:121]
	v_mfma_f32_16x16x32_bf16 v[114:117], v[154:157], v[200:203], v[114:117]
	v_mfma_f32_16x16x32_bf16 v[114:117], v[158:161], v[204:207], v[114:117]
	v_mfma_f32_16x16x32_bf16 v[106:109], v[146:149], v[208:211], v[106:109]
	v_mfma_f32_16x16x32_bf16 v[106:109], v[150:153], v[212:215], v[106:109]
	v_mfma_f32_16x16x32_bf16 v[98:101], v[154:157], v[208:211], v[98:101]
	v_mfma_f32_16x16x32_bf16 v[98:101], v[158:161], v[212:215], v[98:101]
	v_mfma_f32_16x16x32_bf16 v[90:93], v[146:149], v[216:219], v[90:93]
	v_mfma_f32_16x16x32_bf16 v[90:93], v[150:153], v[220:223], v[90:93]
	v_mfma_f32_16x16x32_bf16 v[82:85], v[154:157], v[216:219], v[82:85]
	v_mfma_f32_16x16x32_bf16 v[82:85], v[158:161], v[220:223], v[82:85]
	s_setprio 0
	s_setprio 1
	v_mfma_f32_16x16x32_bf16 v[110:113], v[168:171], v[184:187], v[110:113]
	v_mfma_f32_16x16x32_bf16 v[110:113], v[172:175], v[188:191], v[110:113]
	v_mfma_f32_16x16x32_bf16 v[102:105], v[176:179], v[184:187], v[102:105]
	v_mfma_f32_16x16x32_bf16 v[102:105], v[180:183], v[188:191], v[102:105]
	v_mfma_f32_16x16x32_bf16 v[94:97], v[168:171], v[200:203], v[94:97]
	v_mfma_f32_16x16x32_bf16 v[94:97], v[172:175], v[204:207], v[94:97]
	v_mfma_f32_16x16x32_bf16 v[86:89], v[176:179], v[200:203], v[86:89]
	v_mfma_f32_16x16x32_bf16 v[86:89], v[180:183], v[204:207], v[86:89]
	v_mfma_f32_16x16x32_bf16 v[78:81], v[168:171], v[208:211], v[78:81]
	v_mfma_f32_16x16x32_bf16 v[78:81], v[172:175], v[212:215], v[78:81]
	v_mfma_f32_16x16x32_bf16 v[74:77], v[176:179], v[208:211], v[74:77]
	v_mfma_f32_16x16x32_bf16 v[74:77], v[180:183], v[212:215], v[74:77]
	v_mfma_f32_16x16x32_bf16 v[70:73], v[168:171], v[216:219], v[70:73]
	v_mfma_f32_16x16x32_bf16 v[70:73], v[172:175], v[220:223], v[70:73]
	v_mfma_f32_16x16x32_bf16 v[66:69], v[176:179], v[216:219], v[66:69]
	v_mfma_f32_16x16x32_bf16 v[66:69], v[180:183], v[220:223], v[66:69]
	s_barrier
	s_setprio 0
	s_mov_b32 m0, s35
	v_lshl_add_u64 v[162:163], s[52:53], 0, v[130:131]
	s_add_u32 s46, s52, 0x100000
	ds_read_b128 v[184:187], v142 offset:16384
	ds_read_b128 v[188:191], v142 offset:17408
	ds_read_b128 v[200:203], v142 offset:18432
	ds_read_b128 v[204:207], v142 offset:19456
	ds_read_b128 v[208:211], v142 offset:20480
	ds_read_b128 v[212:215], v142 offset:21504
	ds_read_b128 v[216:219], v142 offset:22528
	ds_read_b128 v[220:223], v142 offset:23552
	global_load_lds_dwordx4 v[162:163], off
	v_lshl_add_u64 v[192:193], s[52:53], 0, v[132:133]
	s_mov_b32 m0, s39
	s_addc_u32 s47, s53, 0
	global_load_lds_dwordx4 v[192:193], off
	v_lshl_add_u64 v[194:195], s[46:47], 0, v[130:131]
	s_mov_b32 m0, s40
	v_lshl_add_u64 v[224:225], s[54:55], 0, v[132:133]
	global_load_lds_dwordx4 v[194:195], off
	v_lshl_add_u64 v[194:195], s[46:47], 0, v[132:133]
	s_mov_b32 m0, s41
	s_nop 0
	global_load_lds_dwordx4 v[194:195], off
	v_lshl_add_u64 v[194:195], s[54:55], 0, v[130:131]
	s_mov_b32 m0, s7
	s_nop 0
	global_load_lds_dwordx4 v[194:195], off
	s_mov_b32 m0, s16
	s_nop 0
	global_load_lds_dwordx4 v[224:225], off
	s_waitcnt vmcnt(8)
	s_waitcnt lgkmcnt(0)
	s_setprio 1
	s_barrier
; #define PG8_STAGE(bufoff, gbase, voff) do { _Pragma("unroll") for (int _i = 0; _i < 2; ++_i) \
;         __builtin_amdgcn_global_load_lds((const unsigned*)((const char*)(gbase) + (voff)[_i]), (PG8_LAS unsigned*)(lds + (bufoff) + ldsw + _i * 8192), 16, 0, 0); } while (0)
; #define PG8_LDA(dst, b, h) do { _Pragma("unroll") for (int m = 0; m < 4; ++m) _Pragma("unroll") for (int k = 0; k < 2; ++k) dst[m][k] = *(const PG8_LAS bf16x8*)(lds + PG8_SA(b, h) + aoff + m * 2048 + k * 1024); } while (0)
; #define PG8_LDB(dst, b, h) do { _Pragma("unroll") for (int n = 0; n < 2; ++n) _Pragma("unroll") for (int k = 0; k < 2; ++k) dst[n][k] = *(const PG8_LAS bf16x8*)(lds + PG8_SB(b, h) + boff + n * 2048 + k * 1024); } while (0)
; #define PG8_MMA(ai, bj, At, Bt) do { __builtin_amdgcn_s_setprio(1); _Pragma("unroll") for (int m = 0; m < 4; ++m) _Pragma("unroll") for (int n = 0; n < 2; ++n) _Pragma("unroll") for (int k = 0; k < 2; ++k) \
;         acc[ai][bj][m][n] = __builtin_amdgcn_mfma_f32_16x16x32_bf16(Bt[n][k], At[m][k], acc[ai][bj][m][n], 0, 0, 0); __builtin_amdgcn_s_setprio(0); } while (0)
; #define PG8_WAIT_V(n) asm volatile("s_waitcnt vmcnt(" #n ")" ::: "memory")
; #define PG8_WAIT_L(n) asm volatile("s_waitcnt lgkmcnt(" #n ")" ::: "memory")
; #define PG8_BAR __builtin_amdgcn_s_barrier()
; #define PG8_SCHED __builtin_amdgcn_sched_barrier(0)
; template <class Epi, class Sched, bool ALIGN_EPI = false, bool SP2 = false>
; __device__ __forceinline__ void gemm_phase(PG8_LAS unsigned char* lds, const Gemm g, const Sched& S, const Epi& E) {
;     ...
;             PG8_WAIT_V(8); PG8_WAIT_L(0); PG8_BAR; PG8_MMA(1, 0, At, B0); PG8_MMA(1, 1, At, B1); PG8_BAR; PG8_SCHED;
;             PG8_LDB(B0, 1, 0); PG8_LDB(B1, 1, 1); PG8_SCHED; PG8_LDA(At, 1, 0); PG8_STAGE(PG8_SA(0, 1), a2 + hstep, voffA);
;             PG8_WAIT_V(8); PG8_WAIT_L(0); PG8_BAR; PG8_MMA(0, 0, At, B0); PG8_MMA(0, 1, At, B1); PG8_BAR; PG8_SCHED;
	v_mfma_f32_16x16x32_bf16 v[62:65], v[146:149], v[184:187], v[62:65]
	v_mfma_f32_16x16x32_bf16 v[62:65], v[150:153], v[188:191], v[62:65]
	v_mfma_f32_16x16x32_bf16 v[58:61], v[154:157], v[184:187], v[58:61]
	v_mfma_f32_16x16x32_bf16 v[58:61], v[158:161], v[188:191], v[58:61]
	v_mfma_f32_16x16x32_bf16 v[54:57], v[146:149], v[200:203], v[54:57]
	v_mfma_f32_16x16x32_bf16 v[54:57], v[150:153], v[204:207], v[54:57]
	v_mfma_f32_16x16x32_bf16 v[50:53], v[154:157], v[200:203], v[50:53]
	v_mfma_f32_16x16x32_bf16 v[50:53], v[158:161], v[204:207], v[50:53]
	v_mfma_f32_16x16x32_bf16 v[42:45], v[146:149], v[208:211], v[42:45]
	v_mfma_f32_16x16x32_bf16 v[42:45], v[150:153], v[212:215], v[42:45]
	v_mfma_f32_16x16x32_bf16 v[34:37], v[154:157], v[208:211], v[34:37]
	v_mfma_f32_16x16x32_bf16 v[34:37], v[158:161], v[212:215], v[34:37]
	v_mfma_f32_16x16x32_bf16 v[26:29], v[146:149], v[216:219], v[26:29]
	v_mfma_f32_16x16x32_bf16 v[26:29], v[150:153], v[220:223], v[26:29]
	v_mfma_f32_16x16x32_bf16 v[18:21], v[154:157], v[216:219], v[18:21]
	v_mfma_f32_16x16x32_bf16 v[18:21], v[158:161], v[220:223], v[18:21]
	s_setprio 0
	s_setprio 1
	v_mfma_f32_16x16x32_bf16 v[46:49], v[168:171], v[184:187], v[46:49]
	v_mfma_f32_16x16x32_bf16 v[46:49], v[172:175], v[188:191], v[46:49]
	v_mfma_f32_16x16x32_bf16 v[38:41], v[176:179], v[184:187], v[38:41]
	v_mfma_f32_16x16x32_bf16 v[38:41], v[180:183], v[188:191], v[38:41]
	v_mfma_f32_16x16x32_bf16 v[30:33], v[168:171], v[200:203], v[30:33]
	v_mfma_f32_16x16x32_bf16 v[30:33], v[172:175], v[204:207], v[30:33]
	v_mfma_f32_16x16x32_bf16 v[22:25], v[176:179], v[200:203], v[22:25]
	v_mfma_f32_16x16x32_bf16 v[22:25], v[180:183], v[204:207], v[22:25]
	v_mfma_f32_16x16x32_bf16 v[14:17], v[168:171], v[208:211], v[14:17]
	v_mfma_f32_16x16x32_bf16 v[14:17], v[172:175], v[212:215], v[14:17]
	v_mfma_f32_16x16x32_bf16 v[10:13], v[176:179], v[208:211], v[10:13]
	v_mfma_f32_16x16x32_bf16 v[10:13], v[180:183], v[212:215], v[10:13]
	v_mfma_f32_16x16x32_bf16 v[6:9], v[168:171], v[216:219], v[6:9]
	v_mfma_f32_16x16x32_bf16 v[6:9], v[172:175], v[220:223], v[6:9]
	v_mfma_f32_16x16x32_bf16 v[2:5], v[176:179], v[216:219], v[2:5]
	v_mfma_f32_16x16x32_bf16 v[2:5], v[180:183], v[220:223], v[2:5]
	s_barrier
	s_setprio 0
	ds_read_b128 v[146:149], v143
	ds_read_b128 v[150:153], v143 offset:1024
	ds_read_b128 v[154:157], v143 offset:2048
	ds_read_b128 v[158:161], v143 offset:3072
	ds_read_b128 v[168:171], v144
	ds_read_b128 v[172:175], v144 offset:1024
	ds_read_b128 v[176:179], v144 offset:2048
	ds_read_b128 v[180:183], v144 offset:3072
	s_add_u32 s46, s54, 0x100000
	s_addc_u32 s47, s55, 0
	s_mov_b32 m0, s17
	v_lshl_add_u64 v[226:227], s[46:47], 0, v[130:131]
	ds_read_b128 v[184:187], v142 offset:32768
	ds_read_b128 v[188:191], v142 offset:33792
	ds_read_b128 v[200:203], v142 offset:34816
	ds_read_b128 v[204:207], v142 offset:35840
	ds_read_b128 v[208:211], v142 offset:36864
	ds_read_b128 v[212:215], v142 offset:37888
	ds_read_b128 v[216:219], v142 offset:38912
	ds_read_b128 v[220:223], v142 offset:39936
	global_load_lds_dwordx4 v[226:227], off
	v_lshl_add_u64 v[226:227], s[46:47], 0, v[132:133]
	s_mov_b32 m0, s26
	s_nop 0
	global_load_lds_dwordx4 v[226:227], off
	s_waitcnt vmcnt(8)
	s_waitcnt lgkmcnt(0)
	s_setprio 1
	s_barrier
	v_mfma_f32_16x16x32_bf16 v[126:129], v[146:149], v[184:187], v[126:129]
	v_mfma_f32_16x16x32_bf16 v[126:129], v[150:153], v[188:191], v[126:129]
	v_mfma_f32_16x16x32_bf16 v[122:125], v[154:157], v[184:187], v[122:125]
	v_mfma_f32_16x16x32_bf16 v[122:125], v[158:161], v[188:191], v[122:125]
	v_mfma_f32_16x16x32_bf16 v[118:121], v[146:149], v[200:203], v[118:121]
	v_mfma_f32_16x16x32_bf16 v[118:121], v[150:153], v[204:207], v[118:121]
	v_mfma_f32_16x16x32_bf16 v[114:117], v[154:157], v[200:203], v[114:117]
	v_mfma_f32_16x16x32_bf16 v[114:117], v[158:161], v[204:207], v[114:117]
	v_mfma_f32_16x16x32_bf16 v[106:109], v[146:149], v[208:211], v[106:109]
	v_mfma_f32_16x16x32_bf16 v[106:109], v[150:153], v[212:215], v[106:109]
	v_mfma_f32_16x16x32_bf16 v[98:101], v[154:157], v[208:211], v[98:101]
	v_mfma_f32_16x16x32_bf16 v[98:101], v[158:161], v[212:215], v[98:101]
	v_mfma_f32_16x16x32_bf16 v[90:93], v[146:149], v[216:219], v[90:93]
	v_mfma_f32_16x16x32_bf16 v[90:93], v[150:153], v[220:223], v[90:93]
	v_mfma_f32_16x16x32_bf16 v[82:85], v[154:157], v[216:219], v[82:85]
	v_mfma_f32_16x16x32_bf16 v[82:85], v[158:161], v[220:223], v[82:85]
	s_setprio 0
	s_setprio 1
	v_mfma_f32_16x16x32_bf16 v[110:113], v[168:171], v[184:187], v[110:113]
	v_mfma_f32_16x16x32_bf16 v[110:113], v[172:175], v[188:191], v[110:113]
	v_mfma_f32_16x16x32_bf16 v[102:105], v[176:179], v[184:187], v[102:105]
	v_mfma_f32_16x16x32_bf16 v[102:105], v[180:183], v[188:191], v[102:105]
	v_mfma_f32_16x16x32_bf16 v[94:97], v[168:171], v[200:203], v[94:97]
	v_mfma_f32_16x16x32_bf16 v[94:97], v[172:175], v[204:207], v[94:97]
	v_mfma_f32_16x16x32_bf16 v[86:89], v[176:179], v[200:203], v[86:89]
	v_mfma_f32_16x16x32_bf16 v[86:89], v[180:183], v[204:207], v[86:89]
	v_mfma_f32_16x16x32_bf16 v[78:81], v[168:171], v[208:211], v[78:81]
	v_mfma_f32_16x16x32_bf16 v[78:81], v[172:175], v[212:215], v[78:81]
	v_mfma_f32_16x16x32_bf16 v[74:77], v[176:179], v[208:211], v[74:77]
	v_mfma_f32_16x16x32_bf16 v[74:77], v[180:183], v[212:215], v[74:77]
	v_mfma_f32_16x16x32_bf16 v[70:73], v[168:171], v[216:219], v[70:73]
	v_mfma_f32_16x16x32_bf16 v[70:73], v[172:175], v[220:223], v[70:73]
	v_mfma_f32_16x16x32_bf16 v[66:69], v[176:179], v[216:219], v[66:69]
	v_mfma_f32_16x16x32_bf16 v[66:69], v[180:183], v[220:223], v[66:69]
	s_barrier
; #define PG8_STAGE(bufoff, gbase, voff) do { _Pragma("unroll") for (int _i = 0; _i < 2; ++_i) \
;         __builtin_amdgcn_global_load_lds((const unsigned*)((const char*)(gbase) + (voff)[_i]), (PG8_LAS unsigned*)(lds + (bufoff) + ldsw + _i * 8192), 16, 0, 0); } while (0)
; #define PG8_LDA(dst, b, h) do { _Pragma("unroll") for (int m = 0; m < 4; ++m) _Pragma("unroll") for (int k = 0; k < 2; ++k) dst[m][k] = *(const PG8_LAS bf16x8*)(lds + PG8_SA(b, h) + aoff + m * 2048 + k * 1024); } while (0)
; #define PG8_MMA(ai, bj, At, Bt) do { __builtin_amdgcn_s_setprio(1); _Pragma("unroll") for (int m = 0; m < 4; ++m) _Pragma("unroll") for (int n = 0; n < 2; ++n) _Pragma("unroll") for (int k = 0; k < 2; ++k) \
;         acc[ai][bj][m][n] = __builtin_amdgcn_mfma_f32_16x16x32_bf16(Bt[n][k], At[m][k], acc[ai][bj][m][n], 0, 0, 0); __builtin_amdgcn_s_setprio(0); } while (0)
; #define PG8_WAIT_V(n) asm volatile("s_waitcnt vmcnt(" #n ")" ::: "memory")
; #define PG8_WAIT_L(n) asm volatile("s_waitcnt lgkmcnt(" #n ")" ::: "memory")
; #define PG8_BAR __builtin_amdgcn_s_barrier()
; #define PG8_SCHED __builtin_amdgcn_sched_barrier(0)
; template <class Epi, class Sched, bool ALIGN_EPI = false, bool SP2 = false>
; __device__ __forceinline__ void gemm_phase(PG8_LAS unsigned char* lds, const Gemm g, const Sched& S, const Epi& E) {
;     ...
;             PG8_LDA(At, 1, 1); PG8_STAGE(PG8_SB(1, 0), b3, voffB); PG8_STAGE(PG8_SB(1, 1), b3 + hstep, voffB); PG8_STAGE(PG8_SA(1, 0), a3, voffA);
;             PG8_WAIT_V(8); PG8_WAIT_L(0); PG8_BAR; PG8_MMA(1, 0, At, B0); PG8_MMA(1, 1, At, B1); PG8_BAR; PG8_SCHED;
	s_setprio 0
	s_mov_b32 m0, s44
	v_lshl_add_u64 v[162:163], v[162:163], 0, s[12:13]
	s_add_u32 s46, s52, 0x100080
	ds_read_b128 v[184:187], v142 offset:49152
	ds_read_b128 v[188:191], v142 offset:50176
	ds_read_b128 v[200:203], v142 offset:51200
	ds_read_b128 v[204:207], v142 offset:52224
	ds_read_b128 v[208:211], v142 offset:53248
	ds_read_b128 v[212:215], v142 offset:54272
	ds_read_b128 v[216:219], v142 offset:55296
	ds_read_b128 v[220:223], v142 offset:56320
	global_load_lds_dwordx4 v[162:163], off
	v_lshl_add_u64 v[162:163], v[192:193], 0, s[12:13]
	s_mov_b32 m0, s45
	s_addc_u32 s47, s53, 0
	global_load_lds_dwordx4 v[162:163], off
	v_lshl_add_u64 v[162:163], s[46:47], 0, v[130:131]
	s_mov_b32 m0, s56
	s_nop 0
	global_load_lds_dwordx4 v[162:163], off
	v_lshl_add_u64 v[162:163], s[46:47], 0, v[132:133]
	s_mov_b32 m0, s57
	s_nop 0
	global_load_lds_dwordx4 v[162:163], off
	v_lshl_add_u64 v[162:163], v[194:195], 0, s[12:13]
	s_mov_b32 m0, s28
	s_nop 0
	global_load_lds_dwordx4 v[162:163], off
	v_lshl_add_u64 v[162:163], v[224:225], 0, s[12:13]
	s_mov_b32 m0, s29
	s_nop 0
	global_load_lds_dwordx4 v[162:163], off
	s_waitcnt vmcnt(8)
	s_waitcnt lgkmcnt(0)
	s_setprio 1
	s_barrier
	v_mfma_f32_16x16x32_bf16 v[62:65], v[146:149], v[184:187], v[62:65]
	v_mfma_f32_16x16x32_bf16 v[62:65], v[150:153], v[188:191], v[62:65]
	v_mfma_f32_16x16x32_bf16 v[58:61], v[154:157], v[184:187], v[58:61]
	v_mfma_f32_16x16x32_bf16 v[58:61], v[158:161], v[188:191], v[58:61]
	v_mfma_f32_16x16x32_bf16 v[54:57], v[146:149], v[200:203], v[54:57]
	v_mfma_f32_16x16x32_bf16 v[54:57], v[150:153], v[204:207], v[54:57]
	v_mfma_f32_16x16x32_bf16 v[50:53], v[154:157], v[200:203], v[50:53]
	v_mfma_f32_16x16x32_bf16 v[50:53], v[158:161], v[204:207], v[50:53]
	v_mfma_f32_16x16x32_bf16 v[42:45], v[146:149], v[208:211], v[42:45]
	v_mfma_f32_16x16x32_bf16 v[42:45], v[150:153], v[212:215], v[42:45]
	v_mfma_f32_16x16x32_bf16 v[34:37], v[154:157], v[208:211], v[34:37]
	v_mfma_f32_16x16x32_bf16 v[34:37], v[158:161], v[212:215], v[34:37]
	v_mfma_f32_16x16x32_bf16 v[26:29], v[146:149], v[216:219], v[26:29]
	v_mfma_f32_16x16x32_bf16 v[26:29], v[150:153], v[220:223], v[26:29]
	v_mfma_f32_16x16x32_bf16 v[18:21], v[154:157], v[216:219], v[18:21]
	v_mfma_f32_16x16x32_bf16 v[18:21], v[158:161], v[220:223], v[18:21]
	s_setprio 0
	s_setprio 1
	v_mfma_f32_16x16x32_bf16 v[46:49], v[168:171], v[184:187], v[46:49]
	v_mfma_f32_16x16x32_bf16 v[46:49], v[172:175], v[188:191], v[46:49]
	v_mfma_f32_16x16x32_bf16 v[38:41], v[176:179], v[184:187], v[38:41]
	v_mfma_f32_16x16x32_bf16 v[38:41], v[180:183], v[188:191], v[38:41]
	v_mfma_f32_16x16x32_bf16 v[30:33], v[168:171], v[200:203], v[30:33]
	v_mfma_f32_16x16x32_bf16 v[30:33], v[172:175], v[204:207], v[30:33]
	v_mfma_f32_16x16x32_bf16 v[22:25], v[176:179], v[200:203], v[22:25]
	v_mfma_f32_16x16x32_bf16 v[22:25], v[180:183], v[204:207], v[22:25]
	v_mfma_f32_16x16x32_bf16 v[14:17], v[168:171], v[208:211], v[14:17]
	v_mfma_f32_16x16x32_bf16 v[14:17], v[172:175], v[212:215], v[14:17]
	v_mfma_f32_16x16x32_bf16 v[10:13], v[176:179], v[208:211], v[10:13]
	v_mfma_f32_16x16x32_bf16 v[10:13], v[180:183], v[212:215], v[10:13]
	v_mfma_f32_16x16x32_bf16 v[6:9], v[168:171], v[216:219], v[6:9]
	v_mfma_f32_16x16x32_bf16 v[6:9], v[172:175], v[220:223], v[6:9]
	v_mfma_f32_16x16x32_bf16 v[2:5], v[176:179], v[216:219], v[2:5]
	v_mfma_f32_16x16x32_bf16 v[2:5], v[180:183], v[220:223], v[2:5]
	s_barrier
	s_setprio 0
	s_add_i32 s30, s30, 2
	s_cmp_gt_u32 s30, 13
	s_mov_b64 s[46:47], s[50:51]
	s_cbranch_scc0 .LBB0_1230
	s_cmpk_lt_u32 s2, 0x100
	s_cbranch_scc0 .LBB0_1233
	s_barrier

; #define PG8_STAGE(bufoff, gbase, voff) do { _Pragma("unroll") for (int _i = 0; _i < 2; ++_i) \
;         __builtin_amdgcn_global_load_lds((const unsigned*)((const char*)(gbase) + (voff)[_i]), (PG8_LAS unsigned*)(lds + (bufoff) + ldsw + _i * 8192), 16, 0, 0); } while (0)
; #define PG8_LDA(dst, b, h) do { _Pragma("unroll") for (int m = 0; m < 4; ++m) _Pragma("unroll") for (int k = 0; k < 2; ++k) dst[m][k] = *(const PG8_LAS bf16x8*)(lds + PG8_SA(b, h) + aoff + m * 2048 + k * 1024); } while (0)
; #define PG8_LDB(dst, b, h) do { _Pragma("unroll") for (int n = 0; n < 2; ++n) _Pragma("unroll") for (int k = 0; k < 2; ++k) dst[n][k] = *(const PG8_LAS bf16x8*)(lds + PG8_SB(b, h) + boff + n * 2048 + k * 1024); } while (0)
; #define PG8_MMA(ai, bj, At, Bt) do { __builtin_amdgcn_s_setprio(1); _Pragma("unroll") for (int m = 0; m < 4; ++m) _Pragma("unroll") for (int n = 0; n < 2; ++n) _Pragma("unroll") for (int k = 0; k < 2; ++k) \
;         acc[ai][bj][m][n] = __builtin_amdgcn_mfma_f32_16x16x32_bf16(Bt[n][k], At[m][k], acc[ai][bj][m][n], 0, 0, 0); __builtin_amdgcn_s_setprio(0); } while (0)
; #define PG8_WAIT_V(n) asm volatile("s_waitcnt vmcnt(" #n ")" ::: "memory")
; #define PG8_WAIT_L(n) asm volatile("s_waitcnt lgkmcnt(" #n ")" ::: "memory")
; #define PG8_BAR __builtin_amdgcn_s_barrier()
; #define PG8_SCHED __builtin_amdgcn_sched_barrier(0)
; template <class Epi, class Sched, bool ALIGN_EPI = false, bool SP2 = false>
; __device__ __forceinline__ void gemm_phase(PG8_LAS unsigned char* lds, const Gemm g, const Sched& S, const Epi& E) {
;     ...
;             const bool last = (t == nt - 2);
;             const char* a1 = cA + (size_t)(t + 1) * kstep;
;             const char* a2 = last ? nA : cA + (size_t)(t + 2) * kstep; const char* b2 = last ? nB : cB + (size_t)(t + 2) * kstep;
;             const char* a3 = a2 + kstep; const char* b3 = b2 + kstep;
;             if (last && has_next) S.a_ready(nxt);
;             if constexpr (SP2) {
;             PG8_LDB(B0, 0, 0); PG8_LDB(B1, 0, 1); PG8_SCHED; PG8_LDA(At, 0, 0); PG8_STAGE(PG8_SA(1, 1), a1 + hstep, voffA);
;             PG8_WAIT_V(8); PG8_WAIT_L(0); PG8_BAR; PG8_MMA(0, 0, At, B0); PG8_MMA(0, 1, At, B1); PG8_BAR; PG8_SCHED;
;             PG8_LDA(At, 0, 1); PG8_STAGE(PG8_SB(0, 0), b2, voffB); PG8_STAGE(PG8_SB(0, 1), b2 + hstep, voffB); PG8_STAGE(PG8_SA(0, 0), a2, voffA);
.LBB0_1478:
	v_add_u32_e32 v144, s31, v201
	v_add_u32_e32 v160, s52, v201
	ds_read_b128 v[132:135], v144
	ds_read_b128 v[136:139], v144 offset:1024
	ds_read_b128 v[140:143], v144 offset:2048
	ds_read_b128 v[144:147], v144 offset:3072
	ds_read_b128 v[148:151], v160
	ds_read_b128 v[152:155], v160 offset:1024
	ds_read_b128 v[156:159], v160 offset:2048
	ds_read_b128 v[160:163], v160 offset:3072
	s_add_u32 s50, s82, 0xfff00080
	s_addc_u32 s56, s83, -1
	s_and_b64 s[34:35], s[84:85], exec
	s_cselect_b32 s87, s65, s56
	s_cselect_b32 s86, s69, s50
	s_cselect_b32 s85, s67, s88
	s_cselect_b32 s84, s77, s79
	v_lshl_add_u64 v[192:193], s[82:83], 0, v[220:221]
	s_add_i32 m0, s28, 0xc000
	ds_read_b128 v[164:167], v242
	ds_read_b128 v[168:171], v242 offset:1024
	ds_read_b128 v[172:175], v242 offset:2048
	ds_read_b128 v[176:179], v242 offset:3072
	ds_read_b128 v[180:183], v242 offset:4096
	ds_read_b128 v[184:187], v242 offset:5120
	ds_read_b128 v[188:191], v242 offset:6144
	ds_read_b128 v[226:229], v242 offset:7168
	global_load_lds_dwordx4 v[192:193], off
	v_lshl_add_u64 v[192:193], s[82:83], 0, v[222:223]
	s_add_i32 m0, s28, 0xe000
	s_nop 0
	global_load_lds_dwordx4 v[192:193], off
	s_waitcnt vmcnt(8)
	s_waitcnt lgkmcnt(0)
	s_setprio 1
	s_barrier
	v_mfma_f32_16x16x32_bf16 v[126:129], v[132:135], v[164:167], v[126:129]
	v_mfma_f32_16x16x32_bf16 v[126:129], v[136:139], v[168:171], v[126:129]
	v_mfma_f32_16x16x32_bf16 v[46:49], v[140:143], v[164:167], v[46:49]
	v_mfma_f32_16x16x32_bf16 v[46:49], v[144:147], v[168:171], v[46:49]
	v_mfma_f32_16x16x32_bf16 v[118:121], v[132:135], v[172:175], v[118:121]
	v_mfma_f32_16x16x32_bf16 v[118:121], v[136:139], v[176:179], v[118:121]
	v_mfma_f32_16x16x32_bf16 v[122:125], v[140:143], v[172:175], v[122:125]
	v_mfma_f32_16x16x32_bf16 v[122:125], v[144:147], v[176:179], v[122:125]
	v_mfma_f32_16x16x32_bf16 v[110:113], v[132:135], v[180:183], v[110:113]
	v_mfma_f32_16x16x32_bf16 v[110:113], v[136:139], v[184:187], v[110:113]
	v_mfma_f32_16x16x32_bf16 v[114:117], v[140:143], v[180:183], v[114:117]
	v_mfma_f32_16x16x32_bf16 v[114:117], v[144:147], v[184:187], v[114:117]
	v_mfma_f32_16x16x32_bf16 v[102:105], v[132:135], v[188:191], v[102:105]
	v_mfma_f32_16x16x32_bf16 v[102:105], v[136:139], v[226:229], v[102:105]
	v_mfma_f32_16x16x32_bf16 v[106:109], v[140:143], v[188:191], v[106:109]
	v_mfma_f32_16x16x32_bf16 v[106:109], v[144:147], v[226:229], v[106:109]
	s_setprio 0
	s_setprio 1
	v_mfma_f32_16x16x32_bf16 v[54:57], v[148:151], v[164:167], v[54:57]
	v_mfma_f32_16x16x32_bf16 v[54:57], v[152:155], v[168:171], v[54:57]
	v_mfma_f32_16x16x32_bf16 v[38:41], v[156:159], v[164:167], v[38:41]
	v_mfma_f32_16x16x32_bf16 v[38:41], v[160:163], v[168:171], v[38:41]
	v_mfma_f32_16x16x32_bf16 v[58:61], v[148:151], v[172:175], v[58:61]
	v_mfma_f32_16x16x32_bf16 v[58:61], v[152:155], v[176:179], v[58:61]
	v_mfma_f32_16x16x32_bf16 v[30:33], v[156:159], v[172:175], v[30:33]
	v_mfma_f32_16x16x32_bf16 v[30:33], v[160:163], v[176:179], v[30:33]
	v_mfma_f32_16x16x32_bf16 v[62:65], v[148:151], v[180:183], v[62:65]
	v_mfma_f32_16x16x32_bf16 v[62:65], v[152:155], v[184:187], v[62:65]
	v_mfma_f32_16x16x32_bf16 v[22:25], v[156:159], v[180:183], v[22:25]
	v_mfma_f32_16x16x32_bf16 v[22:25], v[160:163], v[184:187], v[22:25]
	v_mfma_f32_16x16x32_bf16 v[98:101], v[148:151], v[188:191], v[98:101]
	v_mfma_f32_16x16x32_bf16 v[98:101], v[152:155], v[226:229], v[98:101]
	v_mfma_f32_16x16x32_bf16 v[50:53], v[156:159], v[188:191], v[50:53]
	v_mfma_f32_16x16x32_bf16 v[50:53], v[160:163], v[226:229], v[50:53]
	s_barrier
	s_setprio 0
	s_add_i32 s34, s31, s45
	v_lshl_add_u64 v[192:193], s[84:85], 0, v[208:209]
	s_mov_b32 m0, s34
	ds_read_b128 v[164:167], v242 offset:16384
	ds_read_b128 v[168:171], v242 offset:17408
	ds_read_b128 v[172:175], v242 offset:18432
	ds_read_b128 v[176:179], v242 offset:19456
	ds_read_b128 v[180:183], v242 offset:20480
	ds_read_b128 v[184:187], v242 offset:21504
	ds_read_b128 v[188:191], v242 offset:22528
	ds_read_b128 v[226:229], v242 offset:23552
	global_load_lds_dwordx4 v[192:193], off
	s_add_i32 m0, s34, 0x2000
	s_add_u32 s34, s84, 0x100000
	v_lshl_add_u64 v[194:195], s[84:85], 0, v[212:213]
	s_addc_u32 s35, s85, 0
	s_add_i32 s50, s52, s45
	global_load_lds_dwordx4 v[194:195], off
	v_lshl_add_u64 v[230:231], s[34:35], 0, v[208:209]
	s_mov_b32 m0, s50
	v_lshl_add_u64 v[232:233], s[86:87], 0, v[210:211]
	global_load_lds_dwordx4 v[230:231], off
	v_lshl_add_u64 v[230:231], s[34:35], 0, v[212:213]
	s_add_i32 m0, s50, 0x2000
	s_nop 0
	global_load_lds_dwordx4 v[230:231], off
	v_lshl_add_u64 v[230:231], s[86:87], 0, v[206:207]
	s_mov_b32 m0, s28
	s_nop 0
	global_load_lds_dwordx4 v[230:231], off
	s_mov_b32 m0, s29
	s_nop 0
	global_load_lds_dwordx4 v[232:233], off
	s_waitcnt vmcnt(8)
	s_waitcnt lgkmcnt(0)
	s_setprio 1
	s_barrier
; #define PG8_STAGE(bufoff, gbase, voff) do { _Pragma("unroll") for (int _i = 0; _i < 2; ++_i) \
;         __builtin_amdgcn_global_load_lds((const unsigned*)((const char*)(gbase) + (voff)[_i]), (PG8_LAS unsigned*)(lds + (bufoff) + ldsw + _i * 8192), 16, 0, 0); } while (0)
; #define PG8_LDA(dst, b, h) do { _Pragma("unroll") for (int m = 0; m < 4; ++m) _Pragma("unroll") for (int k = 0; k < 2; ++k) dst[m][k] = *(const PG8_LAS bf16x8*)(lds + PG8_SA(b, h) + aoff + m * 2048 + k * 1024); } while (0)
; #define PG8_LDB(dst, b, h) do { _Pragma("unroll") for (int n = 0; n < 2; ++n) _Pragma("unroll") for (int k = 0; k < 2; ++k) dst[n][k] = *(const PG8_LAS bf16x8*)(lds + PG8_SB(b, h) + boff + n * 2048 + k * 1024); } while (0)
; #define PG8_MMA(ai, bj, At, Bt) do { __builtin_amdgcn_s_setprio(1); _Pragma("unroll") for (int m = 0; m < 4; ++m) _Pragma("unroll") for (int n = 0; n < 2; ++n) _Pragma("unroll") for (int k = 0; k < 2; ++k) \
;         acc[ai][bj][m][n] = __builtin_amdgcn_mfma_f32_16x16x32_bf16(Bt[n][k], At[m][k], acc[ai][bj][m][n], 0, 0, 0); __builtin_amdgcn_s_setprio(0); } while (0)
; #define PG8_WAIT_V(n) asm volatile("s_waitcnt vmcnt(" #n ")" ::: "memory")
; #define PG8_WAIT_L(n) asm volatile("s_waitcnt lgkmcnt(" #n ")" ::: "memory")
; #define PG8_BAR __builtin_amdgcn_s_barrier()
; #define PG8_SCHED __builtin_amdgcn_sched_barrier(0)
; template <class Epi, class Sched, bool ALIGN_EPI = false, bool SP2 = false>
; __device__ __forceinline__ void gemm_phase(PG8_LAS unsigned char* lds, const Gemm g, const Sched& S, const Epi& E) {
;     ...
;             PG8_WAIT_V(8); PG8_WAIT_L(0); PG8_BAR; PG8_MMA(1, 0, At, B0); PG8_MMA(1, 1, At, B1); PG8_BAR; PG8_SCHED;
;             PG8_LDB(B0, 1, 0); PG8_LDB(B1, 1, 1); PG8_SCHED; PG8_LDA(At, 1, 0); PG8_STAGE(PG8_SA(0, 1), a2 + hstep, voffA);
;             PG8_WAIT_V(8); PG8_WAIT_L(0); PG8_BAR; PG8_MMA(0, 0, At, B0); PG8_MMA(0, 1, At, B1); PG8_BAR; PG8_SCHED;
	v_mfma_f32_16x16x32_bf16 v[78:81], v[132:135], v[164:167], v[78:81]
	v_mfma_f32_16x16x32_bf16 v[78:81], v[136:139], v[168:171], v[78:81]
	v_mfma_f32_16x16x32_bf16 v[14:17], v[140:143], v[164:167], v[14:17]
	v_mfma_f32_16x16x32_bf16 v[14:17], v[144:147], v[168:171], v[14:17]
	v_mfma_f32_16x16x32_bf16 v[66:69], v[132:135], v[172:175], v[66:69]
	v_mfma_f32_16x16x32_bf16 v[66:69], v[136:139], v[176:179], v[66:69]
	v_mfma_f32_16x16x32_bf16 v[94:97], v[140:143], v[172:175], v[94:97]
	v_mfma_f32_16x16x32_bf16 v[94:97], v[144:147], v[176:179], v[94:97]
	v_mfma_f32_16x16x32_bf16 v[70:73], v[132:135], v[180:183], v[70:73]
	v_mfma_f32_16x16x32_bf16 v[70:73], v[136:139], v[184:187], v[70:73]
	v_mfma_f32_16x16x32_bf16 v[90:93], v[140:143], v[180:183], v[90:93]
	v_mfma_f32_16x16x32_bf16 v[90:93], v[144:147], v[184:187], v[90:93]
	v_mfma_f32_16x16x32_bf16 v[74:77], v[132:135], v[188:191], v[74:77]
	v_mfma_f32_16x16x32_bf16 v[74:77], v[136:139], v[226:229], v[74:77]
	v_mfma_f32_16x16x32_bf16 v[10:13], v[140:143], v[188:191], v[10:13]
	v_mfma_f32_16x16x32_bf16 v[10:13], v[144:147], v[226:229], v[10:13]
	s_setprio 0
	s_setprio 1
	v_mfma_f32_16x16x32_bf16 v[42:45], v[148:151], v[164:167], v[42:45]
	v_mfma_f32_16x16x32_bf16 v[42:45], v[152:155], v[168:171], v[42:45]
	v_mfma_f32_16x16x32_bf16 v[2:5], v[156:159], v[164:167], v[2:5]
	v_mfma_f32_16x16x32_bf16 v[2:5], v[160:163], v[168:171], v[2:5]
	v_mfma_f32_16x16x32_bf16 v[34:37], v[148:151], v[172:175], v[34:37]
	v_mfma_f32_16x16x32_bf16 v[34:37], v[152:155], v[176:179], v[34:37]
	v_mfma_f32_16x16x32_bf16 v[6:9], v[156:159], v[172:175], v[6:9]
	v_mfma_f32_16x16x32_bf16 v[6:9], v[160:163], v[176:179], v[6:9]
	v_mfma_f32_16x16x32_bf16 v[86:89], v[148:151], v[180:183], v[86:89]
	v_mfma_f32_16x16x32_bf16 v[86:89], v[152:155], v[184:187], v[86:89]
	v_mfma_f32_16x16x32_bf16 v[26:29], v[156:159], v[180:183], v[26:29]
	v_mfma_f32_16x16x32_bf16 v[26:29], v[160:163], v[184:187], v[26:29]
	v_mfma_f32_16x16x32_bf16 v[82:85], v[148:151], v[188:191], v[82:85]
	v_mfma_f32_16x16x32_bf16 v[82:85], v[152:155], v[226:229], v[82:85]
	v_mfma_f32_16x16x32_bf16 v[18:21], v[156:159], v[188:191], v[18:21]
	v_mfma_f32_16x16x32_bf16 v[18:21], v[160:163], v[226:229], v[18:21]
	s_barrier
	s_setprio 0
	s_add_i32 s50, 0, 0x18000
	s_add_i32 s56, 0, 0x1c000
	v_add_u32_e32 v144, s50, v201
	v_add_u32_e32 v160, s56, v201
	ds_read_b128 v[132:135], v144
	ds_read_b128 v[136:139], v144 offset:1024
	ds_read_b128 v[140:143], v144 offset:2048
	ds_read_b128 v[144:147], v144 offset:3072
	ds_read_b128 v[148:151], v160
	ds_read_b128 v[152:155], v160 offset:1024
	ds_read_b128 v[156:159], v160 offset:2048
	ds_read_b128 v[160:163], v160 offset:3072
	s_add_u32 s34, s86, 0x100000
	s_addc_u32 s35, s87, 0
	s_mov_b32 m0, s16
	v_lshl_add_u64 v[246:247], s[34:35], 0, v[206:207]
	ds_read_b128 v[164:167], v242 offset:32768
	ds_read_b128 v[168:171], v242 offset:33792
	ds_read_b128 v[172:175], v242 offset:34816
	ds_read_b128 v[176:179], v242 offset:35840
	ds_read_b128 v[180:183], v242 offset:36864
	ds_read_b128 v[184:187], v242 offset:37888
	ds_read_b128 v[188:191], v242 offset:38912
	ds_read_b128 v[226:229], v242 offset:39936
	global_load_lds_dwordx4 v[246:247], off
	v_lshl_add_u64 v[246:247], s[34:35], 0, v[210:211]
	s_mov_b32 m0, s17
	s_nop 0
	global_load_lds_dwordx4 v[246:247], off
	s_waitcnt vmcnt(8)
	s_waitcnt lgkmcnt(0)
	s_setprio 1
	s_barrier
	v_mfma_f32_16x16x32_bf16 v[126:129], v[132:135], v[164:167], v[126:129]
	v_mfma_f32_16x16x32_bf16 v[126:129], v[136:139], v[168:171], v[126:129]
	v_mfma_f32_16x16x32_bf16 v[46:49], v[140:143], v[164:167], v[46:49]
	v_mfma_f32_16x16x32_bf16 v[46:49], v[144:147], v[168:171], v[46:49]
	v_mfma_f32_16x16x32_bf16 v[118:121], v[132:135], v[172:175], v[118:121]
	v_mfma_f32_16x16x32_bf16 v[118:121], v[136:139], v[176:179], v[118:121]
	v_mfma_f32_16x16x32_bf16 v[122:125], v[140:143], v[172:175], v[122:125]
	v_mfma_f32_16x16x32_bf16 v[122:125], v[144:147], v[176:179], v[122:125]
	v_mfma_f32_16x16x32_bf16 v[110:113], v[132:135], v[180:183], v[110:113]
	v_mfma_f32_16x16x32_bf16 v[110:113], v[136:139], v[184:187], v[110:113]
	v_mfma_f32_16x16x32_bf16 v[114:117], v[140:143], v[180:183], v[114:117]
	v_mfma_f32_16x16x32_bf16 v[114:117], v[144:147], v[184:187], v[114:117]
	v_mfma_f32_16x16x32_bf16 v[102:105], v[132:135], v[188:191], v[102:105]
	v_mfma_f32_16x16x32_bf16 v[102:105], v[136:139], v[226:229], v[102:105]
	v_mfma_f32_16x16x32_bf16 v[106:109], v[140:143], v[188:191], v[106:109]
	v_mfma_f32_16x16x32_bf16 v[106:109], v[144:147], v[226:229], v[106:109]
	s_setprio 0
	s_setprio 1
	v_mfma_f32_16x16x32_bf16 v[54:57], v[148:151], v[164:167], v[54:57]
	v_mfma_f32_16x16x32_bf16 v[54:57], v[152:155], v[168:171], v[54:57]
	v_mfma_f32_16x16x32_bf16 v[38:41], v[156:159], v[164:167], v[38:41]
	v_mfma_f32_16x16x32_bf16 v[38:41], v[160:163], v[168:171], v[38:41]
	v_mfma_f32_16x16x32_bf16 v[58:61], v[148:151], v[172:175], v[58:61]
	v_mfma_f32_16x16x32_bf16 v[58:61], v[152:155], v[176:179], v[58:61]
	v_mfma_f32_16x16x32_bf16 v[30:33], v[156:159], v[172:175], v[30:33]
	v_mfma_f32_16x16x32_bf16 v[30:33], v[160:163], v[176:179], v[30:33]
	v_mfma_f32_16x16x32_bf16 v[62:65], v[148:151], v[180:183], v[62:65]
	v_mfma_f32_16x16x32_bf16 v[62:65], v[152:155], v[184:187], v[62:65]
	v_mfma_f32_16x16x32_bf16 v[22:25], v[156:159], v[180:183], v[22:25]
	v_mfma_f32_16x16x32_bf16 v[22:25], v[160:163], v[184:187], v[22:25]
	v_mfma_f32_16x16x32_bf16 v[98:101], v[148:151], v[188:191], v[98:101]
	v_mfma_f32_16x16x32_bf16 v[98:101], v[152:155], v[226:229], v[98:101]
	v_mfma_f32_16x16x32_bf16 v[50:53], v[156:159], v[188:191], v[50:53]
	v_mfma_f32_16x16x32_bf16 v[50:53], v[160:163], v[226:229], v[50:53]
	s_barrier
; #define PG8_STAGE(bufoff, gbase, voff) do { _Pragma("unroll") for (int _i = 0; _i < 2; ++_i) \
;         __builtin_amdgcn_global_load_lds((const unsigned*)((const char*)(gbase) + (voff)[_i]), (PG8_LAS unsigned*)(lds + (bufoff) + ldsw + _i * 8192), 16, 0, 0); } while (0)
; #define PG8_LDA(dst, b, h) do { _Pragma("unroll") for (int m = 0; m < 4; ++m) _Pragma("unroll") for (int k = 0; k < 2; ++k) dst[m][k] = *(const PG8_LAS bf16x8*)(lds + PG8_SA(b, h) + aoff + m * 2048 + k * 1024); } while (0)
; #define PG8_MMA(ai, bj, At, Bt) do { __builtin_amdgcn_s_setprio(1); _Pragma("unroll") for (int m = 0; m < 4; ++m) _Pragma("unroll") for (int n = 0; n < 2; ++n) _Pragma("unroll") for (int k = 0; k < 2; ++k) \
;         acc[ai][bj][m][n] = __builtin_amdgcn_mfma_f32_16x16x32_bf16(Bt[n][k], At[m][k], acc[ai][bj][m][n], 0, 0, 0); __builtin_amdgcn_s_setprio(0); } while (0)
; #define PG8_WAIT_V(n) asm volatile("s_waitcnt vmcnt(" #n ")" ::: "memory")
; #define PG8_WAIT_L(n) asm volatile("s_waitcnt lgkmcnt(" #n ")" ::: "memory")
; #define PG8_BAR __builtin_amdgcn_s_barrier()
; #define PG8_SCHED __builtin_amdgcn_sched_barrier(0)
; template <class Epi, class Sched, bool ALIGN_EPI = false, bool SP2 = false>
; __device__ __forceinline__ void gemm_phase(PG8_LAS unsigned char* lds, const Gemm g, const Sched& S, const Epi& E) {
;     ...
;         for (int t = 0; t < nt; t += 2) {
;             const bool last = (t == nt - 2);
;             const char* a1 = cA + (size_t)(t + 1) * kstep;
;             const char* a2 = last ? nA : cA + (size_t)(t + 2) * kstep; const char* b2 = last ? nB : cB + (size_t)(t + 2) * kstep;
;             const char* a3 = a2 + kstep; const char* b3 = b2 + kstep;
;     ...
;             PG8_LDA(At, 1, 1); PG8_STAGE(PG8_SB(1, 0), b3, voffB); PG8_STAGE(PG8_SB(1, 1), b3 + hstep, voffB); PG8_STAGE(PG8_SA(1, 0), a3, voffA);
;             PG8_WAIT_V(8); PG8_WAIT_L(0); PG8_BAR; PG8_MMA(1, 0, At, B0); PG8_MMA(1, 1, At, B1); PG8_BAR; PG8_SCHED;
	s_setprio 0
	s_add_i32 s34, s50, s45
	v_lshl_add_u64 v[192:193], v[192:193], 0, s[54:55]
	s_mov_b32 m0, s34
	ds_read_b128 v[164:167], v242 offset:49152
	ds_read_b128 v[168:171], v242 offset:50176
	ds_read_b128 v[172:175], v242 offset:51200
	ds_read_b128 v[176:179], v242 offset:52224
	ds_read_b128 v[180:183], v242 offset:53248
	ds_read_b128 v[184:187], v242 offset:54272
	ds_read_b128 v[188:191], v242 offset:55296
	ds_read_b128 v[226:229], v242 offset:56320
	global_load_lds_dwordx4 v[192:193], off
	s_add_i32 m0, s34, 0x2000
	s_add_u32 s34, s84, 0x100080
	v_lshl_add_u64 v[192:193], v[194:195], 0, s[54:55]
	s_addc_u32 s35, s85, 0
	s_add_i32 s50, s56, s45
	global_load_lds_dwordx4 v[192:193], off
	v_lshl_add_u64 v[192:193], s[34:35], 0, v[208:209]
	s_mov_b32 m0, s50
	s_nop 0
	global_load_lds_dwordx4 v[192:193], off
	v_lshl_add_u64 v[192:193], s[34:35], 0, v[212:213]
	s_add_i32 m0, s50, 0x2000
	s_nop 0
	global_load_lds_dwordx4 v[192:193], off
	v_lshl_add_u64 v[192:193], v[230:231], 0, s[54:55]
	s_mov_b32 m0, s39
	s_nop 0
	global_load_lds_dwordx4 v[192:193], off
	v_lshl_add_u64 v[192:193], v[232:233], 0, s[54:55]
	s_mov_b32 m0, s46
	s_nop 0
	global_load_lds_dwordx4 v[192:193], off
	s_waitcnt vmcnt(8)
	s_waitcnt lgkmcnt(0)
	s_setprio 1
	s_barrier
	v_mfma_f32_16x16x32_bf16 v[78:81], v[132:135], v[164:167], v[78:81]
	v_mfma_f32_16x16x32_bf16 v[78:81], v[136:139], v[168:171], v[78:81]
	v_mfma_f32_16x16x32_bf16 v[14:17], v[140:143], v[164:167], v[14:17]
	v_mfma_f32_16x16x32_bf16 v[14:17], v[144:147], v[168:171], v[14:17]
	v_mfma_f32_16x16x32_bf16 v[66:69], v[132:135], v[172:175], v[66:69]
	v_mfma_f32_16x16x32_bf16 v[66:69], v[136:139], v[176:179], v[66:69]
	v_mfma_f32_16x16x32_bf16 v[94:97], v[140:143], v[172:175], v[94:97]
	v_mfma_f32_16x16x32_bf16 v[94:97], v[144:147], v[176:179], v[94:97]
	v_mfma_f32_16x16x32_bf16 v[70:73], v[132:135], v[180:183], v[70:73]
	v_mfma_f32_16x16x32_bf16 v[70:73], v[136:139], v[184:187], v[70:73]
	v_mfma_f32_16x16x32_bf16 v[90:93], v[140:143], v[180:183], v[90:93]
	v_mfma_f32_16x16x32_bf16 v[90:93], v[144:147], v[184:187], v[90:93]
	v_mfma_f32_16x16x32_bf16 v[74:77], v[132:135], v[188:191], v[74:77]
	v_mfma_f32_16x16x32_bf16 v[74:77], v[136:139], v[226:229], v[74:77]
	v_mfma_f32_16x16x32_bf16 v[10:13], v[140:143], v[188:191], v[10:13]
	v_mfma_f32_16x16x32_bf16 v[10:13], v[144:147], v[226:229], v[10:13]
	s_setprio 0
	s_setprio 1
	v_mfma_f32_16x16x32_bf16 v[42:45], v[148:151], v[164:167], v[42:45]
	v_mfma_f32_16x16x32_bf16 v[42:45], v[152:155], v[168:171], v[42:45]
	v_mfma_f32_16x16x32_bf16 v[2:5], v[156:159], v[164:167], v[2:5]
	v_mfma_f32_16x16x32_bf16 v[2:5], v[160:163], v[168:171], v[2:5]
	v_mfma_f32_16x16x32_bf16 v[34:37], v[148:151], v[172:175], v[34:37]
	v_mfma_f32_16x16x32_bf16 v[34:37], v[152:155], v[176:179], v[34:37]
	v_mfma_f32_16x16x32_bf16 v[6:9], v[156:159], v[172:175], v[6:9]
	v_mfma_f32_16x16x32_bf16 v[6:9], v[160:163], v[176:179], v[6:9]
	v_mfma_f32_16x16x32_bf16 v[86:89], v[148:151], v[180:183], v[86:89]
	v_mfma_f32_16x16x32_bf16 v[86:89], v[152:155], v[184:187], v[86:89]
	v_mfma_f32_16x16x32_bf16 v[26:29], v[156:159], v[180:183], v[26:29]
	v_mfma_f32_16x16x32_bf16 v[26:29], v[160:163], v[184:187], v[26:29]
	v_mfma_f32_16x16x32_bf16 v[82:85], v[148:151], v[188:191], v[82:85]
	v_mfma_f32_16x16x32_bf16 v[82:85], v[152:155], v[226:229], v[82:85]
	v_mfma_f32_16x16x32_bf16 v[18:21], v[156:159], v[188:191], v[18:21]
	v_mfma_f32_16x16x32_bf16 v[18:21], v[160:163], v[226:229], v[18:21]
	s_barrier
	s_setprio 0
	s_add_i32 s89, s89, 2
	s_add_u32 s82, s82, 0x100
	s_addc_u32 s83, s83, 0
	s_add_u32 s79, s79, 0x100
	s_addc_u32 s88, s88, 0
	s_cmp_gt_u32 s89, 61
	s_cbranch_scc1 .LBB0_1490

; #define PG8_STAGE(bufoff, gbase, voff) do { _Pragma("unroll") for (int _i = 0; _i < 2; ++_i) \
;         __builtin_amdgcn_global_load_lds((const unsigned*)((const char*)(gbase) + (voff)[_i]), (PG8_LAS unsigned*)(lds + (bufoff) + ldsw + _i * 8192), 16, 0, 0); } while (0)
; #define PG8_LDA(dst, b, h) do { _Pragma("unroll") for (int m = 0; m < 4; ++m) _Pragma("unroll") for (int k = 0; k < 2; ++k) dst[m][k] = *(const PG8_LAS bf16x8*)(lds + PG8_SA(b, h) + aoff + m * 2048 + k * 1024); } while (0)
; #define PG8_LDB(dst, b, h) do { _Pragma("unroll") for (int n = 0; n < 2; ++n) _Pragma("unroll") for (int k = 0; k < 2; ++k) dst[n][k] = *(const PG8_LAS bf16x8*)(lds + PG8_SB(b, h) + boff + n * 2048 + k * 1024); } while (0)
; #define PG8_MMA(ai, bj, At, Bt) do { __builtin_amdgcn_s_setprio(1); _Pragma("unroll") for (int m = 0; m < 4; ++m) _Pragma("unroll") for (int n = 0; n < 2; ++n) _Pragma("unroll") for (int k = 0; k < 2; ++k) \
;         acc[ai][bj][m][n] = __builtin_amdgcn_mfma_f32_16x16x32_bf16(Bt[n][k], At[m][k], acc[ai][bj][m][n], 0, 0, 0); __builtin_amdgcn_s_setprio(0); } while (0)
; #define PG8_WAIT_V(n) asm volatile("s_waitcnt vmcnt(" #n ")" ::: "memory")
; #define PG8_WAIT_L(n) asm volatile("s_waitcnt lgkmcnt(" #n ")" ::: "memory")
; #define PG8_BAR __builtin_amdgcn_s_barrier()
; #define PG8_SCHED __builtin_amdgcn_sched_barrier(0)
; template <class Epi, class Sched, bool ALIGN_EPI = false, bool SP2 = false>
; __device__ __forceinline__ void gemm_phase(PG8_LAS unsigned char* lds, const Gemm g, const Sched& S, const Epi& E) {
;     ...
;             const bool last = (t == nt - 2);
;             const char* a1 = cA + (size_t)(t + 1) * kstep;
;             const char* a2 = last ? nA : cA + (size_t)(t + 2) * kstep; const char* b2 = last ? nB : cB + (size_t)(t + 2) * kstep;
;             const char* a3 = a2 + kstep; const char* b3 = b2 + kstep;
;             if (last && has_next) S.a_ready(nxt);
;             if constexpr (SP2) {
;             PG8_LDB(B0, 0, 0); PG8_LDB(B1, 0, 1); PG8_SCHED; PG8_LDA(At, 0, 0); PG8_STAGE(PG8_SA(1, 1), a1 + hstep, voffA);
;             PG8_WAIT_V(8); PG8_WAIT_L(0); PG8_BAR; PG8_MMA(0, 0, At, B0); PG8_MMA(0, 1, At, B1); PG8_BAR; PG8_SCHED;
;             PG8_LDA(At, 0, 1); PG8_STAGE(PG8_SB(0, 0), b2, voffB); PG8_STAGE(PG8_SB(0, 1), b2 + hstep, voffB); PG8_STAGE(PG8_SA(0, 0), a2, voffA);
.LBB0_1731:
	ds_read_b128 v[170:173], v166
	ds_read_b128 v[174:177], v166 offset:1024
	ds_read_b128 v[178:181], v166 offset:2048
	ds_read_b128 v[182:185], v166 offset:3072
	ds_read_b128 v[186:189], v167
	ds_read_b128 v[190:193], v167 offset:1024
	ds_read_b128 v[196:199], v167 offset:2048
	ds_read_b128 v[202:205], v167 offset:3072
	s_add_u32 s48, s40, 0x100
	s_addc_u32 s49, s41, 0
	s_cmpk_eq_i32 s56, 0xa8
	s_cselect_b32 s53, s7, s49
	s_cselect_b32 s52, s6, s48
	s_cselect_b32 s51, s39, s55
	s_cselect_b32 s50, s38, s54
	v_lshl_add_u64 v[146:147], s[40:41], 0, v[138:139]
	s_add_i32 m0, s16, 0xc000
	ds_read_b128 v[206:209], v168
	ds_read_b128 v[210:213], v168 offset:1024
	ds_read_b128 v[214:217], v168 offset:2048
	ds_read_b128 v[218:221], v168 offset:3072
	ds_read_b128 v[222:225], v168 offset:4096
	ds_read_b128 v[226:229], v168 offset:5120
	ds_read_b128 v[230:233], v168 offset:6144
	ds_read_b128 v[234:237], v168 offset:7168
	global_load_lds_dwordx4 v[146:147], off
	v_lshl_add_u64 v[146:147], s[40:41], 0, v[140:141]
	s_add_i32 m0, s16, 0xe000
	s_nop 0
	global_load_lds_dwordx4 v[146:147], off
	s_waitcnt vmcnt(8)
	s_waitcnt lgkmcnt(0)
	s_setprio 1
	s_barrier
	v_mfma_f32_16x16x32_bf16 v[126:129], v[170:173], v[206:209], v[126:129]
	v_mfma_f32_16x16x32_bf16 v[126:129], v[174:177], v[210:213], v[126:129]
	v_mfma_f32_16x16x32_bf16 v[122:125], v[178:181], v[206:209], v[122:125]
	v_mfma_f32_16x16x32_bf16 v[122:125], v[182:185], v[210:213], v[122:125]
	v_mfma_f32_16x16x32_bf16 v[110:113], v[170:173], v[214:217], v[110:113]
	v_mfma_f32_16x16x32_bf16 v[110:113], v[174:177], v[218:221], v[110:113]
	v_mfma_f32_16x16x32_bf16 v[106:109], v[178:181], v[214:217], v[106:109]
	v_mfma_f32_16x16x32_bf16 v[106:109], v[182:185], v[218:221], v[106:109]
	v_mfma_f32_16x16x32_bf16 v[94:97], v[170:173], v[222:225], v[94:97]
	v_mfma_f32_16x16x32_bf16 v[94:97], v[174:177], v[226:229], v[94:97]
	v_mfma_f32_16x16x32_bf16 v[90:93], v[178:181], v[222:225], v[90:93]
	v_mfma_f32_16x16x32_bf16 v[90:93], v[182:185], v[226:229], v[90:93]
	v_mfma_f32_16x16x32_bf16 v[78:81], v[170:173], v[230:233], v[78:81]
	v_mfma_f32_16x16x32_bf16 v[78:81], v[174:177], v[234:237], v[78:81]
	v_mfma_f32_16x16x32_bf16 v[74:77], v[178:181], v[230:233], v[74:77]
	v_mfma_f32_16x16x32_bf16 v[74:77], v[182:185], v[234:237], v[74:77]
	s_setprio 0
	s_setprio 1
	v_mfma_f32_16x16x32_bf16 v[118:121], v[186:189], v[206:209], v[118:121]
	v_mfma_f32_16x16x32_bf16 v[118:121], v[190:193], v[210:213], v[118:121]
	v_mfma_f32_16x16x32_bf16 v[114:117], v[196:199], v[206:209], v[114:117]
	v_mfma_f32_16x16x32_bf16 v[114:117], v[202:205], v[210:213], v[114:117]
	v_mfma_f32_16x16x32_bf16 v[102:105], v[186:189], v[214:217], v[102:105]
	v_mfma_f32_16x16x32_bf16 v[102:105], v[190:193], v[218:221], v[102:105]
	v_mfma_f32_16x16x32_bf16 v[98:101], v[196:199], v[214:217], v[98:101]
	v_mfma_f32_16x16x32_bf16 v[98:101], v[202:205], v[218:221], v[98:101]
	v_mfma_f32_16x16x32_bf16 v[86:89], v[186:189], v[222:225], v[86:89]
	v_mfma_f32_16x16x32_bf16 v[86:89], v[190:193], v[226:229], v[86:89]
	v_mfma_f32_16x16x32_bf16 v[82:85], v[196:199], v[222:225], v[82:85]
	v_mfma_f32_16x16x32_bf16 v[82:85], v[202:205], v[226:229], v[82:85]
	v_mfma_f32_16x16x32_bf16 v[70:73], v[186:189], v[230:233], v[70:73]
	v_mfma_f32_16x16x32_bf16 v[70:73], v[190:193], v[234:237], v[70:73]
	v_mfma_f32_16x16x32_bf16 v[66:69], v[196:199], v[230:233], v[66:69]
	v_mfma_f32_16x16x32_bf16 v[66:69], v[202:205], v[234:237], v[66:69]
	s_barrier
	s_setprio 0
	s_add_i32 s40, s31, s3
	v_lshl_add_u64 v[146:147], s[50:51], 0, v[132:133]
	s_mov_b32 m0, s40
	ds_read_b128 v[206:209], v168 offset:16384
	ds_read_b128 v[210:213], v168 offset:17408
	ds_read_b128 v[214:217], v168 offset:18432
	ds_read_b128 v[218:221], v168 offset:19456
	ds_read_b128 v[222:225], v168 offset:20480
	ds_read_b128 v[226:229], v168 offset:21504
	ds_read_b128 v[230:233], v168 offset:22528
	ds_read_b128 v[234:237], v168 offset:23552
	global_load_lds_dwordx4 v[146:147], off
	s_add_i32 m0, s40, 0x2000
	s_add_u32 s40, s50, 0x2b0000
	v_lshl_add_u64 v[194:195], s[50:51], 0, v[136:137]
	s_addc_u32 s41, s51, 0
	s_add_i32 s57, s35, s3
	global_load_lds_dwordx4 v[194:195], off
	v_lshl_add_u64 v[238:239], s[40:41], 0, v[132:133]
	s_mov_b32 m0, s57
	v_lshl_add_u64 v[240:241], s[52:53], 0, v[134:135]
	global_load_lds_dwordx4 v[238:239], off
	v_lshl_add_u64 v[238:239], s[40:41], 0, v[136:137]
	s_add_i32 m0, s57, 0x2000
	s_nop 0
	global_load_lds_dwordx4 v[238:239], off
	v_lshl_add_u64 v[238:239], s[52:53], 0, v[130:131]
	s_mov_b32 m0, s16
	s_nop 0
	global_load_lds_dwordx4 v[238:239], off
	s_mov_b32 m0, s17
	s_nop 0
	global_load_lds_dwordx4 v[240:241], off
	s_waitcnt vmcnt(8)
	s_waitcnt lgkmcnt(0)
	s_setprio 1
	s_barrier
; #define PG8_STAGE(bufoff, gbase, voff) do { _Pragma("unroll") for (int _i = 0; _i < 2; ++_i) \
;         __builtin_amdgcn_global_load_lds((const unsigned*)((const char*)(gbase) + (voff)[_i]), (PG8_LAS unsigned*)(lds + (bufoff) + ldsw + _i * 8192), 16, 0, 0); } while (0)
; #define PG8_LDA(dst, b, h) do { _Pragma("unroll") for (int m = 0; m < 4; ++m) _Pragma("unroll") for (int k = 0; k < 2; ++k) dst[m][k] = *(const PG8_LAS bf16x8*)(lds + PG8_SA(b, h) + aoff + m * 2048 + k * 1024); } while (0)
; #define PG8_LDB(dst, b, h) do { _Pragma("unroll") for (int n = 0; n < 2; ++n) _Pragma("unroll") for (int k = 0; k < 2; ++k) dst[n][k] = *(const PG8_LAS bf16x8*)(lds + PG8_SB(b, h) + boff + n * 2048 + k * 1024); } while (0)
; #define PG8_MMA(ai, bj, At, Bt) do { __builtin_amdgcn_s_setprio(1); _Pragma("unroll") for (int m = 0; m < 4; ++m) _Pragma("unroll") for (int n = 0; n < 2; ++n) _Pragma("unroll") for (int k = 0; k < 2; ++k) \
;         acc[ai][bj][m][n] = __builtin_amdgcn_mfma_f32_16x16x32_bf16(Bt[n][k], At[m][k], acc[ai][bj][m][n], 0, 0, 0); __builtin_amdgcn_s_setprio(0); } while (0)
; #define PG8_WAIT_V(n) asm volatile("s_waitcnt vmcnt(" #n ")" ::: "memory")
; #define PG8_WAIT_L(n) asm volatile("s_waitcnt lgkmcnt(" #n ")" ::: "memory")
; #define PG8_BAR __builtin_amdgcn_s_barrier()
; #define PG8_SCHED __builtin_amdgcn_sched_barrier(0)
; template <class Epi, class Sched, bool ALIGN_EPI = false, bool SP2 = false>
; __device__ __forceinline__ void gemm_phase(PG8_LAS unsigned char* lds, const Gemm g, const Sched& S, const Epi& E) {
;     ...
;             PG8_WAIT_V(8); PG8_WAIT_L(0); PG8_BAR; PG8_MMA(1, 0, At, B0); PG8_MMA(1, 1, At, B1); PG8_BAR; PG8_SCHED;
;             PG8_LDB(B0, 1, 0); PG8_LDB(B1, 1, 1); PG8_SCHED; PG8_LDA(At, 1, 0); PG8_STAGE(PG8_SA(0, 1), a2 + hstep, voffA);
;             PG8_WAIT_V(8); PG8_WAIT_L(0); PG8_BAR; PG8_MMA(0, 0, At, B0); PG8_MMA(0, 1, At, B1); PG8_BAR; PG8_SCHED;
	v_mfma_f32_16x16x32_bf16 v[62:65], v[170:173], v[206:209], v[62:65]
	v_mfma_f32_16x16x32_bf16 v[62:65], v[174:177], v[210:213], v[62:65]
	v_mfma_f32_16x16x32_bf16 v[58:61], v[178:181], v[206:209], v[58:61]
	v_mfma_f32_16x16x32_bf16 v[58:61], v[182:185], v[210:213], v[58:61]
	v_mfma_f32_16x16x32_bf16 v[46:49], v[170:173], v[214:217], v[46:49]
	v_mfma_f32_16x16x32_bf16 v[46:49], v[174:177], v[218:221], v[46:49]
	v_mfma_f32_16x16x32_bf16 v[42:45], v[178:181], v[214:217], v[42:45]
	v_mfma_f32_16x16x32_bf16 v[42:45], v[182:185], v[218:221], v[42:45]
	v_mfma_f32_16x16x32_bf16 v[30:33], v[170:173], v[222:225], v[30:33]
	v_mfma_f32_16x16x32_bf16 v[30:33], v[174:177], v[226:229], v[30:33]
	v_mfma_f32_16x16x32_bf16 v[26:29], v[178:181], v[222:225], v[26:29]
	v_mfma_f32_16x16x32_bf16 v[26:29], v[182:185], v[226:229], v[26:29]
	v_mfma_f32_16x16x32_bf16 v[14:17], v[170:173], v[230:233], v[14:17]
	v_mfma_f32_16x16x32_bf16 v[14:17], v[174:177], v[234:237], v[14:17]
	v_mfma_f32_16x16x32_bf16 v[10:13], v[178:181], v[230:233], v[10:13]
	v_mfma_f32_16x16x32_bf16 v[10:13], v[182:185], v[234:237], v[10:13]
	s_setprio 0
	s_setprio 1
	v_mfma_f32_16x16x32_bf16 v[54:57], v[186:189], v[206:209], v[54:57]
	v_mfma_f32_16x16x32_bf16 v[54:57], v[190:193], v[210:213], v[54:57]
	v_mfma_f32_16x16x32_bf16 v[50:53], v[196:199], v[206:209], v[50:53]
	v_mfma_f32_16x16x32_bf16 v[50:53], v[202:205], v[210:213], v[50:53]
	v_mfma_f32_16x16x32_bf16 v[38:41], v[186:189], v[214:217], v[38:41]
	v_mfma_f32_16x16x32_bf16 v[38:41], v[190:193], v[218:221], v[38:41]
	v_mfma_f32_16x16x32_bf16 v[34:37], v[196:199], v[214:217], v[34:37]
	v_mfma_f32_16x16x32_bf16 v[34:37], v[202:205], v[218:221], v[34:37]
	v_mfma_f32_16x16x32_bf16 v[22:25], v[186:189], v[222:225], v[22:25]
	v_mfma_f32_16x16x32_bf16 v[22:25], v[190:193], v[226:229], v[22:25]
	v_mfma_f32_16x16x32_bf16 v[18:21], v[196:199], v[222:225], v[18:21]
	v_mfma_f32_16x16x32_bf16 v[18:21], v[202:205], v[226:229], v[18:21]
	v_mfma_f32_16x16x32_bf16 v[6:9], v[186:189], v[230:233], v[6:9]
	v_mfma_f32_16x16x32_bf16 v[6:9], v[190:193], v[234:237], v[6:9]
	v_mfma_f32_16x16x32_bf16 v[2:5], v[196:199], v[230:233], v[2:5]
	v_mfma_f32_16x16x32_bf16 v[2:5], v[202:205], v[234:237], v[2:5]
	s_barrier
	s_setprio 0
	s_add_i32 s57, 0, 0x18000
	v_add_u32_e32 v169, s57, v148
	s_add_i32 s58, 0, 0x1c000
	ds_read_b128 v[170:173], v169
	ds_read_b128 v[174:177], v169 offset:1024
	ds_read_b128 v[178:181], v169 offset:2048
	ds_read_b128 v[182:185], v169 offset:3072
	v_add_u32_e32 v169, s58, v148
	ds_read_b128 v[186:189], v169
	ds_read_b128 v[190:193], v169 offset:1024
	ds_read_b128 v[196:199], v169 offset:2048
	ds_read_b128 v[202:205], v169 offset:3072
	s_add_u32 s40, s52, 0x2b0000
	s_addc_u32 s41, s53, 0
	s_mov_b32 m0, s25
	v_lshl_add_u64 v[242:243], s[40:41], 0, v[130:131]
	ds_read_b128 v[206:209], v168 offset:32768
	ds_read_b128 v[210:213], v168 offset:33792
	ds_read_b128 v[214:217], v168 offset:34816
	ds_read_b128 v[218:221], v168 offset:35840
	ds_read_b128 v[222:225], v168 offset:36864
	ds_read_b128 v[226:229], v168 offset:37888
	ds_read_b128 v[230:233], v168 offset:38912
	ds_read_b128 v[234:237], v168 offset:39936
	global_load_lds_dwordx4 v[242:243], off
	v_lshl_add_u64 v[242:243], s[40:41], 0, v[134:135]
	s_mov_b32 m0, s26
	s_nop 0
	global_load_lds_dwordx4 v[242:243], off
	s_waitcnt vmcnt(8)
	s_waitcnt lgkmcnt(0)
	s_setprio 1
	s_barrier
	v_mfma_f32_16x16x32_bf16 v[126:129], v[170:173], v[206:209], v[126:129]
	v_mfma_f32_16x16x32_bf16 v[126:129], v[174:177], v[210:213], v[126:129]
	v_mfma_f32_16x16x32_bf16 v[122:125], v[178:181], v[206:209], v[122:125]
	v_mfma_f32_16x16x32_bf16 v[122:125], v[182:185], v[210:213], v[122:125]
	v_mfma_f32_16x16x32_bf16 v[110:113], v[170:173], v[214:217], v[110:113]
	v_mfma_f32_16x16x32_bf16 v[110:113], v[174:177], v[218:221], v[110:113]
	v_mfma_f32_16x16x32_bf16 v[106:109], v[178:181], v[214:217], v[106:109]
	v_mfma_f32_16x16x32_bf16 v[106:109], v[182:185], v[218:221], v[106:109]
	v_mfma_f32_16x16x32_bf16 v[94:97], v[170:173], v[222:225], v[94:97]
	v_mfma_f32_16x16x32_bf16 v[94:97], v[174:177], v[226:229], v[94:97]
	v_mfma_f32_16x16x32_bf16 v[90:93], v[178:181], v[222:225], v[90:93]
	v_mfma_f32_16x16x32_bf16 v[90:93], v[182:185], v[226:229], v[90:93]
	v_mfma_f32_16x16x32_bf16 v[78:81], v[170:173], v[230:233], v[78:81]
	v_mfma_f32_16x16x32_bf16 v[78:81], v[174:177], v[234:237], v[78:81]
	v_mfma_f32_16x16x32_bf16 v[74:77], v[178:181], v[230:233], v[74:77]
	v_mfma_f32_16x16x32_bf16 v[74:77], v[182:185], v[234:237], v[74:77]
	s_setprio 0
	s_setprio 1
	v_mfma_f32_16x16x32_bf16 v[118:121], v[186:189], v[206:209], v[118:121]
	v_mfma_f32_16x16x32_bf16 v[118:121], v[190:193], v[210:213], v[118:121]
	v_mfma_f32_16x16x32_bf16 v[114:117], v[196:199], v[206:209], v[114:117]
	v_mfma_f32_16x16x32_bf16 v[114:117], v[202:205], v[210:213], v[114:117]
	v_mfma_f32_16x16x32_bf16 v[102:105], v[186:189], v[214:217], v[102:105]
	v_mfma_f32_16x16x32_bf16 v[102:105], v[190:193], v[218:221], v[102:105]
	v_mfma_f32_16x16x32_bf16 v[98:101], v[196:199], v[214:217], v[98:101]
	v_mfma_f32_16x16x32_bf16 v[98:101], v[202:205], v[218:221], v[98:101]
	v_mfma_f32_16x16x32_bf16 v[86:89], v[186:189], v[222:225], v[86:89]
	v_mfma_f32_16x16x32_bf16 v[86:89], v[190:193], v[226:229], v[86:89]
	v_mfma_f32_16x16x32_bf16 v[82:85], v[196:199], v[222:225], v[82:85]
	v_mfma_f32_16x16x32_bf16 v[82:85], v[202:205], v[226:229], v[82:85]
	v_mfma_f32_16x16x32_bf16 v[70:73], v[186:189], v[230:233], v[70:73]
	v_mfma_f32_16x16x32_bf16 v[70:73], v[190:193], v[234:237], v[70:73]
	v_mfma_f32_16x16x32_bf16 v[66:69], v[196:199], v[230:233], v[66:69]
	v_mfma_f32_16x16x32_bf16 v[66:69], v[202:205], v[234:237], v[66:69]
	s_barrier
; #define PG8_STAGE(bufoff, gbase, voff) do { _Pragma("unroll") for (int _i = 0; _i < 2; ++_i) \
;         __builtin_amdgcn_global_load_lds((const unsigned*)((const char*)(gbase) + (voff)[_i]), (PG8_LAS unsigned*)(lds + (bufoff) + ldsw + _i * 8192), 16, 0, 0); } while (0)
; #define PG8_LDA(dst, b, h) do { _Pragma("unroll") for (int m = 0; m < 4; ++m) _Pragma("unroll") for (int k = 0; k < 2; ++k) dst[m][k] = *(const PG8_LAS bf16x8*)(lds + PG8_SA(b, h) + aoff + m * 2048 + k * 1024); } while (0)
; #define PG8_MMA(ai, bj, At, Bt) do { __builtin_amdgcn_s_setprio(1); _Pragma("unroll") for (int m = 0; m < 4; ++m) _Pragma("unroll") for (int n = 0; n < 2; ++n) _Pragma("unroll") for (int k = 0; k < 2; ++k) \
;         acc[ai][bj][m][n] = __builtin_amdgcn_mfma_f32_16x16x32_bf16(Bt[n][k], At[m][k], acc[ai][bj][m][n], 0, 0, 0); __builtin_amdgcn_s_setprio(0); } while (0)
; #define PG8_WAIT_V(n) asm volatile("s_waitcnt vmcnt(" #n ")" ::: "memory")
; #define PG8_WAIT_L(n) asm volatile("s_waitcnt lgkmcnt(" #n ")" ::: "memory")
; #define PG8_BAR __builtin_amdgcn_s_barrier()
; #define PG8_SCHED __builtin_amdgcn_sched_barrier(0)
; template <class Epi, class Sched, bool ALIGN_EPI = false, bool SP2 = false>
; __device__ __forceinline__ void gemm_phase(PG8_LAS unsigned char* lds, const Gemm g, const Sched& S, const Epi& E) {
;     ...
;         for (int t = 0; t < nt; t += 2) {
;             const bool last = (t == nt - 2);
;             const char* a1 = cA + (size_t)(t + 1) * kstep;
;             const char* a2 = last ? nA : cA + (size_t)(t + 2) * kstep; const char* b2 = last ? nB : cB + (size_t)(t + 2) * kstep;
;             const char* a3 = a2 + kstep; const char* b3 = b2 + kstep;
;     ...
;             PG8_LDA(At, 1, 1); PG8_STAGE(PG8_SB(1, 0), b3, voffB); PG8_STAGE(PG8_SB(1, 1), b3 + hstep, voffB); PG8_STAGE(PG8_SA(1, 0), a3, voffA);
;             PG8_WAIT_V(8); PG8_WAIT_L(0); PG8_BAR; PG8_MMA(1, 0, At, B0); PG8_MMA(1, 1, At, B1); PG8_BAR; PG8_SCHED;
	s_setprio 0
	s_add_i32 s40, s57, s3
	v_lshl_add_u64 v[146:147], v[146:147], 0, s[10:11]
	s_mov_b32 m0, s40
	ds_read_b128 v[206:209], v168 offset:49152
	ds_read_b128 v[210:213], v168 offset:50176
	ds_read_b128 v[214:217], v168 offset:51200
	ds_read_b128 v[218:221], v168 offset:52224
	ds_read_b128 v[222:225], v168 offset:53248
	ds_read_b128 v[226:229], v168 offset:54272
	ds_read_b128 v[230:233], v168 offset:55296
	ds_read_b128 v[234:237], v168 offset:56320
	global_load_lds_dwordx4 v[146:147], off
	s_add_i32 m0, s40, 0x2000
	s_add_u32 s40, s50, 0x2b0080
	v_lshl_add_u64 v[146:147], v[194:195], 0, s[10:11]
	s_addc_u32 s41, s51, 0
	s_add_i32 s50, s58, s3
	global_load_lds_dwordx4 v[146:147], off
	v_lshl_add_u64 v[146:147], s[40:41], 0, v[132:133]
	s_mov_b32 m0, s50
	s_nop 0
	global_load_lds_dwordx4 v[146:147], off
	v_lshl_add_u64 v[146:147], s[40:41], 0, v[136:137]
	s_add_i32 m0, s50, 0x2000
	s_nop 0
	global_load_lds_dwordx4 v[146:147], off
	v_lshl_add_u64 v[146:147], v[238:239], 0, s[10:11]
	s_mov_b32 m0, s28
	s_nop 0
	global_load_lds_dwordx4 v[146:147], off
	v_lshl_add_u64 v[146:147], v[240:241], 0, s[10:11]
	s_mov_b32 m0, s29
	s_nop 0
	global_load_lds_dwordx4 v[146:147], off
	s_waitcnt vmcnt(8)
	s_waitcnt lgkmcnt(0)
	s_setprio 1
	s_barrier
	v_mfma_f32_16x16x32_bf16 v[62:65], v[170:173], v[206:209], v[62:65]
	v_mfma_f32_16x16x32_bf16 v[62:65], v[174:177], v[210:213], v[62:65]
	v_mfma_f32_16x16x32_bf16 v[58:61], v[178:181], v[206:209], v[58:61]
	v_mfma_f32_16x16x32_bf16 v[58:61], v[182:185], v[210:213], v[58:61]
	v_mfma_f32_16x16x32_bf16 v[46:49], v[170:173], v[214:217], v[46:49]
	v_mfma_f32_16x16x32_bf16 v[46:49], v[174:177], v[218:221], v[46:49]
	v_mfma_f32_16x16x32_bf16 v[42:45], v[178:181], v[214:217], v[42:45]
	v_mfma_f32_16x16x32_bf16 v[42:45], v[182:185], v[218:221], v[42:45]
	v_mfma_f32_16x16x32_bf16 v[30:33], v[170:173], v[222:225], v[30:33]
	v_mfma_f32_16x16x32_bf16 v[30:33], v[174:177], v[226:229], v[30:33]
	v_mfma_f32_16x16x32_bf16 v[26:29], v[178:181], v[222:225], v[26:29]
	v_mfma_f32_16x16x32_bf16 v[26:29], v[182:185], v[226:229], v[26:29]
	v_mfma_f32_16x16x32_bf16 v[14:17], v[170:173], v[230:233], v[14:17]
	v_mfma_f32_16x16x32_bf16 v[14:17], v[174:177], v[234:237], v[14:17]
	v_mfma_f32_16x16x32_bf16 v[10:13], v[178:181], v[230:233], v[10:13]
	v_mfma_f32_16x16x32_bf16 v[10:13], v[182:185], v[234:237], v[10:13]
	s_setprio 0
	s_setprio 1
	v_mfma_f32_16x16x32_bf16 v[54:57], v[186:189], v[206:209], v[54:57]
	v_mfma_f32_16x16x32_bf16 v[54:57], v[190:193], v[210:213], v[54:57]
	v_mfma_f32_16x16x32_bf16 v[50:53], v[196:199], v[206:209], v[50:53]
	v_mfma_f32_16x16x32_bf16 v[50:53], v[202:205], v[210:213], v[50:53]
	v_mfma_f32_16x16x32_bf16 v[38:41], v[186:189], v[214:217], v[38:41]
	v_mfma_f32_16x16x32_bf16 v[38:41], v[190:193], v[218:221], v[38:41]
	v_mfma_f32_16x16x32_bf16 v[34:37], v[196:199], v[214:217], v[34:37]
	v_mfma_f32_16x16x32_bf16 v[34:37], v[202:205], v[218:221], v[34:37]
	v_mfma_f32_16x16x32_bf16 v[22:25], v[186:189], v[222:225], v[22:25]
	v_mfma_f32_16x16x32_bf16 v[22:25], v[190:193], v[226:229], v[22:25]
	v_mfma_f32_16x16x32_bf16 v[18:21], v[196:199], v[222:225], v[18:21]
	v_mfma_f32_16x16x32_bf16 v[18:21], v[202:205], v[226:229], v[18:21]
	v_mfma_f32_16x16x32_bf16 v[6:9], v[186:189], v[230:233], v[6:9]
	v_mfma_f32_16x16x32_bf16 v[6:9], v[190:193], v[234:237], v[6:9]
	v_mfma_f32_16x16x32_bf16 v[2:5], v[196:199], v[230:233], v[2:5]
	v_mfma_f32_16x16x32_bf16 v[2:5], v[202:205], v[234:237], v[2:5]
	s_barrier
	s_setprio 0
	s_add_i32 s56, s56, 2
	s_add_u32 s54, s54, 0x100
	s_addc_u32 s55, s55, 0
	s_cmpk_gt_u32 s56, 0xa9
	s_mov_b64 s[40:41], s[48:49]
	s_cbranch_scc0 .LBB0_1731
	s_and_b64 vcc, exec, s[12:13]
	s_cbranch_vccz .LBB0_1734
	s_barrier

; #define PG8_STAGE(bufoff, gbase, voff) do { _Pragma("unroll") for (int _i = 0; _i < 2; ++_i) \
;         __builtin_amdgcn_global_load_lds((const unsigned*)((const char*)(gbase) + (voff)[_i]), (PG8_LAS unsigned*)(lds + (bufoff) + ldsw + _i * 8192), 16, 0, 0); } while (0)
; #define PG8_LDA(dst, b, h) do { _Pragma("unroll") for (int m = 0; m < 4; ++m) _Pragma("unroll") for (int k = 0; k < 2; ++k) dst[m][k] = *(const PG8_LAS bf16x8*)(lds + PG8_SA(b, h) + aoff + m * 2048 + k * 1024); } while (0)
; #define PG8_LDB(dst, b, h) do { _Pragma("unroll") for (int n = 0; n < 2; ++n) _Pragma("unroll") for (int k = 0; k < 2; ++k) dst[n][k] = *(const PG8_LAS bf16x8*)(lds + PG8_SB(b, h) + boff + n * 2048 + k * 1024); } while (0)
; #define PG8_MMA(ai, bj, At, Bt) do { __builtin_amdgcn_s_setprio(1); _Pragma("unroll") for (int m = 0; m < 4; ++m) _Pragma("unroll") for (int n = 0; n < 2; ++n) _Pragma("unroll") for (int k = 0; k < 2; ++k) \
;         acc[ai][bj][m][n] = __builtin_amdgcn_mfma_f32_16x16x32_bf16(Bt[n][k], At[m][k], acc[ai][bj][m][n], 0, 0, 0); __builtin_amdgcn_s_setprio(0); } while (0)
; #define PG8_WAIT_V(n) asm volatile("s_waitcnt vmcnt(" #n ")" ::: "memory")
; #define PG8_WAIT_L(n) asm volatile("s_waitcnt lgkmcnt(" #n ")" ::: "memory")
; #define PG8_BAR __builtin_amdgcn_s_barrier()
; #define PG8_SCHED __builtin_amdgcn_sched_barrier(0)
; template <class Epi, class Sched, bool ALIGN_EPI = false, bool SP2 = false>
; __device__ __forceinline__ void gemm_phase(PG8_LAS unsigned char* lds, const Gemm g, const Sched& S, const Epi& E) {
;     ...
;             const bool last = (t == nt - 2);
;             const char* a1 = cA + (size_t)(t + 1) * kstep;
;             const char* a2 = last ? nA : cA + (size_t)(t + 2) * kstep; const char* b2 = last ? nB : cB + (size_t)(t + 2) * kstep;
;             const char* a3 = a2 + kstep; const char* b3 = b2 + kstep;
;             if (last && has_next) S.a_ready(nxt);
;             if constexpr (SP2) {
;             PG8_LDB(B0, 0, 0); PG8_LDB(B1, 0, 1); PG8_SCHED; PG8_LDA(At, 0, 0); PG8_STAGE(PG8_SA(1, 1), a1 + hstep, voffA);
;             PG8_WAIT_V(8); PG8_WAIT_L(0); PG8_BAR; PG8_MMA(0, 0, At, B0); PG8_MMA(0, 1, At, B1); PG8_BAR; PG8_SCHED;
;             PG8_LDA(At, 0, 1); PG8_STAGE(PG8_SB(0, 0), b2, voffB); PG8_STAGE(PG8_SB(0, 1), b2 + hstep, voffB); PG8_STAGE(PG8_SA(0, 0), a2, voffA);
.LBB0_1746:
	ds_read_b128 v[140:143], v134
	ds_read_b128 v[144:147], v134 offset:1024
	ds_read_b128 v[148:151], v134 offset:2048
	ds_read_b128 v[152:155], v134 offset:3072
	ds_read_b128 v[156:159], v135
	ds_read_b128 v[160:163], v135 offset:1024
	ds_read_b128 v[164:167], v135 offset:2048
	ds_read_b128 v[168:171], v135 offset:3072
	s_add_i32 s36, s38, 2
	s_mov_b32 s37, s11
	s_or_b32 s10, s38, 1
	s_lshl_b64 s[40:41], s[36:37], 7
	s_cmp_lg_u32 s38, s42
	s_cselect_b32 s38, s40, 0
	s_cselect_b32 s37, s41, 0
	s_add_u32 s40, s6, s38
	s_addc_u32 s41, s7, s37
	s_add_u32 s38, s2, s38
	s_addc_u32 s39, s3, s37
	s_lshl_b64 s[52:53], s[10:11], 7
	s_add_u32 s52, s8, s52
	s_addc_u32 s53, s9, s53
	s_mov_b32 m0, s43
	v_lshl_add_u64 v[192:193], s[52:53], 0, v[128:129]
	ds_read_b128 v[172:175], v136
	ds_read_b128 v[176:179], v136 offset:1024
	ds_read_b128 v[180:183], v136 offset:2048
	ds_read_b128 v[184:187], v136 offset:3072
	ds_read_b128 v[188:191], v136 offset:4096
	ds_read_b128 v[196:199], v136 offset:5120
	ds_read_b128 v[202:205], v136 offset:6144
	ds_read_b128 v[206:209], v136 offset:7168
	global_load_lds_dwordx4 v[192:193], off
	v_lshl_add_u64 v[192:193], s[52:53], 0, v[130:131]
	s_mov_b32 m0, s44
	s_nop 0
	global_load_lds_dwordx4 v[192:193], off
	s_waitcnt vmcnt(8)
	s_waitcnt lgkmcnt(0)
	s_setprio 1
	s_barrier
	v_mfma_f32_16x16x32_bf16 v[124:127], v[140:143], v[172:175], v[124:127]
	v_mfma_f32_16x16x32_bf16 v[124:127], v[144:147], v[176:179], v[124:127]
	v_mfma_f32_16x16x32_bf16 v[120:123], v[148:151], v[172:175], v[120:123]
	v_mfma_f32_16x16x32_bf16 v[120:123], v[152:155], v[176:179], v[120:123]
	v_mfma_f32_16x16x32_bf16 v[116:119], v[140:143], v[180:183], v[116:119]
	v_mfma_f32_16x16x32_bf16 v[116:119], v[144:147], v[184:187], v[116:119]
	v_mfma_f32_16x16x32_bf16 v[112:115], v[148:151], v[180:183], v[112:115]
	v_mfma_f32_16x16x32_bf16 v[112:115], v[152:155], v[184:187], v[112:115]
	v_mfma_f32_16x16x32_bf16 v[104:107], v[140:143], v[188:191], v[104:107]
	v_mfma_f32_16x16x32_bf16 v[104:107], v[144:147], v[196:199], v[104:107]
	v_mfma_f32_16x16x32_bf16 v[96:99], v[148:151], v[188:191], v[96:99]
	v_mfma_f32_16x16x32_bf16 v[96:99], v[152:155], v[196:199], v[96:99]
	v_mfma_f32_16x16x32_bf16 v[88:91], v[140:143], v[202:205], v[88:91]
	v_mfma_f32_16x16x32_bf16 v[88:91], v[144:147], v[206:209], v[88:91]
	v_mfma_f32_16x16x32_bf16 v[80:83], v[148:151], v[202:205], v[80:83]
	v_mfma_f32_16x16x32_bf16 v[80:83], v[152:155], v[206:209], v[80:83]
	s_setprio 0
	s_setprio 1
	v_mfma_f32_16x16x32_bf16 v[108:111], v[156:159], v[172:175], v[108:111]
	v_mfma_f32_16x16x32_bf16 v[108:111], v[160:163], v[176:179], v[108:111]
	v_mfma_f32_16x16x32_bf16 v[100:103], v[164:167], v[172:175], v[100:103]
	v_mfma_f32_16x16x32_bf16 v[100:103], v[168:171], v[176:179], v[100:103]
	v_mfma_f32_16x16x32_bf16 v[92:95], v[156:159], v[180:183], v[92:95]
	v_mfma_f32_16x16x32_bf16 v[92:95], v[160:163], v[184:187], v[92:95]
	v_mfma_f32_16x16x32_bf16 v[84:87], v[164:167], v[180:183], v[84:87]
	v_mfma_f32_16x16x32_bf16 v[84:87], v[168:171], v[184:187], v[84:87]
	v_mfma_f32_16x16x32_bf16 v[76:79], v[156:159], v[188:191], v[76:79]
	v_mfma_f32_16x16x32_bf16 v[76:79], v[160:163], v[196:199], v[76:79]
	v_mfma_f32_16x16x32_bf16 v[72:75], v[164:167], v[188:191], v[72:75]
	v_mfma_f32_16x16x32_bf16 v[72:75], v[168:171], v[196:199], v[72:75]
	v_mfma_f32_16x16x32_bf16 v[68:71], v[156:159], v[202:205], v[68:71]
	v_mfma_f32_16x16x32_bf16 v[68:71], v[160:163], v[206:209], v[68:71]
	v_mfma_f32_16x16x32_bf16 v[64:67], v[164:167], v[202:205], v[64:67]
	v_mfma_f32_16x16x32_bf16 v[64:67], v[168:171], v[206:209], v[64:67]
	s_barrier
	s_setprio 0
	s_mov_b32 m0, s31
	v_lshl_add_u64 v[192:193], s[38:39], 0, v[128:129]
	s_add_u32 s52, s38, 0x2b0000
	ds_read_b128 v[172:175], v136 offset:16384
	ds_read_b128 v[176:179], v136 offset:17408
	ds_read_b128 v[180:183], v136 offset:18432
	ds_read_b128 v[184:187], v136 offset:19456
	ds_read_b128 v[188:191], v136 offset:20480
	ds_read_b128 v[196:199], v136 offset:21504
	ds_read_b128 v[202:205], v136 offset:22528
	ds_read_b128 v[206:209], v136 offset:23552
	global_load_lds_dwordx4 v[192:193], off
	v_lshl_add_u64 v[194:195], s[38:39], 0, v[130:131]
	s_mov_b32 m0, s45
	s_addc_u32 s53, s39, 0
	global_load_lds_dwordx4 v[194:195], off
	v_lshl_add_u64 v[210:211], s[52:53], 0, v[128:129]
	s_mov_b32 m0, s46
	v_lshl_add_u64 v[212:213], s[40:41], 0, v[130:131]
	global_load_lds_dwordx4 v[210:211], off
	v_lshl_add_u64 v[210:211], s[52:53], 0, v[130:131]
	s_mov_b32 m0, s47
	s_nop 0
	global_load_lds_dwordx4 v[210:211], off
	v_lshl_add_u64 v[210:211], s[40:41], 0, v[128:129]
	s_mov_b32 m0, s26
	s_nop 0
	global_load_lds_dwordx4 v[210:211], off
	s_mov_b32 m0, s27
	s_nop 0
	global_load_lds_dwordx4 v[212:213], off
	s_waitcnt vmcnt(8)
	s_waitcnt lgkmcnt(0)
	s_setprio 1
	s_barrier
; #define PG8_STAGE(bufoff, gbase, voff) do { _Pragma("unroll") for (int _i = 0; _i < 2; ++_i) \
;         __builtin_amdgcn_global_load_lds((const unsigned*)((const char*)(gbase) + (voff)[_i]), (PG8_LAS unsigned*)(lds + (bufoff) + ldsw + _i * 8192), 16, 0, 0); } while (0)
; #define PG8_LDA(dst, b, h) do { _Pragma("unroll") for (int m = 0; m < 4; ++m) _Pragma("unroll") for (int k = 0; k < 2; ++k) dst[m][k] = *(const PG8_LAS bf16x8*)(lds + PG8_SA(b, h) + aoff + m * 2048 + k * 1024); } while (0)
; #define PG8_LDB(dst, b, h) do { _Pragma("unroll") for (int n = 0; n < 2; ++n) _Pragma("unroll") for (int k = 0; k < 2; ++k) dst[n][k] = *(const PG8_LAS bf16x8*)(lds + PG8_SB(b, h) + boff + n * 2048 + k * 1024); } while (0)
; #define PG8_MMA(ai, bj, At, Bt) do { __builtin_amdgcn_s_setprio(1); _Pragma("unroll") for (int m = 0; m < 4; ++m) _Pragma("unroll") for (int n = 0; n < 2; ++n) _Pragma("unroll") for (int k = 0; k < 2; ++k) \
;         acc[ai][bj][m][n] = __builtin_amdgcn_mfma_f32_16x16x32_bf16(Bt[n][k], At[m][k], acc[ai][bj][m][n], 0, 0, 0); __builtin_amdgcn_s_setprio(0); } while (0)
; #define PG8_WAIT_V(n) asm volatile("s_waitcnt vmcnt(" #n ")" ::: "memory")
; #define PG8_WAIT_L(n) asm volatile("s_waitcnt lgkmcnt(" #n ")" ::: "memory")
; #define PG8_BAR __builtin_amdgcn_s_barrier()
; #define PG8_SCHED __builtin_amdgcn_sched_barrier(0)
; template <class Epi, class Sched, bool ALIGN_EPI = false, bool SP2 = false>
; __device__ __forceinline__ void gemm_phase(PG8_LAS unsigned char* lds, const Gemm g, const Sched& S, const Epi& E) {
;     ...
;             PG8_WAIT_V(8); PG8_WAIT_L(0); PG8_BAR; PG8_MMA(1, 0, At, B0); PG8_MMA(1, 1, At, B1); PG8_BAR; PG8_SCHED;
;             PG8_LDB(B0, 1, 0); PG8_LDB(B1, 1, 1); PG8_SCHED; PG8_LDA(At, 1, 0); PG8_STAGE(PG8_SA(0, 1), a2 + hstep, voffA);
;             PG8_WAIT_V(8); PG8_WAIT_L(0); PG8_BAR; PG8_MMA(0, 0, At, B0); PG8_MMA(0, 1, At, B1); PG8_BAR; PG8_SCHED;
	v_mfma_f32_16x16x32_bf16 v[60:63], v[140:143], v[172:175], v[60:63]
	v_mfma_f32_16x16x32_bf16 v[60:63], v[144:147], v[176:179], v[60:63]
	v_mfma_f32_16x16x32_bf16 v[56:59], v[148:151], v[172:175], v[56:59]
	v_mfma_f32_16x16x32_bf16 v[56:59], v[152:155], v[176:179], v[56:59]
	v_mfma_f32_16x16x32_bf16 v[52:55], v[140:143], v[180:183], v[52:55]
	v_mfma_f32_16x16x32_bf16 v[52:55], v[144:147], v[184:187], v[52:55]
	v_mfma_f32_16x16x32_bf16 v[48:51], v[148:151], v[180:183], v[48:51]
	v_mfma_f32_16x16x32_bf16 v[48:51], v[152:155], v[184:187], v[48:51]
	v_mfma_f32_16x16x32_bf16 v[40:43], v[140:143], v[188:191], v[40:43]
	v_mfma_f32_16x16x32_bf16 v[40:43], v[144:147], v[196:199], v[40:43]
	v_mfma_f32_16x16x32_bf16 v[32:35], v[148:151], v[188:191], v[32:35]
	v_mfma_f32_16x16x32_bf16 v[32:35], v[152:155], v[196:199], v[32:35]
	v_mfma_f32_16x16x32_bf16 v[24:27], v[140:143], v[202:205], v[24:27]
	v_mfma_f32_16x16x32_bf16 v[24:27], v[144:147], v[206:209], v[24:27]
	v_mfma_f32_16x16x32_bf16 v[16:19], v[148:151], v[202:205], v[16:19]
	v_mfma_f32_16x16x32_bf16 v[16:19], v[152:155], v[206:209], v[16:19]
	s_setprio 0
	s_setprio 1
	v_mfma_f32_16x16x32_bf16 v[44:47], v[156:159], v[172:175], v[44:47]
	v_mfma_f32_16x16x32_bf16 v[44:47], v[160:163], v[176:179], v[44:47]
	v_mfma_f32_16x16x32_bf16 v[36:39], v[164:167], v[172:175], v[36:39]
	v_mfma_f32_16x16x32_bf16 v[36:39], v[168:171], v[176:179], v[36:39]
	v_mfma_f32_16x16x32_bf16 v[28:31], v[156:159], v[180:183], v[28:31]
	v_mfma_f32_16x16x32_bf16 v[28:31], v[160:163], v[184:187], v[28:31]
	v_mfma_f32_16x16x32_bf16 v[20:23], v[164:167], v[180:183], v[20:23]
	v_mfma_f32_16x16x32_bf16 v[20:23], v[168:171], v[184:187], v[20:23]
	v_mfma_f32_16x16x32_bf16 v[12:15], v[156:159], v[188:191], v[12:15]
	v_mfma_f32_16x16x32_bf16 v[12:15], v[160:163], v[196:199], v[12:15]
	v_mfma_f32_16x16x32_bf16 v[8:11], v[164:167], v[188:191], v[8:11]
	v_mfma_f32_16x16x32_bf16 v[8:11], v[168:171], v[196:199], v[8:11]
	v_mfma_f32_16x16x32_bf16 v[4:7], v[156:159], v[202:205], v[4:7]
	v_mfma_f32_16x16x32_bf16 v[4:7], v[160:163], v[206:209], v[4:7]
	v_mfma_f32_16x16x32_bf16 v[0:3], v[164:167], v[202:205], v[0:3]
	v_mfma_f32_16x16x32_bf16 v[0:3], v[168:171], v[206:209], v[0:3]
	s_barrier
	s_setprio 0
	ds_read_b128 v[140:143], v137
	ds_read_b128 v[144:147], v137 offset:1024
	ds_read_b128 v[148:151], v137 offset:2048
	ds_read_b128 v[152:155], v137 offset:3072
	ds_read_b128 v[156:159], v138
	ds_read_b128 v[160:163], v138 offset:1024
	ds_read_b128 v[164:167], v138 offset:2048
	ds_read_b128 v[168:171], v138 offset:3072
	s_add_u32 s40, s40, 0x2b0000
	s_addc_u32 s41, s41, 0
	s_mov_b32 m0, s28
	v_lshl_add_u64 v[214:215], s[40:41], 0, v[128:129]
	ds_read_b128 v[172:175], v136 offset:32768
	ds_read_b128 v[176:179], v136 offset:33792
	ds_read_b128 v[180:183], v136 offset:34816
	ds_read_b128 v[184:187], v136 offset:35840
	ds_read_b128 v[188:191], v136 offset:36864
	ds_read_b128 v[196:199], v136 offset:37888
	ds_read_b128 v[202:205], v136 offset:38912
	ds_read_b128 v[206:209], v136 offset:39936
	global_load_lds_dwordx4 v[214:215], off
	v_lshl_add_u64 v[214:215], s[40:41], 0, v[130:131]
	s_mov_b32 m0, s30
	s_nop 0
	global_load_lds_dwordx4 v[214:215], off
	s_waitcnt vmcnt(8)
	s_waitcnt lgkmcnt(0)
	s_setprio 1
	s_barrier
	v_mfma_f32_16x16x32_bf16 v[124:127], v[140:143], v[172:175], v[124:127]
	v_mfma_f32_16x16x32_bf16 v[124:127], v[144:147], v[176:179], v[124:127]
	v_mfma_f32_16x16x32_bf16 v[120:123], v[148:151], v[172:175], v[120:123]
	v_mfma_f32_16x16x32_bf16 v[120:123], v[152:155], v[176:179], v[120:123]
	v_mfma_f32_16x16x32_bf16 v[116:119], v[140:143], v[180:183], v[116:119]
	v_mfma_f32_16x16x32_bf16 v[116:119], v[144:147], v[184:187], v[116:119]
	v_mfma_f32_16x16x32_bf16 v[112:115], v[148:151], v[180:183], v[112:115]
	v_mfma_f32_16x16x32_bf16 v[112:115], v[152:155], v[184:187], v[112:115]
	v_mfma_f32_16x16x32_bf16 v[104:107], v[140:143], v[188:191], v[104:107]
	v_mfma_f32_16x16x32_bf16 v[104:107], v[144:147], v[196:199], v[104:107]
	v_mfma_f32_16x16x32_bf16 v[96:99], v[148:151], v[188:191], v[96:99]
	v_mfma_f32_16x16x32_bf16 v[96:99], v[152:155], v[196:199], v[96:99]
	v_mfma_f32_16x16x32_bf16 v[88:91], v[140:143], v[202:205], v[88:91]
	v_mfma_f32_16x16x32_bf16 v[88:91], v[144:147], v[206:209], v[88:91]
	v_mfma_f32_16x16x32_bf16 v[80:83], v[148:151], v[202:205], v[80:83]
	v_mfma_f32_16x16x32_bf16 v[80:83], v[152:155], v[206:209], v[80:83]
	s_setprio 0
	s_setprio 1
	v_mfma_f32_16x16x32_bf16 v[108:111], v[156:159], v[172:175], v[108:111]
	v_mfma_f32_16x16x32_bf16 v[108:111], v[160:163], v[176:179], v[108:111]
	v_mfma_f32_16x16x32_bf16 v[100:103], v[164:167], v[172:175], v[100:103]
	v_mfma_f32_16x16x32_bf16 v[100:103], v[168:171], v[176:179], v[100:103]
	v_mfma_f32_16x16x32_bf16 v[92:95], v[156:159], v[180:183], v[92:95]
	v_mfma_f32_16x16x32_bf16 v[92:95], v[160:163], v[184:187], v[92:95]
	v_mfma_f32_16x16x32_bf16 v[84:87], v[164:167], v[180:183], v[84:87]
	v_mfma_f32_16x16x32_bf16 v[84:87], v[168:171], v[184:187], v[84:87]
	v_mfma_f32_16x16x32_bf16 v[76:79], v[156:159], v[188:191], v[76:79]
	v_mfma_f32_16x16x32_bf16 v[76:79], v[160:163], v[196:199], v[76:79]
	v_mfma_f32_16x16x32_bf16 v[72:75], v[164:167], v[188:191], v[72:75]
	v_mfma_f32_16x16x32_bf16 v[72:75], v[168:171], v[196:199], v[72:75]
	v_mfma_f32_16x16x32_bf16 v[68:71], v[156:159], v[202:205], v[68:71]
	v_mfma_f32_16x16x32_bf16 v[68:71], v[160:163], v[206:209], v[68:71]
	v_mfma_f32_16x16x32_bf16 v[64:67], v[164:167], v[202:205], v[64:67]
	v_mfma_f32_16x16x32_bf16 v[64:67], v[168:171], v[206:209], v[64:67]
	s_barrier
; #define PG8_STAGE(bufoff, gbase, voff) do { _Pragma("unroll") for (int _i = 0; _i < 2; ++_i) \
;         __builtin_amdgcn_global_load_lds((const unsigned*)((const char*)(gbase) + (voff)[_i]), (PG8_LAS unsigned*)(lds + (bufoff) + ldsw + _i * 8192), 16, 0, 0); } while (0)
; #define PG8_LDA(dst, b, h) do { _Pragma("unroll") for (int m = 0; m < 4; ++m) _Pragma("unroll") for (int k = 0; k < 2; ++k) dst[m][k] = *(const PG8_LAS bf16x8*)(lds + PG8_SA(b, h) + aoff + m * 2048 + k * 1024); } while (0)
; #define PG8_MMA(ai, bj, At, Bt) do { __builtin_amdgcn_s_setprio(1); _Pragma("unroll") for (int m = 0; m < 4; ++m) _Pragma("unroll") for (int n = 0; n < 2; ++n) _Pragma("unroll") for (int k = 0; k < 2; ++k) \
;         acc[ai][bj][m][n] = __builtin_amdgcn_mfma_f32_16x16x32_bf16(Bt[n][k], At[m][k], acc[ai][bj][m][n], 0, 0, 0); __builtin_amdgcn_s_setprio(0); } while (0)
; #define PG8_WAIT_V(n) asm volatile("s_waitcnt vmcnt(" #n ")" ::: "memory")
; #define PG8_WAIT_L(n) asm volatile("s_waitcnt lgkmcnt(" #n ")" ::: "memory")
; #define PG8_BAR __builtin_amdgcn_s_barrier()
; #define PG8_SCHED __builtin_amdgcn_sched_barrier(0)
; template <class Epi, class Sched, bool ALIGN_EPI = false, bool SP2 = false>
; __device__ __forceinline__ void gemm_phase(PG8_LAS unsigned char* lds, const Gemm g, const Sched& S, const Epi& E) {
;     ...
;         for (int t = 0; t < nt; t += 2) {
;             const bool last = (t == nt - 2);
;             const char* a1 = cA + (size_t)(t + 1) * kstep;
;             const char* a2 = last ? nA : cA + (size_t)(t + 2) * kstep; const char* b2 = last ? nB : cB + (size_t)(t + 2) * kstep;
;             const char* a3 = a2 + kstep; const char* b3 = b2 + kstep;
;     ...
;             PG8_LDA(At, 1, 1); PG8_STAGE(PG8_SB(1, 0), b3, voffB); PG8_STAGE(PG8_SB(1, 1), b3 + hstep, voffB); PG8_STAGE(PG8_SA(1, 0), a3, voffA);
;             PG8_WAIT_V(8); PG8_WAIT_L(0); PG8_BAR; PG8_MMA(1, 0, At, B0); PG8_MMA(1, 1, At, B1); PG8_BAR; PG8_SCHED;
	s_setprio 0
	s_mov_b32 m0, s48
	v_lshl_add_u64 v[192:193], v[192:193], 0, s[12:13]
	s_add_u32 s38, s38, 0x2b0080
	ds_read_b128 v[172:175], v136 offset:49152
	ds_read_b128 v[176:179], v136 offset:50176
	ds_read_b128 v[180:183], v136 offset:51200
	ds_read_b128 v[184:187], v136 offset:52224
	ds_read_b128 v[188:191], v136 offset:53248
	ds_read_b128 v[196:199], v136 offset:54272
	ds_read_b128 v[202:205], v136 offset:55296
	ds_read_b128 v[206:209], v136 offset:56320
	global_load_lds_dwordx4 v[192:193], off
	v_lshl_add_u64 v[192:193], v[194:195], 0, s[12:13]
	s_mov_b32 m0, s49
	s_addc_u32 s39, s39, 0
	global_load_lds_dwordx4 v[192:193], off
	v_lshl_add_u64 v[192:193], s[38:39], 0, v[128:129]
	s_mov_b32 m0, s50
	s_nop 0
	global_load_lds_dwordx4 v[192:193], off
	v_lshl_add_u64 v[192:193], s[38:39], 0, v[130:131]
	s_mov_b32 m0, s51
	s_nop 0
	global_load_lds_dwordx4 v[192:193], off
	v_lshl_add_u64 v[192:193], v[210:211], 0, s[12:13]
	s_mov_b32 m0, s34
	s_nop 0
	global_load_lds_dwordx4 v[192:193], off
	v_lshl_add_u64 v[192:193], v[212:213], 0, s[12:13]
	s_mov_b32 m0, s35
	s_nop 0
	global_load_lds_dwordx4 v[192:193], off
	s_waitcnt vmcnt(8)
	s_waitcnt lgkmcnt(0)
	s_setprio 1
	s_barrier
	v_mfma_f32_16x16x32_bf16 v[60:63], v[140:143], v[172:175], v[60:63]
	v_mfma_f32_16x16x32_bf16 v[60:63], v[144:147], v[176:179], v[60:63]
	v_mfma_f32_16x16x32_bf16 v[56:59], v[148:151], v[172:175], v[56:59]
	v_mfma_f32_16x16x32_bf16 v[56:59], v[152:155], v[176:179], v[56:59]
	v_mfma_f32_16x16x32_bf16 v[52:55], v[140:143], v[180:183], v[52:55]
	v_mfma_f32_16x16x32_bf16 v[52:55], v[144:147], v[184:187], v[52:55]
	v_mfma_f32_16x16x32_bf16 v[48:51], v[148:151], v[180:183], v[48:51]
	v_mfma_f32_16x16x32_bf16 v[48:51], v[152:155], v[184:187], v[48:51]
	v_mfma_f32_16x16x32_bf16 v[40:43], v[140:143], v[188:191], v[40:43]
	v_mfma_f32_16x16x32_bf16 v[40:43], v[144:147], v[196:199], v[40:43]
	v_mfma_f32_16x16x32_bf16 v[32:35], v[148:151], v[188:191], v[32:35]
	v_mfma_f32_16x16x32_bf16 v[32:35], v[152:155], v[196:199], v[32:35]
	v_mfma_f32_16x16x32_bf16 v[24:27], v[140:143], v[202:205], v[24:27]
	v_mfma_f32_16x16x32_bf16 v[24:27], v[144:147], v[206:209], v[24:27]
	v_mfma_f32_16x16x32_bf16 v[16:19], v[148:151], v[202:205], v[16:19]
	v_mfma_f32_16x16x32_bf16 v[16:19], v[152:155], v[206:209], v[16:19]
	s_setprio 0
	s_setprio 1
	v_mfma_f32_16x16x32_bf16 v[44:47], v[156:159], v[172:175], v[44:47]
	v_mfma_f32_16x16x32_bf16 v[44:47], v[160:163], v[176:179], v[44:47]
	v_mfma_f32_16x16x32_bf16 v[36:39], v[164:167], v[172:175], v[36:39]
	v_mfma_f32_16x16x32_bf16 v[36:39], v[168:171], v[176:179], v[36:39]
	v_mfma_f32_16x16x32_bf16 v[28:31], v[156:159], v[180:183], v[28:31]
	v_mfma_f32_16x16x32_bf16 v[28:31], v[160:163], v[184:187], v[28:31]
	v_mfma_f32_16x16x32_bf16 v[20:23], v[164:167], v[180:183], v[20:23]
	v_mfma_f32_16x16x32_bf16 v[20:23], v[168:171], v[184:187], v[20:23]
	v_mfma_f32_16x16x32_bf16 v[12:15], v[156:159], v[188:191], v[12:15]
	v_mfma_f32_16x16x32_bf16 v[12:15], v[160:163], v[196:199], v[12:15]
	v_mfma_f32_16x16x32_bf16 v[8:11], v[164:167], v[188:191], v[8:11]
	v_mfma_f32_16x16x32_bf16 v[8:11], v[168:171], v[196:199], v[8:11]
	v_mfma_f32_16x16x32_bf16 v[4:7], v[156:159], v[202:205], v[4:7]
	v_mfma_f32_16x16x32_bf16 v[4:7], v[160:163], v[206:209], v[4:7]
	v_mfma_f32_16x16x32_bf16 v[0:3], v[164:167], v[202:205], v[0:3]
	v_mfma_f32_16x16x32_bf16 v[0:3], v[168:171], v[206:209], v[0:3]
	s_barrier
	s_setprio 0
	s_cmp_ge_u32 s36, s5
	s_mov_b32 s38, s36
	s_cbranch_scc0 .LBB0_1746
	s_cmpk_lt_u32 s16, 0x100
	s_cbranch_scc0 .LBB0_1749
	s_barrier
